# FFT loop: dropped 618 compiler pad s_nop 0 after packed-f32 ops (not a hardware hazard: pk f32 does not move result bit position)
# baseline (speedup 1.0000x reference)
.Lmy_fft_kj:
	v_mov_b32 v66, 0
	v_mov_b32_e32 v68, v1
	v_add_u32_e32 v0, v66, v0
	v_cvt_f32_i32_e32 v70, v0
	v_ashrrev_i32_e32 v66, 5, v0
	v_lshlrev_b32_e32 v69, 3, v0
	v_lshlrev_b32_e32 v66, 3, v66
	v_add3_u32 v127, 0, v66, v69
	v_add_u32_e32 v220, 0x10800, v127
	v_mul_f32_e32 v0, 0x38800000, v70
	v_sin_f32_e32 v107, v0
	v_cos_f32_e32 v106, v0
	v_xor_b32_e32 v124, 0x80000000, v107
	v_mov_b32_e32 v125, v107
	v_pk_mul_f32 v[128:129], v[124:125], v[106:107] op_sel:[0,1] op_sel_hi:[1,0]
	v_pk_fma_f32 v[128:129], v[106:107], v[106:107], v[128:129] op_sel_hi:[1,0,1]
	v_pk_mul_f32 v[132:133], v[124:125], v[128:129] op_sel:[0,1] op_sel_hi:[1,0]
	s_waitcnt vmcnt(21)
	v_sub_f32_e32 v70, v112, v120
	v_pk_fma_f32 v[132:133], v[128:129], v[106:107], v[132:133] op_sel_hi:[1,0,1]
	s_waitcnt vmcnt(20)
	v_sub_f32_e32 v76, v113, v121
	v_pk_mul_f32 v[136:137], v[124:125], v[132:133] op_sel:[0,1] op_sel_hi:[1,0]
	v_pk_fma_f32 v[136:137], v[132:133], v[106:107], v[136:137] op_sel_hi:[1,0,1]
	v_pk_mul_f32 v[140:141], v[124:125], v[136:137] op_sel:[0,1] op_sel_hi:[1,0]
	v_pk_fma_f32 v[140:141], v[136:137], v[106:107], v[140:141] op_sel_hi:[1,0,1]
	v_sub_f32_e32 v66, v109, v119
	v_pk_mul_f32 v[144:145], v[124:125], v[140:141] op_sel:[0,1] op_sel_hi:[1,0]
	v_mul_f32_e32 v73, 0xbf3504f3, v70
	v_pk_fma_f32 v[144:145], v[140:141], v[106:107], v[144:145] op_sel_hi:[1,0,1]
	v_mul_f32_e32 v85, 0xbf6c835e, v76
	v_pk_mul_f32 v[148:149], v[124:125], v[144:145] op_sel:[0,1] op_sel_hi:[1,0]
	v_pk_fma_f32 v[148:149], v[144:145], v[106:107], v[148:149] op_sel_hi:[1,0,1]
	v_pk_mul_f32 v[152:153], v[124:125], v[148:149] op_sel:[0,1] op_sel_hi:[1,0]
	v_pk_fma_f32 v[152:153], v[148:149], v[106:107], v[152:153] op_sel_hi:[1,0,1]
	v_pk_mul_f32 v[156:157], v[124:125], v[152:153] op_sel:[0,1] op_sel_hi:[1,0]
	v_pk_fma_f32 v[156:157], v[152:153], v[106:107], v[156:157] op_sel_hi:[1,0,1]
	v_sub_f32_e32 v0, v108, v118
	v_pk_mul_f32 v[160:161], v[124:125], v[156:157] op_sel:[0,1] op_sel_hi:[1,0]
	v_pk_add_f32 v[108:109], v[108:109], v[118:119]
	v_pk_fma_f32 v[160:161], v[156:157], v[106:107], v[160:161] op_sel_hi:[1,0,1]
	v_mul_f32_e32 v69, 0xbec3ef15, v66
	v_pk_mul_f32 v[164:165], v[124:125], v[160:161] op_sel:[0,1] op_sel_hi:[1,0]
	v_pk_fma_f32 v[70:71], v[70:71], s[10:11], v[72:73] op_sel_hi:[1,0,1]
	v_pk_fma_f32 v[72:73], v[76:77], s[14:15], v[84:85] op_sel_hi:[1,0,1]
	s_waitcnt vmcnt(18)
	v_sub_f32_e32 v82, v115, v123
	v_pk_add_f32 v[76:77], v[114:115], v[122:123]
	v_mov_b32_e32 v83, v1
	v_mov_b32_e32 v90, v1
	s_movk_i32 s5, 0x200
	v_pk_fma_f32 v[164:165], v[160:161], v[106:107], v[164:165] op_sel_hi:[1,0,1]
	v_pk_fma_f32 v[66:67], v[66:67], s[6:7], v[68:69] op_sel_hi:[1,0,1]
	v_pk_add_f32 v[68:69], v[112:113], v[120:121]
	v_mul_f32_e32 v91, 0xbf6c835e, v82
	s_waitcnt vmcnt(17)
	v_sub_f32_e32 v80, v116, v110
	v_pk_add_f32 v[112:113], v[108:109], v[76:77] neg_lo:[0,1] neg_hi:[0,1]
	v_mov_b32_e32 v81, v1
	v_mov_b32_e32 v88, v1
	v_mov_b32_e32 v101, v1
	v_mov_b32_e32 v102, v1
	v_pk_mul_f32 v[168:169], v[124:125], v[164:165] op_sel:[0,1] op_sel_hi:[1,0]
	v_pk_fma_f32 v[82:83], v[82:83], s[4:5], v[90:91] op_sel_hi:[1,0,1]
	v_mul_f32_e32 v89, 0xbf3504f3, v80
	s_waitcnt vmcnt(16)
	v_sub_f32_e32 v78, v117, v111
	v_pk_add_f32 v[90:91], v[116:117], v[110:111]
	v_mov_b32_e32 v100, v113
	v_mul_f32_e32 v103, 0xbf3504f3, v113
	v_mov_b32_e32 v79, v1
	v_mov_b32_e32 v86, v1
	v_pk_fma_f32 v[168:169], v[164:165], v[106:107], v[168:169] op_sel_hi:[1,0,1]
	v_sub_f32_e32 v75, v114, v122
	v_pk_fma_f32 v[80:81], v[80:81], s[8:9], v[88:89] op_sel_hi:[1,0,1]
	v_mul_f32_e32 v87, 0xbec3ef15, v78
	v_pk_add_f32 v[88:89], v[66:67], v[82:83]
	v_pk_add_f32 v[66:67], v[66:67], v[82:83] neg_lo:[0,1] neg_hi:[0,1]
	v_pk_fma_f32 v[82:83], v[100:101], s[10:11], v[102:103] op_sel_hi:[1,0,1]
	v_pk_add_f32 v[100:101], v[68:69], v[90:91] neg_lo:[0,1] neg_hi:[0,1]
	v_mov_b32_e32 v74, v1
	v_mov_b32_e32 v97, v1
	v_mov_b32_e32 v98, v1
	v_pk_mul_f32 v[174:175], v[124:125], v[168:169] op_sel:[0,1] op_sel_hi:[1,0]
	v_xor_b32_e32 v75, 0x80000000, v75
	v_pk_add_f32 v[76:77], v[108:109], v[76:77]
	v_pk_add_f32 v[68:69], v[68:69], v[90:91]
	v_pk_fma_f32 v[78:79], v[78:79], s[12:13], v[86:87] op_sel_hi:[1,0,1]
	v_pk_add_f32 v[90:91], v[70:71], v[80:81]
	v_pk_add_f32 v[70:71], v[70:71], v[80:81] neg_lo:[0,1] neg_hi:[0,1]
	v_mov_b32_e32 v96, v101
	v_mul_f32_e32 v99, 0xbf3504f3, v101
	v_pk_fma_f32 v[174:175], v[168:169], v[106:107], v[174:175] op_sel_hi:[1,0,1]
	v_pk_add_f32 v[84:85], v[0:1], v[74:75]
	v_pk_add_f32 v[80:81], v[76:77], v[68:69] neg_lo:[0,1] neg_hi:[0,1]
	v_pk_add_f32 v[68:69], v[76:77], v[68:69]
	v_xor_b32_e32 v77, 0x80000000, v70
	v_mov_b32_e32 v76, v71
	v_pk_add_f32 v[70:71], v[72:73], v[78:79]
	v_pk_add_f32 v[72:73], v[72:73], v[78:79] neg_lo:[0,1] neg_hi:[0,1]
	v_pk_fma_f32 v[78:79], v[96:97], s[8:9], v[98:99] op_sel_hi:[1,0,1]
	v_mov_b32_e32 v94, v1
	v_pk_mul_f32 v[178:179], v[124:125], v[174:175] op_sel:[0,1] op_sel_hi:[1,0]
	v_pk_add_f32 v[74:75], v[0:1], v[74:75] neg_lo:[0,1] neg_hi:[0,1]
	v_mov_b32_e32 v0, v112
	v_pk_mul_f32 v[86:87], v[66:67], s[16:17]
	v_xor_b32_e32 v95, 0x80000000, v100
	v_mov_b32_e32 v92, v80
	v_pk_add_f32 v[80:81], v[80:81], 0 neg_lo:[1,1] neg_hi:[1,1]
	v_pk_add_f32 v[96:97], v[84:85], v[90:91]
	v_pk_add_f32 v[84:85], v[84:85], v[90:91] neg_lo:[0,1] neg_hi:[0,1]
	v_pk_add_f32 v[90:91], v[68:69], v[68:69] op_sel:[0,1] op_sel_hi:[1,0]
	v_pk_mul_f32 v[98:99], v[72:73], s[16:17]
	v_pk_add_f32 v[100:101], v[82:83], v[78:79]
	v_pk_add_f32 v[78:79], v[82:83], v[78:79] neg_lo:[0,1] neg_hi:[0,1]
	v_pk_add_f32 v[82:83], v[88:89], v[70:71]
	v_pk_add_f32 v[70:71], v[88:89], v[70:71] neg_lo:[0,1] neg_hi:[0,1]
	v_mov_b32_e32 v93, v1
	v_mov_b32_e32 v126, v107
	v_pk_add_f32 v[130:131], v[128:129], 0 neg_lo:[1,1] neg_hi:[1,1]
	v_pk_add_f32 v[158:159], v[156:157], 0 neg_lo:[1,1] neg_hi:[1,1]
	v_pk_fma_f32 v[178:179], v[174:175], v[106:107], v[178:179] op_sel_hi:[1,0,1]
	v_pk_fma_f32 v[66:67], v[66:67], s[10:11], v[86:87] op_sel:[0,0,1] op_sel_hi:[1,0,0]
	v_pk_add_f32 v[86:87], v[0:1], v[94:95]
	v_pk_add_f32 v[94:95], v[0:1], v[94:95] neg_lo:[0,1] neg_hi:[0,1]
	v_mov_b32_e32 v80, v1
	v_pk_add_f32 v[88:89], v[74:75], v[76:77]
	v_pk_add_f32 v[74:75], v[74:75], v[76:77] neg_lo:[0,1] neg_hi:[0,1]
	v_mov_b32_e32 v91, v1
	v_pk_fma_f32 v[72:73], v[72:73], s[8:9], v[98:99] op_sel:[0,0,1] op_sel_hi:[1,0,0]
	v_xor_b32_e32 v77, 0x80000000, v78
	v_mov_b32_e32 v76, v79
	v_xor_b32_e32 v79, 0x80000000, v70
	v_mov_b32_e32 v78, v71
	v_pk_add_f32 v[98:99], v[96:97], v[82:83]
	v_mov_b32_e32 v130, v129
	v_pk_add_f32 v[134:135], v[132:133], 0 neg_lo:[1,1] neg_hi:[1,1]
	v_pk_add_f32 v[142:143], v[140:141], 0 neg_lo:[1,1] neg_hi:[1,1]
	v_mov_b32_e32 v158, v157
	v_pk_mul_f32 v[124:125], v[124:125], v[178:179] op_sel:[0,1] op_sel_hi:[1,0]
	v_pk_add_f32 v[70:71], v[92:93], v[80:81]
	v_pk_add_f32 v[80:81], v[92:93], v[80:81] neg_lo:[0,1] neg_hi:[0,1]
	v_pk_add_f32 v[92:93], v[86:87], v[100:101]
	v_pk_add_f32 v[82:83], v[96:97], v[82:83] neg_lo:[0,1] neg_hi:[0,1]
	ds_write_b64 v127, v[90:91]
	v_pk_add_f32 v[90:91], v[66:67], v[72:73]
	v_pk_add_f32 v[112:113], v[66:67], v[72:73] op_sel:[1,1] op_sel_hi:[0,0] neg_lo:[0,1] neg_hi:[1,0]
	v_pk_add_f32 v[72:73], v[94:95], v[76:77]
	v_pk_add_f32 v[76:77], v[94:95], v[76:77] neg_lo:[0,1] neg_hi:[0,1]
	v_pk_add_f32 v[94:95], v[84:85], v[78:79]
	v_pk_add_f32 v[78:79], v[84:85], v[78:79] neg_lo:[0,1] neg_hi:[0,1]
	v_pk_mul_f32 v[84:85], v[126:127], v[98:99] op_sel:[0,1] op_sel_hi:[0,0] neg_hi:[1,0]
	v_mov_b32_e32 v134, v133
	v_pk_add_f32 v[138:139], v[136:137], 0 neg_lo:[1,1] neg_hi:[1,1]
	v_mov_b32_e32 v142, v141
	v_pk_add_f32 v[146:147], v[144:145], 0 neg_lo:[1,1] neg_hi:[1,1]
	v_pk_add_f32 v[150:151], v[148:149], 0 neg_lo:[1,1] neg_hi:[1,1]
	v_pk_add_f32 v[166:167], v[164:165], 0 neg_lo:[1,1] neg_hi:[1,1]
	v_pk_fma_f32 v[124:125], v[178:179], v[106:107], v[124:125] op_sel_hi:[1,0,1]
	v_pk_mul_f32 v[96:97], v[92:93], v[130:131] op_sel:[1,0] op_sel_hi:[0,1]
	v_pk_mul_f32 v[102:103], v[82:83], v[158:159] op_sel:[1,0] op_sel_hi:[0,1]
	v_pk_add_f32 v[66:67], v[88:89], v[90:91]
	v_pk_fma_f32 v[84:85], v[98:99], v[106:107], v[84:85] op_sel_hi:[1,0,1]
	v_mov_b32_e32 v138, v137
	v_mov_b32_e32 v146, v145
	v_mov_b32_e32 v150, v149
	v_pk_add_f32 v[154:155], v[152:153], 0 neg_lo:[1,1] neg_hi:[1,1]
	v_pk_add_f32 v[162:163], v[160:161], 0 neg_lo:[1,1] neg_hi:[1,1]
	v_mov_b32_e32 v166, v165
	v_pk_add_f32 v[172:173], v[168:169], 0 neg_lo:[1,1] neg_hi:[1,1]
	v_pk_add_f32 v[176:177], v[174:175], 0 neg_lo:[1,1] neg_hi:[1,1]
	v_pk_add_f32 v[180:181], v[178:179], 0 neg_lo:[1,1] neg_hi:[1,1]
	v_pk_add_f32 v[182:183], v[124:125], 0 neg_lo:[1,1] neg_hi:[1,1]
	v_pk_add_f32 v[68:69], v[68:69], v[68:69] op_sel:[0,1] op_sel_hi:[1,0] neg_lo:[0,1] neg_hi:[0,1]
	v_pk_add_f32 v[88:89], v[88:89], v[90:91] neg_lo:[0,1] neg_hi:[0,1]
	v_pk_fma_f32 v[90:91], v[92:93], v[128:129], v[96:97] op_sel_hi:[1,0,1]
	v_pk_mul_f32 v[92:93], v[94:95], v[142:143] op_sel:[1,0] op_sel_hi:[0,1]
	v_pk_fma_f32 v[82:83], v[82:83], v[156:157], v[102:103] op_sel_hi:[1,0,1]
	v_pk_add_f32 v[102:103], v[74:75], v[112:113]
	ds_write_b64 v127, v[84:85] offset:8448
	ds_write_b64 v127, v[90:91] offset:16896
	v_pk_mul_f32 v[84:85], v[66:67], v[134:135] op_sel:[1,0] op_sel_hi:[0,1]
	v_mov_b32_e32 v154, v153
	v_mov_b32_e32 v162, v161
	v_mov_b32_e32 v172, v169
	v_mov_b32_e32 v176, v175
	v_mov_b32_e32 v180, v179
	v_mov_b32_e32 v182, v125
	v_mov_b32_e32 v0, v68
	v_pk_mov_b32 v[68:69], s[2:3], v[68:69] op_sel:[1,0]
	v_pk_add_f32 v[86:87], v[86:87], v[100:101] neg_lo:[0,1] neg_hi:[0,1]
	v_pk_mul_f32 v[100:101], v[70:71], v[138:139] op_sel:[1,0] op_sel_hi:[0,1]
	v_pk_mul_f32 v[96:97], v[72:73], v[146:147] op_sel:[1,0] op_sel_hi:[0,1]
	v_pk_add_f32 v[74:75], v[74:75], v[112:113] neg_lo:[0,1] neg_hi:[0,1]
	v_pk_fma_f32 v[90:91], v[94:95], v[140:141], v[92:93] op_sel_hi:[1,0,1]
	v_pk_mul_f32 v[92:93], v[88:89], v[166:167] op_sel:[1,0] op_sel_hi:[0,1]
	v_pk_fma_f32 v[66:67], v[66:67], v[132:133], v[84:85] op_sel_hi:[1,0,1]
	v_pk_mul_f32 v[84:85], v[102:103], v[150:151] op_sel:[1,0] op_sel_hi:[0,1]
	s_mov_b64 s[46:47], 0
	s_and_b64 vcc, exec, s[0:1]
	v_pk_mul_f32 v[68:69], v[68:69], v[154:155]
	v_pk_mul_f32 v[108:109], v[86:87], v[162:163] op_sel:[1,0] op_sel_hi:[0,1]
	v_pk_mul_f32 v[110:111], v[80:81], v[172:173] op_sel:[1,0] op_sel_hi:[0,1]
	v_pk_fma_f32 v[70:71], v[70:71], v[136:137], v[100:101] op_sel_hi:[1,0,1]
	v_pk_mul_f32 v[98:99], v[78:79], v[176:177] op_sel:[1,0] op_sel_hi:[0,1]
	v_pk_mul_f32 v[100:101], v[76:77], v[180:181] op_sel:[1,0] op_sel_hi:[0,1]
	v_pk_fma_f32 v[72:73], v[72:73], v[144:145], v[96:97] op_sel_hi:[1,0,1]
	v_pk_fma_f32 v[88:89], v[88:89], v[164:165], v[92:93] op_sel_hi:[1,0,1]
	v_pk_mul_f32 v[92:93], v[74:75], v[182:183] op_sel:[1,0] op_sel_hi:[0,1]
	ds_write_b64 v127, v[66:67] offset:25344
	ds_write_b64 v127, v[70:71] offset:33792
	ds_write_b64 v127, v[90:91] offset:42240
	ds_write_b64 v127, v[72:73] offset:50688
	v_pk_fma_f32 v[66:67], v[102:103], v[148:149], v[84:85] op_sel_hi:[1,0,1]
	v_pk_fma_f32 v[68:69], v[0:1], v[152:153], v[68:69] op_sel_hi:[1,0,1]
	v_pk_fma_f32 v[86:87], v[86:87], v[160:161], v[108:109] op_sel_hi:[1,0,1]
	v_pk_fma_f32 v[80:81], v[80:81], v[168:169], v[110:111] op_sel_hi:[1,0,1]
	v_pk_fma_f32 v[78:79], v[78:79], v[174:175], v[98:99] op_sel_hi:[1,0,1]
	v_pk_fma_f32 v[76:77], v[76:77], v[178:179], v[100:101] op_sel_hi:[1,0,1]
	v_pk_fma_f32 v[70:71], v[74:75], v[124:125], v[92:93] op_sel_hi:[1,0,1]
	ds_write_b64 v127, v[66:67] offset:59136
	ds_write_b64 v220, v[68:69]
	ds_write_b64 v220, v[82:83] offset:8448
	ds_write_b64 v220, v[86:87] offset:16896
	ds_write_b64 v220, v[88:89] offset:25344
	ds_write_b64 v220, v[80:81] offset:33792
	ds_write_b64 v220, v[78:79] offset:42240
	ds_write_b64 v220, v[76:77] offset:50688
	ds_write_b64 v220, v[70:71] offset:59136
	s_cbranch_vccz .LBB0_359
	s_waitcnt lgkmcnt(0)
	s_barrier
	v_mov_b32 v0, 0
	s_mov_b32 s5, s14
	v_add_u32_e32 v74, v0, v170
	v_lshlrev_b32_e32 v0, 5, v74
	v_and_b32_e32 v71, 0xfffffc00, v0
	v_and_b32_e32 v70, 31, v74
	v_lshlrev_b32_e32 v78, 3, v71
	v_lshlrev_b32_e32 v79, 3, v70
	v_or_b32_e32 v67, 32, v71
	v_ashrrev_i32_e32 v67, 2, v67
	v_add_u32_e32 v67, 0, v67
	v_add3_u32 v114, v67, v78, v79
	v_ashrrev_i32_e32 v66, 2, v71
	v_add_u32_e32 v66, 0, v66
	v_add3_u32 v66, v66, v78, v79
	v_mov_b32_e32 v221, v114
	ds_read_b64 v[66:67], v66
	ds_read_b64 v[68:69], v221 offset:256
	ds_read_b64 v[72:73], v221 offset:520
	ds_read_b64 v[76:77], v221 offset:784
	ds_read_b64 v[80:81], v221 offset:1048
	ds_read_b64 v[82:83], v221 offset:1312
	ds_read_b64 v[116:117], v221 offset:1576
	ds_read_b64 v[118:119], v221 offset:1840
	ds_read_b64 v[120:121], v221 offset:2104
	ds_read_b64 v[122:123], v221 offset:2368
	ds_read_b64 v[124:125], v221 offset:2632
	ds_read_b64 v[126:127], v221 offset:2896
	ds_read_b64 v[128:129], v221 offset:3160
	ds_read_b64 v[130:131], v221 offset:3424
	ds_read_b64 v[132:133], v221 offset:3688
	ds_read_b64 v[134:135], v221 offset:3952
	ds_read_b64 v[136:137], v221 offset:4216
	ds_read_b64 v[138:139], v221 offset:4480
	ds_read_b64 v[140:141], v221 offset:4744
	ds_read_b64 v[142:143], v221 offset:5008
	s_waitcnt lgkmcnt(3)
	v_pk_add_f32 v[168:169], v[66:67], v[136:137]
	v_pk_add_f32 v[66:67], v[66:67], v[136:137] neg_lo:[0,1] neg_hi:[0,1]
	s_waitcnt lgkmcnt(2)
	v_pk_add_f32 v[136:137], v[68:69], v[138:139]
	v_pk_add_f32 v[68:69], v[68:69], v[138:139] neg_lo:[0,1] neg_hi:[0,1]
	v_pk_mul_f32 v[138:139], v[68:69], s[18:19]
	v_pk_fma_f32 v[68:69], v[68:69], s[20:21], v[138:139] op_sel:[0,0,1] op_sel_hi:[1,0,0]
	s_waitcnt lgkmcnt(1)
	v_pk_add_f32 v[138:139], v[72:73], v[140:141]
	v_pk_add_f32 v[72:73], v[72:73], v[140:141] neg_lo:[0,1] neg_hi:[0,1]
	v_pk_mul_f32 v[140:141], v[72:73], s[4:5]
	ds_read_b64 v[144:145], v221 offset:5272
	ds_read_b64 v[146:147], v221 offset:5536
	ds_read_b64 v[148:149], v221 offset:5800
	ds_read_b64 v[150:151], v221 offset:6064
	v_pk_fma_f32 v[72:73], v[72:73], s[6:7], v[140:141] op_sel:[0,0,1] op_sel_hi:[1,0,0]
	s_waitcnt lgkmcnt(4)
	v_pk_add_f32 v[140:141], v[76:77], v[142:143]
	v_pk_add_f32 v[76:77], v[76:77], v[142:143] neg_lo:[0,1] neg_hi:[0,1]
	v_pk_mul_f32 v[142:143], v[76:77], s[22:23]
	v_pk_fma_f32 v[76:77], v[76:77], s[24:25], v[142:143] op_sel:[0,0,1] op_sel_hi:[1,0,0]
	s_waitcnt lgkmcnt(3)
	v_pk_add_f32 v[142:143], v[80:81], v[144:145]
	v_pk_add_f32 v[80:81], v[80:81], v[144:145] neg_lo:[0,1] neg_hi:[0,1]
	s_mov_b32 s9, s10
	v_pk_mul_f32 v[144:145], v[80:81], s[8:9]
	v_pk_fma_f32 v[80:81], v[80:81], s[10:11], v[144:145] op_sel:[0,0,1] op_sel_hi:[1,0,0]
	s_waitcnt lgkmcnt(2)
	v_pk_add_f32 v[144:145], v[82:83], v[146:147]
	v_pk_add_f32 v[82:83], v[82:83], v[146:147] neg_lo:[0,1] neg_hi:[0,1]
	s_mov_b32 s27, s24
	v_pk_mul_f32 v[146:147], v[82:83], s[26:27]
	s_mov_b32 s0, s23
	v_pk_fma_f32 v[82:83], v[82:83], s[0:1], v[146:147] op_sel:[0,0,1] op_sel_hi:[1,0,0]
	s_waitcnt lgkmcnt(1)
	v_pk_add_f32 v[146:147], v[116:117], v[148:149]
	v_pk_add_f32 v[116:117], v[116:117], v[148:149] neg_lo:[0,1] neg_hi:[0,1]
	s_mov_b32 s13, s6
	v_pk_mul_f32 v[148:149], v[116:117], s[12:13]
	ds_read_b64 v[152:153], v221 offset:6328
	ds_read_b64 v[154:155], v221 offset:6592
	ds_read_b64 v[156:157], v221 offset:6856
	ds_read_b64 v[158:159], v221 offset:7120
	v_pk_fma_f32 v[116:117], v[116:117], s[14:15], v[148:149] op_sel:[0,0,1] op_sel_hi:[1,0,0]
	s_waitcnt lgkmcnt(4)
	v_pk_add_f32 v[148:149], v[118:119], v[150:151]
	v_pk_add_f32 v[118:119], v[118:119], v[150:151] neg_lo:[0,1] neg_hi:[0,1]
	s_mov_b32 s35, s20
	v_pk_mul_f32 v[150:151], v[118:119], s[34:35]
	s_mov_b32 s44, s19
	v_pk_fma_f32 v[118:119], v[118:119], s[44:45], v[150:151] op_sel:[0,0,1] op_sel_hi:[1,0,0]
	s_waitcnt lgkmcnt(3)
	v_pk_add_f32 v[150:151], v[120:121], v[152:153]
	v_pk_add_f32 v[152:153], v[120:121], v[152:153] op_sel:[1,1] op_sel_hi:[0,0] neg_lo:[0,1] neg_hi:[1,0]
	s_waitcnt lgkmcnt(2)
	v_pk_add_f32 v[120:121], v[122:123], v[154:155]
	v_pk_add_f32 v[122:123], v[122:123], v[154:155] neg_lo:[0,1] neg_hi:[0,1]
	v_pk_mul_f32 v[154:155], v[122:123], s[34:35]
	v_pk_fma_f32 v[122:123], v[122:123], s[18:19], v[154:155] op_sel:[0,0,1] op_sel_hi:[1,0,0]
	s_waitcnt lgkmcnt(1)
	v_pk_add_f32 v[154:155], v[124:125], v[156:157]
	v_pk_add_f32 v[124:125], v[124:125], v[156:157] neg_lo:[0,1] neg_hi:[0,1]
	v_pk_mul_f32 v[156:157], v[124:125], s[12:13]
	ds_read_b64 v[160:161], v221 offset:7384
	ds_read_b64 v[162:163], v221 offset:7648
	ds_read_b64 v[164:165], v221 offset:7912
	ds_read_b64 v[166:167], v221 offset:8176
	v_pk_fma_f32 v[124:125], v[124:125], s[4:5], v[156:157] op_sel:[0,0,1] op_sel_hi:[1,0,0]
	s_waitcnt lgkmcnt(4)
	v_pk_add_f32 v[156:157], v[126:127], v[158:159]
	v_pk_add_f32 v[126:127], v[126:127], v[158:159] neg_lo:[0,1] neg_hi:[0,1]
	v_lshlrev_b32_e32 v70, 4, v70
	v_pk_mul_f32 v[158:159], v[126:127], s[26:27]
	v_cvt_f32_u32_e32 v75, v70
	v_pk_fma_f32 v[126:127], v[126:127], s[22:23], v[158:159] op_sel:[0,0,1] op_sel_hi:[1,0,0]
	s_waitcnt lgkmcnt(3)
	v_pk_add_f32 v[158:159], v[128:129], v[160:161]
	v_pk_add_f32 v[128:129], v[128:129], v[160:161] neg_lo:[0,1] neg_hi:[0,1]
	v_and_b32_e32 v74, 0x1fffffe0, v74
	v_pk_mul_f32 v[160:161], v[128:129], s[8:9]
	v_mul_f32_e32 v115, 0x38800000, v75
	v_pk_fma_f32 v[128:129], v[128:129], s[8:9], v[160:161] op_sel:[0,0,1] op_sel_hi:[1,0,0]
	s_waitcnt lgkmcnt(2)
	v_pk_add_f32 v[160:161], v[130:131], v[162:163]
	v_pk_add_f32 v[130:131], v[130:131], v[162:163] neg_lo:[0,1] neg_hi:[0,1]
	v_lshl_add_u32 v74, v74, 3, 0
	v_pk_mul_f32 v[162:163], v[130:131], s[22:23]
	v_sin_f32_e32 v75, v115
	v_pk_fma_f32 v[130:131], v[130:131], s[26:27], v[162:163] op_sel:[0,0,1] op_sel_hi:[1,0,0]
	s_waitcnt lgkmcnt(1)
	v_pk_add_f32 v[162:163], v[132:133], v[164:165]
	v_pk_add_f32 v[132:133], v[132:133], v[164:165] neg_lo:[0,1] neg_hi:[0,1]
	v_add3_u32 v74, v74, v78, v79
	v_pk_mul_f32 v[164:165], v[132:133], s[4:5]
	v_xor_b32_e32 v78, 0x80000000, v75
	v_pk_fma_f32 v[132:133], v[132:133], s[12:13], v[164:165] op_sel:[0,0,1] op_sel_hi:[1,0,0]
	s_waitcnt lgkmcnt(0)
	v_pk_add_f32 v[164:165], v[134:135], v[166:167]
	v_pk_add_f32 v[134:135], v[134:135], v[166:167] neg_lo:[0,1] neg_hi:[0,1]
	v_mov_b32_e32 v79, v75
	v_pk_mul_f32 v[166:167], v[134:135], s[18:19]
	s_add_u32 s41, s56, s42
	v_pk_fma_f32 v[134:135], v[134:135], s[34:35], v[166:167] op_sel:[0,0,1] op_sel_hi:[1,0,0]
	v_pk_add_f32 v[166:167], v[168:169], v[150:151]
	v_pk_add_f32 v[150:151], v[168:169], v[150:151] neg_lo:[0,1] neg_hi:[0,1]
	v_pk_add_f32 v[168:169], v[136:137], v[120:121]
	v_pk_add_f32 v[120:121], v[136:137], v[120:121] neg_lo:[0,1] neg_hi:[0,1]
	s_addc_u32 s61, s57, s43
	v_pk_mul_f32 v[136:137], v[120:121], s[4:5]
	v_pk_fma_f32 v[120:121], v[120:121], s[6:7], v[136:137] op_sel:[0,0,1] op_sel_hi:[1,0,0]
	v_pk_add_f32 v[136:137], v[138:139], v[154:155]
	v_pk_add_f32 v[138:139], v[138:139], v[154:155] neg_lo:[0,1] neg_hi:[0,1]
	v_pk_mul_f32 v[154:155], v[138:139], s[8:9]
	v_pk_fma_f32 v[138:139], v[138:139], s[10:11], v[154:155] op_sel:[0,0,1] op_sel_hi:[1,0,0]
	v_pk_add_f32 v[154:155], v[140:141], v[156:157]
	v_pk_add_f32 v[140:141], v[140:141], v[156:157] neg_lo:[0,1] neg_hi:[0,1]
	v_pk_mul_f32 v[156:157], v[140:141], s[12:13]
	v_pk_fma_f32 v[140:141], v[140:141], s[14:15], v[156:157] op_sel:[0,0,1] op_sel_hi:[1,0,0]
	v_pk_add_f32 v[156:157], v[142:143], v[158:159]
	v_pk_add_f32 v[158:159], v[142:143], v[158:159] op_sel:[1,1] op_sel_hi:[0,0] neg_lo:[0,1] neg_hi:[1,0]
	v_pk_add_f32 v[142:143], v[144:145], v[160:161]
	v_pk_add_f32 v[144:145], v[144:145], v[160:161] neg_lo:[0,1] neg_hi:[0,1]
	v_pk_mul_f32 v[160:161], v[144:145], s[12:13]
	v_pk_fma_f32 v[144:145], v[144:145], s[4:5], v[160:161] op_sel:[0,0,1] op_sel_hi:[1,0,0]
	v_pk_add_f32 v[160:161], v[146:147], v[162:163]
	v_pk_add_f32 v[146:147], v[146:147], v[162:163] neg_lo:[0,1] neg_hi:[0,1]
	v_pk_mul_f32 v[162:163], v[146:147], s[8:9]
	v_pk_fma_f32 v[146:147], v[146:147], s[8:9], v[162:163] op_sel:[0,0,1] op_sel_hi:[1,0,0]
	v_pk_add_f32 v[162:163], v[148:149], v[164:165]
	v_pk_add_f32 v[148:149], v[148:149], v[164:165] neg_lo:[0,1] neg_hi:[0,1]
	v_pk_mul_f32 v[164:165], v[148:149], s[4:5]
	v_pk_fma_f32 v[148:149], v[148:149], s[12:13], v[164:165] op_sel:[0,0,1] op_sel_hi:[1,0,0]
	v_pk_add_f32 v[164:165], v[66:67], v[152:153]
	v_pk_add_f32 v[66:67], v[66:67], v[152:153] neg_lo:[0,1] neg_hi:[0,1]
	v_pk_add_f32 v[152:153], v[68:69], v[122:123]
	v_pk_add_f32 v[68:69], v[68:69], v[122:123] neg_lo:[0,1] neg_hi:[0,1]
	v_pk_mul_f32 v[122:123], v[68:69], s[4:5]
	v_pk_fma_f32 v[68:69], v[68:69], s[6:7], v[122:123] op_sel:[0,0,1] op_sel_hi:[1,0,0]
	v_pk_add_f32 v[122:123], v[72:73], v[124:125]
	v_pk_add_f32 v[72:73], v[72:73], v[124:125] neg_lo:[0,1] neg_hi:[0,1]
	v_pk_mul_f32 v[124:125], v[72:73], s[8:9]
	v_pk_fma_f32 v[72:73], v[72:73], s[10:11], v[124:125] op_sel:[0,0,1] op_sel_hi:[1,0,0]
	v_pk_add_f32 v[124:125], v[76:77], v[126:127]
	v_pk_add_f32 v[76:77], v[76:77], v[126:127] neg_lo:[0,1] neg_hi:[0,1]
	v_pk_mul_f32 v[126:127], v[76:77], s[12:13]
	v_pk_fma_f32 v[76:77], v[76:77], s[14:15], v[126:127] op_sel:[0,0,1] op_sel_hi:[1,0,0]
	v_pk_add_f32 v[126:127], v[80:81], v[128:129]
	v_pk_add_f32 v[128:129], v[80:81], v[128:129] op_sel:[1,1] op_sel_hi:[0,0] neg_lo:[0,1] neg_hi:[1,0]
	v_pk_add_f32 v[80:81], v[82:83], v[130:131]
	v_pk_add_f32 v[82:83], v[82:83], v[130:131] neg_lo:[0,1] neg_hi:[0,1]
	v_pk_mul_f32 v[130:131], v[82:83], s[12:13]
	v_pk_fma_f32 v[82:83], v[82:83], s[4:5], v[130:131] op_sel:[0,0,1] op_sel_hi:[1,0,0]
	v_pk_add_f32 v[130:131], v[116:117], v[132:133]
	v_pk_add_f32 v[116:117], v[116:117], v[132:133] neg_lo:[0,1] neg_hi:[0,1]
	v_pk_mul_f32 v[132:133], v[116:117], s[8:9]
	v_pk_fma_f32 v[116:117], v[116:117], s[8:9], v[132:133] op_sel:[0,0,1] op_sel_hi:[1,0,0]
	v_pk_add_f32 v[132:133], v[118:119], v[134:135]
	v_pk_add_f32 v[118:119], v[118:119], v[134:135] neg_lo:[0,1] neg_hi:[0,1]
	v_pk_mul_f32 v[134:135], v[118:119], s[4:5]
	v_pk_fma_f32 v[118:119], v[118:119], s[12:13], v[134:135] op_sel:[0,0,1] op_sel_hi:[1,0,0]
	v_pk_add_f32 v[134:135], v[166:167], v[156:157]
	v_pk_add_f32 v[156:157], v[166:167], v[156:157] neg_lo:[0,1] neg_hi:[0,1]
	v_pk_add_f32 v[166:167], v[168:169], v[142:143]
	v_pk_add_f32 v[142:143], v[168:169], v[142:143] neg_lo:[0,1] neg_hi:[0,1]
	v_pk_mul_f32 v[168:169], v[142:143], s[8:9]
	v_pk_fma_f32 v[142:143], v[142:143], s[10:11], v[168:169] op_sel:[0,0,1] op_sel_hi:[1,0,0]
	v_pk_add_f32 v[168:169], v[136:137], v[160:161]
	v_pk_add_f32 v[160:161], v[136:137], v[160:161] op_sel:[1,1] op_sel_hi:[0,0] neg_lo:[0,1] neg_hi:[1,0]
	v_pk_add_f32 v[136:137], v[154:155], v[162:163]
	v_pk_add_f32 v[154:155], v[154:155], v[162:163] neg_lo:[0,1] neg_hi:[0,1]
	v_pk_mul_f32 v[162:163], v[154:155], s[8:9]
	v_pk_fma_f32 v[154:155], v[154:155], s[8:9], v[162:163] op_sel:[0,0,1] op_sel_hi:[1,0,0]
	v_pk_add_f32 v[162:163], v[150:151], v[158:159]
	v_pk_add_f32 v[150:151], v[150:151], v[158:159] neg_lo:[0,1] neg_hi:[0,1]
	v_pk_add_f32 v[158:159], v[120:121], v[144:145]
	v_pk_add_f32 v[120:121], v[120:121], v[144:145] neg_lo:[0,1] neg_hi:[0,1]
	v_pk_mul_f32 v[144:145], v[120:121], s[8:9]
	v_pk_fma_f32 v[120:121], v[120:121], s[10:11], v[144:145] op_sel:[0,0,1] op_sel_hi:[1,0,0]
	v_pk_add_f32 v[144:145], v[138:139], v[146:147]
	v_pk_add_f32 v[146:147], v[138:139], v[146:147] op_sel:[1,1] op_sel_hi:[0,0] neg_lo:[0,1] neg_hi:[1,0]
	v_pk_add_f32 v[138:139], v[140:141], v[148:149]
	v_pk_add_f32 v[140:141], v[140:141], v[148:149] neg_lo:[0,1] neg_hi:[0,1]
	v_pk_mul_f32 v[148:149], v[140:141], s[8:9]
	v_pk_fma_f32 v[140:141], v[140:141], s[8:9], v[148:149] op_sel:[0,0,1] op_sel_hi:[1,0,0]
	v_pk_add_f32 v[148:149], v[164:165], v[126:127]
	v_pk_add_f32 v[126:127], v[164:165], v[126:127] neg_lo:[0,1] neg_hi:[0,1]
	v_pk_add_f32 v[164:165], v[152:153], v[80:81]
	v_pk_add_f32 v[80:81], v[152:153], v[80:81] neg_lo:[0,1] neg_hi:[0,1]
	v_pk_mul_f32 v[152:153], v[80:81], s[8:9]
	v_pk_fma_f32 v[80:81], v[80:81], s[10:11], v[152:153] op_sel:[0,0,1] op_sel_hi:[1,0,0]
	v_pk_add_f32 v[152:153], v[122:123], v[130:131]
	v_pk_add_f32 v[130:131], v[122:123], v[130:131] op_sel:[1,1] op_sel_hi:[0,0] neg_lo:[0,1] neg_hi:[1,0]
	v_pk_add_f32 v[122:123], v[124:125], v[132:133]
	v_pk_add_f32 v[124:125], v[124:125], v[132:133] neg_lo:[0,1] neg_hi:[0,1]
	v_pk_mul_f32 v[132:133], v[124:125], s[8:9]
	v_pk_fma_f32 v[124:125], v[124:125], s[8:9], v[132:133] op_sel:[0,0,1] op_sel_hi:[1,0,0]
	v_pk_add_f32 v[132:133], v[66:67], v[128:129]
	v_pk_add_f32 v[66:67], v[66:67], v[128:129] neg_lo:[0,1] neg_hi:[0,1]
	v_pk_add_f32 v[128:129], v[68:69], v[82:83]
	v_pk_add_f32 v[68:69], v[68:69], v[82:83] neg_lo:[0,1] neg_hi:[0,1]
	v_pk_mul_f32 v[82:83], v[68:69], s[8:9]
	v_pk_fma_f32 v[68:69], v[68:69], s[10:11], v[82:83] op_sel:[0,0,1] op_sel_hi:[1,0,0]
	v_pk_add_f32 v[82:83], v[72:73], v[116:117]
	v_pk_add_f32 v[116:117], v[72:73], v[116:117] op_sel:[1,1] op_sel_hi:[0,0] neg_lo:[0,1] neg_hi:[1,0]
	v_pk_add_f32 v[72:73], v[76:77], v[118:119]
	v_pk_add_f32 v[76:77], v[76:77], v[118:119] neg_lo:[0,1] neg_hi:[0,1]
	v_pk_add_f32 v[174:175], v[66:67], v[116:117]
	v_pk_mul_f32 v[118:119], v[76:77], s[8:9]
	v_pk_add_f32 v[116:117], v[66:67], v[116:117] neg_lo:[0,1] neg_hi:[0,1]
	v_pk_fma_f32 v[76:77], v[76:77], s[8:9], v[118:119] op_sel:[0,0,1] op_sel_hi:[1,0,0]
	v_pk_add_f32 v[118:119], v[134:135], v[168:169]
	v_pk_add_f32 v[134:135], v[134:135], v[168:169] neg_lo:[0,1] neg_hi:[0,1]
	v_pk_add_f32 v[168:169], v[166:167], v[136:137]
	v_pk_add_f32 v[166:167], v[166:167], v[136:137] op_sel:[1,1] op_sel_hi:[0,0] neg_lo:[0,1] neg_hi:[1,0]
	v_pk_add_f32 v[180:181], v[118:119], v[168:169]
	v_pk_add_f32 v[136:137], v[156:157], v[160:161]
	v_pk_add_f32 v[156:157], v[156:157], v[160:161] neg_lo:[0,1] neg_hi:[0,1]
	v_pk_add_f32 v[160:161], v[142:143], v[154:155]
	v_pk_add_f32 v[154:155], v[142:143], v[154:155] op_sel:[1,1] op_sel_hi:[0,0] neg_lo:[0,1] neg_hi:[1,0]
	v_pk_add_f32 v[178:179], v[68:69], v[76:77] op_sel:[1,1] op_sel_hi:[0,0] neg_lo:[0,1] neg_hi:[1,0]
	v_pk_add_f32 v[142:143], v[162:163], v[144:145]
	v_pk_add_f32 v[144:145], v[162:163], v[144:145] neg_lo:[0,1] neg_hi:[0,1]
	v_pk_add_f32 v[162:163], v[158:159], v[138:139]
	v_pk_add_f32 v[158:159], v[158:159], v[138:139] op_sel:[1,1] op_sel_hi:[0,0] neg_lo:[0,1] neg_hi:[1,0]
	ds_write_b64 v74, v[180:181]
	v_pk_add_f32 v[138:139], v[150:151], v[146:147]
	v_pk_add_f32 v[146:147], v[150:151], v[146:147] neg_lo:[0,1] neg_hi:[0,1]
	v_pk_add_f32 v[150:151], v[120:121], v[140:141]
	v_pk_add_f32 v[140:141], v[120:121], v[140:141] op_sel:[1,1] op_sel_hi:[0,0] neg_lo:[0,1] neg_hi:[1,0]
	v_cos_f32_e32 v74, v115
	v_pk_add_f32 v[120:121], v[148:149], v[152:153]
	v_pk_add_f32 v[148:149], v[148:149], v[152:153] neg_lo:[0,1] neg_hi:[0,1]
	v_pk_add_f32 v[152:153], v[164:165], v[122:123]
	v_pk_add_f32 v[164:165], v[164:165], v[122:123] op_sel:[1,1] op_sel_hi:[0,0] neg_lo:[0,1] neg_hi:[1,0]
	v_pk_add_f32 v[122:123], v[126:127], v[130:131]
	v_pk_add_f32 v[126:127], v[126:127], v[130:131] neg_lo:[0,1] neg_hi:[0,1]
	v_pk_add_f32 v[130:131], v[80:81], v[124:125]
	v_pk_add_f32 v[124:125], v[80:81], v[124:125] op_sel:[1,1] op_sel_hi:[0,0] neg_lo:[0,1] neg_hi:[1,0]
	v_pk_add_f32 v[80:81], v[132:133], v[82:83]
	v_pk_add_f32 v[132:133], v[132:133], v[82:83] neg_lo:[0,1] neg_hi:[0,1]
	v_pk_add_f32 v[176:177], v[68:69], v[76:77]
	v_pk_add_f32 v[118:119], v[118:119], v[168:169] neg_lo:[0,1] neg_hi:[0,1]
	v_pk_add_f32 v[168:169], v[134:135], v[166:167]
	v_pk_add_f32 v[82:83], v[134:135], v[166:167] neg_lo:[0,1] neg_hi:[0,1]
	v_pk_add_f32 v[134:135], v[136:137], v[160:161]
	v_pk_add_f32 v[136:137], v[136:137], v[160:161] neg_lo:[0,1] neg_hi:[0,1]
	v_pk_add_f32 v[160:161], v[156:157], v[154:155]
	v_pk_add_f32 v[68:69], v[156:157], v[154:155] neg_lo:[0,1] neg_hi:[0,1]
	v_pk_add_f32 v[154:155], v[142:143], v[162:163]
	v_pk_add_f32 v[142:143], v[142:143], v[162:163] neg_lo:[0,1] neg_hi:[0,1]
	v_pk_add_f32 v[156:157], v[144:145], v[158:159]
	v_pk_add_f32 v[76:77], v[144:145], v[158:159] neg_lo:[0,1] neg_hi:[0,1]
	v_pk_add_f32 v[144:145], v[138:139], v[150:151]
	v_pk_add_f32 v[138:139], v[138:139], v[150:151] neg_lo:[0,1] neg_hi:[0,1]
	v_pk_add_f32 v[150:151], v[146:147], v[140:141]
	v_pk_add_f32 v[66:67], v[146:147], v[140:141] neg_lo:[0,1] neg_hi:[0,1]
	v_pk_add_f32 v[140:141], v[120:121], v[152:153]
	v_pk_add_f32 v[162:163], v[116:117], v[178:179]
	v_pk_add_f32 v[70:71], v[116:117], v[178:179] neg_lo:[0,1] neg_hi:[0,1]
	v_mov_b32_e32 v116, v75
	v_pk_mul_f32 v[116:117], v[116:117], v[140:141] op_sel:[0,1] op_sel_hi:[0,0] neg_hi:[1,0]
	v_pk_fma_f32 v[116:117], v[140:141], v[74:75], v[116:117] op_sel_hi:[1,0,1]
	ds_write_b64 v221, v[116:117] offset:256
	v_pk_mul_f32 v[114:115], v[78:79], v[74:75] op_sel:[0,1] op_sel_hi:[1,0]
	v_pk_add_f32 v[172:173], v[128:129], v[72:73]
	v_pk_fma_f32 v[114:115], v[74:75], v[74:75], v[114:115] op_sel_hi:[1,0,1]
	v_pk_add_f32 v[128:129], v[128:129], v[72:73] op_sel:[1,1] op_sel_hi:[0,0] neg_lo:[0,1] neg_hi:[1,0]
	v_pk_mul_f32 v[116:117], v[154:155], v[114:115] op_sel:[1,1] op_sel_hi:[0,1] neg_hi:[0,1]
	v_pk_fma_f32 v[116:117], v[154:155], v[114:115], v[116:117] op_sel_hi:[1,0,1]
	ds_write_b64 v221, v[116:117] offset:520
	v_pk_mul_f32 v[116:117], v[78:79], v[114:115] op_sel:[0,1] op_sel_hi:[1,0]
	v_pk_add_f32 v[120:121], v[120:121], v[152:153] neg_lo:[0,1] neg_hi:[0,1]
	v_pk_fma_f32 v[114:115], v[114:115], v[74:75], v[116:117] op_sel_hi:[1,0,1]
	v_pk_add_f32 v[152:153], v[122:123], v[130:131]
	v_pk_add_f32 v[122:123], v[122:123], v[130:131] neg_lo:[0,1] neg_hi:[0,1]
	v_pk_add_f32 v[130:131], v[126:127], v[124:125]
	v_pk_add_f32 v[72:73], v[126:127], v[124:125] neg_lo:[0,1] neg_hi:[0,1]
	v_pk_add_f32 v[124:125], v[80:81], v[172:173]
	v_pk_mul_f32 v[116:117], v[124:125], v[114:115] op_sel:[1,1] op_sel_hi:[0,1] neg_hi:[0,1]
	v_pk_add_f32 v[126:127], v[80:81], v[172:173] neg_lo:[0,1] neg_hi:[0,1]
	v_pk_fma_f32 v[116:117], v[124:125], v[114:115], v[116:117] op_sel_hi:[1,0,1]
	ds_write_b64 v221, v[116:117] offset:784
	v_pk_mul_f32 v[112:113], v[78:79], v[114:115] op_sel:[0,1] op_sel_hi:[1,0]
	v_pk_add_f32 v[158:159], v[132:133], v[128:129]
	v_pk_fma_f32 v[112:113], v[114:115], v[74:75], v[112:113] op_sel_hi:[1,0,1]
	v_pk_add_f32 v[80:81], v[132:133], v[128:129] neg_lo:[0,1] neg_hi:[0,1]
	v_pk_add_f32 v[128:129], v[174:175], v[176:177]
	v_pk_mul_f32 v[114:115], v[134:135], v[112:113] op_sel:[1,1] op_sel_hi:[0,1] neg_hi:[0,1]
	v_pk_add_f32 v[146:147], v[148:149], v[164:165]
	v_pk_fma_f32 v[114:115], v[134:135], v[112:113], v[114:115] op_sel_hi:[1,0,1]
	ds_write_b64 v221, v[114:115] offset:1048
	v_pk_mul_f32 v[114:115], v[78:79], v[112:113] op_sel:[0,1] op_sel_hi:[1,0]
	v_pk_add_f32 v[132:133], v[174:175], v[176:177] neg_lo:[0,1] neg_hi:[0,1]
	v_pk_fma_f32 v[112:113], v[112:113], v[74:75], v[114:115] op_sel_hi:[1,0,1]
	v_pk_add_f32 v[148:149], v[148:149], v[164:165] neg_lo:[0,1] neg_hi:[0,1]
	v_pk_mul_f32 v[114:115], v[152:153], v[112:113] op_sel:[1,1] op_sel_hi:[0,1] neg_hi:[0,1]
	v_pk_fma_f32 v[114:115], v[152:153], v[112:113], v[114:115] op_sel_hi:[1,0,1]
	ds_write_b64 v221, v[114:115] offset:1312
	v_pk_mul_f32 v[110:111], v[78:79], v[112:113] op_sel:[0,1] op_sel_hi:[1,0]
	v_pk_fma_f32 v[110:111], v[112:113], v[74:75], v[110:111] op_sel_hi:[1,0,1]
	v_pk_mul_f32 v[112:113], v[144:145], v[110:111] op_sel:[1,1] op_sel_hi:[0,1] neg_hi:[0,1]
	v_pk_fma_f32 v[112:113], v[144:145], v[110:111], v[112:113] op_sel_hi:[1,0,1]
	ds_write_b64 v221, v[112:113] offset:1576
	v_pk_mul_f32 v[112:113], v[78:79], v[110:111] op_sel:[0,1] op_sel_hi:[1,0]
	v_pk_fma_f32 v[110:111], v[110:111], v[74:75], v[112:113] op_sel_hi:[1,0,1]
	v_pk_mul_f32 v[112:113], v[128:129], v[110:111] op_sel:[1,1] op_sel_hi:[0,1] neg_hi:[0,1]
	v_pk_fma_f32 v[112:113], v[128:129], v[110:111], v[112:113] op_sel_hi:[1,0,1]
	ds_write_b64 v221, v[112:113] offset:1840
	v_pk_mul_f32 v[108:109], v[78:79], v[110:111] op_sel:[0,1] op_sel_hi:[1,0]
	v_pk_fma_f32 v[108:109], v[110:111], v[74:75], v[108:109] op_sel_hi:[1,0,1]
	v_pk_mul_f32 v[110:111], v[168:169], v[108:109] op_sel:[1,1] op_sel_hi:[0,1] neg_hi:[0,1]
	v_pk_fma_f32 v[110:111], v[168:169], v[108:109], v[110:111] op_sel_hi:[1,0,1]
	ds_write_b64 v221, v[110:111] offset:2104
	v_pk_mul_f32 v[110:111], v[78:79], v[108:109] op_sel:[0,1] op_sel_hi:[1,0]
	v_pk_fma_f32 v[108:109], v[108:109], v[74:75], v[110:111] op_sel_hi:[1,0,1]
	v_pk_mul_f32 v[110:111], v[146:147], v[108:109] op_sel:[1,1] op_sel_hi:[0,1] neg_hi:[0,1]
	v_pk_fma_f32 v[110:111], v[146:147], v[108:109], v[110:111] op_sel_hi:[1,0,1]
	ds_write_b64 v221, v[110:111] offset:2368
	v_pk_mul_f32 v[106:107], v[78:79], v[108:109] op_sel:[0,1] op_sel_hi:[1,0]
	v_pk_fma_f32 v[106:107], v[108:109], v[74:75], v[106:107] op_sel_hi:[1,0,1]
	v_pk_mul_f32 v[108:109], v[156:157], v[106:107] op_sel:[1,1] op_sel_hi:[0,1] neg_hi:[0,1]
	v_pk_fma_f32 v[108:109], v[156:157], v[106:107], v[108:109] op_sel_hi:[1,0,1]
	ds_write_b64 v221, v[108:109] offset:2632
	v_pk_mul_f32 v[108:109], v[78:79], v[106:107] op_sel:[0,1] op_sel_hi:[1,0]
	v_pk_fma_f32 v[106:107], v[106:107], v[74:75], v[108:109] op_sel_hi:[1,0,1]
	v_pk_mul_f32 v[108:109], v[158:159], v[106:107] op_sel:[1,1] op_sel_hi:[0,1] neg_hi:[0,1]
	v_pk_fma_f32 v[108:109], v[158:159], v[106:107], v[108:109] op_sel_hi:[1,0,1]
	ds_write_b64 v221, v[108:109] offset:2896
	v_pk_mul_f32 v[108:109], v[78:79], v[106:107] op_sel:[0,1] op_sel_hi:[1,0]
	v_pk_fma_f32 v[106:107], v[106:107], v[74:75], v[108:109] op_sel_hi:[1,0,1]
	v_pk_mul_f32 v[108:109], v[160:161], v[106:107] op_sel:[1,1] op_sel_hi:[0,1] neg_hi:[0,1]
	v_pk_fma_f32 v[108:109], v[160:161], v[106:107], v[108:109] op_sel_hi:[1,0,1]
	ds_write_b64 v221, v[108:109] offset:3160
	v_pk_mul_f32 v[102:103], v[78:79], v[106:107] op_sel:[0,1] op_sel_hi:[1,0]
	v_pk_fma_f32 v[102:103], v[106:107], v[74:75], v[102:103] op_sel_hi:[1,0,1]
	v_pk_mul_f32 v[106:107], v[130:131], v[102:103] op_sel:[1,1] op_sel_hi:[0,1] neg_hi:[0,1]
	v_pk_fma_f32 v[106:107], v[130:131], v[102:103], v[106:107] op_sel_hi:[1,0,1]
	ds_write_b64 v221, v[106:107] offset:3424
	v_pk_mul_f32 v[106:107], v[78:79], v[102:103] op_sel:[0,1] op_sel_hi:[1,0]
	v_pk_fma_f32 v[102:103], v[102:103], v[74:75], v[106:107] op_sel_hi:[1,0,1]
	v_pk_mul_f32 v[106:107], v[150:151], v[102:103] op_sel:[1,1] op_sel_hi:[0,1] neg_hi:[0,1]
	v_pk_fma_f32 v[106:107], v[150:151], v[102:103], v[106:107] op_sel_hi:[1,0,1]
	ds_write_b64 v221, v[106:107] offset:3688
	v_pk_mul_f32 v[100:101], v[78:79], v[102:103] op_sel:[0,1] op_sel_hi:[1,0]
	v_pk_fma_f32 v[100:101], v[102:103], v[74:75], v[100:101] op_sel_hi:[1,0,1]
	v_pk_mul_f32 v[102:103], v[162:163], v[100:101] op_sel:[1,1] op_sel_hi:[0,1] neg_hi:[0,1]
	v_pk_fma_f32 v[102:103], v[162:163], v[100:101], v[102:103] op_sel_hi:[1,0,1]
	ds_write_b64 v221, v[102:103] offset:3952
	v_pk_mul_f32 v[102:103], v[78:79], v[100:101] op_sel:[0,1] op_sel_hi:[1,0]
	v_pk_fma_f32 v[100:101], v[100:101], v[74:75], v[102:103] op_sel_hi:[1,0,1]
	v_pk_mul_f32 v[102:103], v[118:119], v[100:101] op_sel:[1,1] op_sel_hi:[0,1] neg_hi:[0,1]
	v_pk_fma_f32 v[102:103], v[118:119], v[100:101], v[102:103] op_sel_hi:[1,0,1]
	ds_write_b64 v221, v[102:103] offset:4216
	v_pk_mul_f32 v[98:99], v[78:79], v[100:101] op_sel:[0,1] op_sel_hi:[1,0]
	v_pk_fma_f32 v[98:99], v[100:101], v[74:75], v[98:99] op_sel_hi:[1,0,1]
	v_pk_mul_f32 v[100:101], v[120:121], v[98:99] op_sel:[1,1] op_sel_hi:[0,1] neg_hi:[0,1]
	v_pk_fma_f32 v[100:101], v[120:121], v[98:99], v[100:101] op_sel_hi:[1,0,1]
	ds_write_b64 v221, v[100:101] offset:4480
	v_pk_mul_f32 v[100:101], v[78:79], v[98:99] op_sel:[0,1] op_sel_hi:[1,0]
	v_pk_fma_f32 v[98:99], v[98:99], v[74:75], v[100:101] op_sel_hi:[1,0,1]
	v_pk_mul_f32 v[100:101], v[142:143], v[98:99] op_sel:[1,1] op_sel_hi:[0,1] neg_hi:[0,1]
	v_pk_fma_f32 v[100:101], v[142:143], v[98:99], v[100:101] op_sel_hi:[1,0,1]
	ds_write_b64 v221, v[100:101] offset:4744
	v_pk_mul_f32 v[96:97], v[78:79], v[98:99] op_sel:[0,1] op_sel_hi:[1,0]
	v_pk_fma_f32 v[96:97], v[98:99], v[74:75], v[96:97] op_sel_hi:[1,0,1]
	v_pk_mul_f32 v[98:99], v[126:127], v[96:97] op_sel:[1,1] op_sel_hi:[0,1] neg_hi:[0,1]
	v_pk_fma_f32 v[98:99], v[126:127], v[96:97], v[98:99] op_sel_hi:[1,0,1]
	ds_write_b64 v221, v[98:99] offset:5008
	v_pk_mul_f32 v[98:99], v[78:79], v[96:97] op_sel:[0,1] op_sel_hi:[1,0]
	v_pk_fma_f32 v[96:97], v[96:97], v[74:75], v[98:99] op_sel_hi:[1,0,1]
	v_pk_mul_f32 v[98:99], v[136:137], v[96:97] op_sel:[1,1] op_sel_hi:[0,1] neg_hi:[0,1]
	v_pk_fma_f32 v[98:99], v[136:137], v[96:97], v[98:99] op_sel_hi:[1,0,1]
	ds_write_b64 v221, v[98:99] offset:5272
	v_pk_mul_f32 v[94:95], v[78:79], v[96:97] op_sel:[0,1] op_sel_hi:[1,0]
	v_pk_fma_f32 v[94:95], v[96:97], v[74:75], v[94:95] op_sel_hi:[1,0,1]
	v_pk_mul_f32 v[96:97], v[122:123], v[94:95] op_sel:[1,1] op_sel_hi:[0,1] neg_hi:[0,1]
	v_pk_fma_f32 v[96:97], v[122:123], v[94:95], v[96:97] op_sel_hi:[1,0,1]
	ds_write_b64 v221, v[96:97] offset:5536
	v_pk_mul_f32 v[96:97], v[78:79], v[94:95] op_sel:[0,1] op_sel_hi:[1,0]
	v_pk_fma_f32 v[94:95], v[94:95], v[74:75], v[96:97] op_sel_hi:[1,0,1]
	v_pk_mul_f32 v[96:97], v[138:139], v[94:95] op_sel:[1,1] op_sel_hi:[0,1] neg_hi:[0,1]
	v_pk_fma_f32 v[96:97], v[138:139], v[94:95], v[96:97] op_sel_hi:[1,0,1]
	ds_write_b64 v221, v[96:97] offset:5800
	v_pk_mul_f32 v[92:93], v[78:79], v[94:95] op_sel:[0,1] op_sel_hi:[1,0]
	v_pk_fma_f32 v[92:93], v[94:95], v[74:75], v[92:93] op_sel_hi:[1,0,1]
	v_pk_mul_f32 v[94:95], v[132:133], v[92:93] op_sel:[1,1] op_sel_hi:[0,1] neg_hi:[0,1]
	v_pk_fma_f32 v[94:95], v[132:133], v[92:93], v[94:95] op_sel_hi:[1,0,1]
	ds_write_b64 v221, v[94:95] offset:6064
	v_pk_mul_f32 v[94:95], v[78:79], v[92:93] op_sel:[0,1] op_sel_hi:[1,0]
	v_pk_fma_f32 v[92:93], v[92:93], v[74:75], v[94:95] op_sel_hi:[1,0,1]
	v_pk_mul_f32 v[94:95], v[82:83], v[92:93] op_sel:[1,1] op_sel_hi:[0,1] neg_hi:[0,1]
	v_pk_fma_f32 v[82:83], v[82:83], v[92:93], v[94:95] op_sel_hi:[1,0,1]
	ds_write_b64 v221, v[82:83] offset:6328
	v_pk_mul_f32 v[82:83], v[78:79], v[92:93] op_sel:[0,1] op_sel_hi:[1,0]
	v_pk_fma_f32 v[82:83], v[92:93], v[74:75], v[82:83] op_sel_hi:[1,0,1]
	v_pk_mul_f32 v[90:91], v[148:149], v[82:83] op_sel:[1,1] op_sel_hi:[0,1] neg_hi:[0,1]
	v_pk_fma_f32 v[90:91], v[148:149], v[82:83], v[90:91] op_sel_hi:[1,0,1]
	ds_write_b64 v221, v[90:91] offset:6592
	v_pk_mul_f32 v[90:91], v[78:79], v[82:83] op_sel:[0,1] op_sel_hi:[1,0]
	v_pk_fma_f32 v[82:83], v[82:83], v[74:75], v[90:91] op_sel_hi:[1,0,1]
	v_pk_mul_f32 v[90:91], v[76:77], v[82:83] op_sel:[1,1] op_sel_hi:[0,1] neg_hi:[0,1]
	v_pk_fma_f32 v[76:77], v[76:77], v[82:83], v[90:91] op_sel_hi:[1,0,1]
	ds_write_b64 v221, v[76:77] offset:6856
	v_pk_mul_f32 v[76:77], v[78:79], v[82:83] op_sel:[0,1] op_sel_hi:[1,0]
	v_pk_fma_f32 v[76:77], v[82:83], v[74:75], v[76:77] op_sel_hi:[1,0,1]
	v_pk_mul_f32 v[82:83], v[80:81], v[76:77] op_sel:[1,1] op_sel_hi:[0,1] neg_hi:[0,1]
	v_pk_fma_f32 v[80:81], v[80:81], v[76:77], v[82:83] op_sel_hi:[1,0,1]
	ds_write_b64 v221, v[80:81] offset:7120
	v_pk_mul_f32 v[80:81], v[78:79], v[76:77] op_sel:[0,1] op_sel_hi:[1,0]
	v_pk_fma_f32 v[76:77], v[76:77], v[74:75], v[80:81] op_sel_hi:[1,0,1]
	v_pk_mul_f32 v[80:81], v[68:69], v[76:77] op_sel:[1,1] op_sel_hi:[0,1] neg_hi:[0,1]
	v_pk_fma_f32 v[68:69], v[68:69], v[76:77], v[80:81] op_sel_hi:[1,0,1]
	ds_write_b64 v221, v[68:69] offset:7384
	v_pk_mul_f32 v[68:69], v[78:79], v[76:77] op_sel:[0,1] op_sel_hi:[1,0]
	v_pk_fma_f32 v[68:69], v[76:77], v[74:75], v[68:69] op_sel_hi:[1,0,1]
	v_pk_mul_f32 v[76:77], v[72:73], v[68:69] op_sel:[1,1] op_sel_hi:[0,1] neg_hi:[0,1]
	v_pk_fma_f32 v[72:73], v[72:73], v[68:69], v[76:77] op_sel_hi:[1,0,1]
	ds_write_b64 v221, v[72:73] offset:7648
	v_pk_mul_f32 v[72:73], v[78:79], v[68:69] op_sel:[0,1] op_sel_hi:[1,0]
	v_pk_fma_f32 v[68:69], v[68:69], v[74:75], v[72:73] op_sel_hi:[1,0,1]
	v_pk_mul_f32 v[72:73], v[66:67], v[68:69] op_sel:[1,1] op_sel_hi:[0,1] neg_hi:[0,1]
	v_pk_fma_f32 v[66:67], v[66:67], v[68:69], v[72:73] op_sel_hi:[1,0,1]
	ds_write_b64 v221, v[66:67] offset:7912
	v_pk_mul_f32 v[66:67], v[78:79], v[68:69] op_sel:[0,1] op_sel_hi:[1,0]
	v_pk_fma_f32 v[66:67], v[68:69], v[74:75], v[66:67] op_sel_hi:[1,0,1]
	v_pk_mul_f32 v[68:69], v[70:71], v[66:67] op_sel:[1,1] op_sel_hi:[0,1] neg_hi:[0,1]
	v_pk_fma_f32 v[66:67], v[70:71], v[66:67], v[68:69] op_sel_hi:[1,0,1]
	ds_write_b64 v221, v[66:67] offset:8176
	s_waitcnt lgkmcnt(0)
	s_barrier
	ds_read2_b64 v[66:69], v104 offset1:1
	ds_read2_b64 v[70:73], v104 offset0:2 offset1:3
	ds_read2_b64 v[74:77], v104 offset0:4 offset1:5
	ds_read2_b64 v[78:81], v104 offset0:6 offset1:7
	ds_read2_b64 v[82:85], v104 offset0:8 offset1:9
	ds_read2_b64 v[86:89], v104 offset0:10 offset1:11
	ds_read2_b64 v[90:93], v104 offset0:12 offset1:13
	ds_read2_b64 v[94:97], v104 offset0:14 offset1:15
	ds_read2_b64 v[98:101], v104 offset0:16 offset1:17
	ds_read2_b64 v[106:109], v104 offset0:18 offset1:19
	ds_read2_b64 v[110:113], v104 offset0:20 offset1:21
	ds_read2_b64 v[114:117], v104 offset0:22 offset1:23
	ds_read2_b64 v[118:121], v104 offset0:24 offset1:25
	ds_read2_b64 v[122:125], v104 offset0:26 offset1:27
	ds_read2_b64 v[126:129], v104 offset0:28 offset1:29
	ds_read2_b64 v[130:133], v104 offset0:30 offset1:31
	s_waitcnt lgkmcnt(7)
	v_pk_add_f32 v[102:103], v[66:67], v[98:99]
	v_pk_add_f32 v[66:67], v[66:67], v[98:99] neg_lo:[0,1] neg_hi:[0,1]
	v_pk_add_f32 v[98:99], v[68:69], v[100:101]
	v_pk_add_f32 v[68:69], v[68:69], v[100:101] neg_lo:[0,1] neg_hi:[0,1]
	v_pk_mul_f32 v[100:101], v[68:69], s[18:19]
	v_pk_fma_f32 v[68:69], v[68:69], s[20:21], v[100:101] op_sel:[0,0,1] op_sel_hi:[1,0,0]
	s_waitcnt lgkmcnt(6)
	v_pk_add_f32 v[100:101], v[70:71], v[106:107]
	v_pk_add_f32 v[70:71], v[70:71], v[106:107] neg_lo:[0,1] neg_hi:[0,1]
	v_pk_mul_f32 v[106:107], v[70:71], s[4:5]
	v_pk_fma_f32 v[70:71], v[70:71], s[6:7], v[106:107] op_sel:[0,0,1] op_sel_hi:[1,0,0]
	v_pk_add_f32 v[106:107], v[72:73], v[108:109]
	v_pk_add_f32 v[72:73], v[72:73], v[108:109] neg_lo:[0,1] neg_hi:[0,1]
	v_pk_mul_f32 v[108:109], v[72:73], s[22:23]
	v_pk_fma_f32 v[72:73], v[72:73], s[24:25], v[108:109] op_sel:[0,0,1] op_sel_hi:[1,0,0]
	s_waitcnt lgkmcnt(5)
	v_pk_add_f32 v[108:109], v[74:75], v[110:111]
	v_pk_add_f32 v[74:75], v[74:75], v[110:111] neg_lo:[0,1] neg_hi:[0,1]
	v_pk_mul_f32 v[110:111], v[74:75], s[8:9]
	v_pk_fma_f32 v[74:75], v[74:75], s[10:11], v[110:111] op_sel:[0,0,1] op_sel_hi:[1,0,0]
	v_pk_add_f32 v[110:111], v[76:77], v[112:113]
	v_pk_add_f32 v[76:77], v[76:77], v[112:113] neg_lo:[0,1] neg_hi:[0,1]
	v_pk_mul_f32 v[112:113], v[76:77], s[26:27]
	v_pk_fma_f32 v[76:77], v[76:77], s[0:1], v[112:113] op_sel:[0,0,1] op_sel_hi:[1,0,0]
	s_waitcnt lgkmcnt(4)
	v_pk_add_f32 v[112:113], v[78:79], v[114:115]
	v_pk_add_f32 v[78:79], v[78:79], v[114:115] neg_lo:[0,1] neg_hi:[0,1]
	s_mov_b64 s[0:1], 0
	v_pk_mul_f32 v[114:115], v[78:79], s[12:13]
	v_pk_fma_f32 v[78:79], v[78:79], s[14:15], v[114:115] op_sel:[0,0,1] op_sel_hi:[1,0,0]
	v_pk_add_f32 v[114:115], v[80:81], v[116:117]
	v_pk_add_f32 v[80:81], v[80:81], v[116:117] neg_lo:[0,1] neg_hi:[0,1]
	v_pk_mul_f32 v[116:117], v[80:81], s[34:35]
	v_pk_fma_f32 v[80:81], v[80:81], s[44:45], v[116:117] op_sel:[0,0,1] op_sel_hi:[1,0,0]
	s_waitcnt lgkmcnt(3)
	v_pk_add_f32 v[116:117], v[82:83], v[118:119]
	v_pk_add_f32 v[118:119], v[82:83], v[118:119] op_sel:[1,1] op_sel_hi:[0,0] neg_lo:[0,1] neg_hi:[1,0]
	s_mov_b64 s[44:45], -1
	v_pk_add_f32 v[82:83], v[84:85], v[120:121]
	v_pk_add_f32 v[84:85], v[84:85], v[120:121] neg_lo:[0,1] neg_hi:[0,1]
	v_pk_mul_f32 v[120:121], v[84:85], s[34:35]
	v_pk_fma_f32 v[84:85], v[84:85], s[18:19], v[120:121] op_sel:[0,0,1] op_sel_hi:[1,0,0]
	s_waitcnt lgkmcnt(2)
	v_pk_add_f32 v[120:121], v[86:87], v[122:123]
	v_pk_add_f32 v[86:87], v[86:87], v[122:123] neg_lo:[0,1] neg_hi:[0,1]
	v_pk_mul_f32 v[122:123], v[86:87], s[12:13]
	v_pk_fma_f32 v[86:87], v[86:87], s[4:5], v[122:123] op_sel:[0,0,1] op_sel_hi:[1,0,0]
	v_pk_add_f32 v[122:123], v[88:89], v[124:125]
	v_pk_add_f32 v[88:89], v[88:89], v[124:125] neg_lo:[0,1] neg_hi:[0,1]
	v_pk_mul_f32 v[124:125], v[88:89], s[26:27]
	v_pk_fma_f32 v[88:89], v[88:89], s[22:23], v[124:125] op_sel:[0,0,1] op_sel_hi:[1,0,0]
	s_waitcnt lgkmcnt(1)
	v_pk_add_f32 v[124:125], v[90:91], v[126:127]
	v_pk_add_f32 v[90:91], v[90:91], v[126:127] neg_lo:[0,1] neg_hi:[0,1]
	v_pk_mul_f32 v[126:127], v[90:91], s[8:9]
	v_pk_fma_f32 v[90:91], v[90:91], s[8:9], v[126:127] op_sel:[0,0,1] op_sel_hi:[1,0,0]
	v_pk_add_f32 v[126:127], v[92:93], v[128:129]
	v_pk_add_f32 v[92:93], v[92:93], v[128:129] neg_lo:[0,1] neg_hi:[0,1]
	v_pk_mul_f32 v[128:129], v[92:93], s[22:23]
	v_pk_fma_f32 v[92:93], v[92:93], s[26:27], v[128:129] op_sel:[0,0,1] op_sel_hi:[1,0,0]
	s_waitcnt lgkmcnt(0)
	v_pk_add_f32 v[128:129], v[94:95], v[130:131]
	v_pk_add_f32 v[94:95], v[94:95], v[130:131] neg_lo:[0,1] neg_hi:[0,1]
	v_pk_mul_f32 v[130:131], v[94:95], s[4:5]
	v_pk_fma_f32 v[94:95], v[94:95], s[12:13], v[130:131] op_sel:[0,0,1] op_sel_hi:[1,0,0]
	v_pk_add_f32 v[130:131], v[96:97], v[132:133]
	v_pk_add_f32 v[96:97], v[96:97], v[132:133] neg_lo:[0,1] neg_hi:[0,1]
	v_pk_mul_f32 v[132:133], v[96:97], s[18:19]
	v_pk_fma_f32 v[96:97], v[96:97], s[34:35], v[132:133] op_sel:[0,0,1] op_sel_hi:[1,0,0]
	v_pk_add_f32 v[132:133], v[102:103], v[116:117]
	v_pk_add_f32 v[102:103], v[102:103], v[116:117] neg_lo:[0,1] neg_hi:[0,1]
	v_pk_add_f32 v[116:117], v[98:99], v[82:83]
	v_pk_add_f32 v[82:83], v[98:99], v[82:83] neg_lo:[0,1] neg_hi:[0,1]
	v_pk_mul_f32 v[98:99], v[82:83], s[4:5]
	v_pk_fma_f32 v[82:83], v[82:83], s[6:7], v[98:99] op_sel:[0,0,1] op_sel_hi:[1,0,0]
	v_pk_add_f32 v[98:99], v[100:101], v[120:121]
	v_pk_add_f32 v[100:101], v[100:101], v[120:121] neg_lo:[0,1] neg_hi:[0,1]
	v_pk_mul_f32 v[120:121], v[100:101], s[8:9]
	v_pk_fma_f32 v[100:101], v[100:101], s[10:11], v[120:121] op_sel:[0,0,1] op_sel_hi:[1,0,0]
	v_pk_add_f32 v[120:121], v[106:107], v[122:123]
	v_pk_add_f32 v[106:107], v[106:107], v[122:123] neg_lo:[0,1] neg_hi:[0,1]
	v_pk_mul_f32 v[122:123], v[106:107], s[12:13]
	v_pk_fma_f32 v[106:107], v[106:107], s[14:15], v[122:123] op_sel:[0,0,1] op_sel_hi:[1,0,0]
	v_pk_add_f32 v[122:123], v[108:109], v[124:125]
	v_pk_add_f32 v[124:125], v[108:109], v[124:125] op_sel:[1,1] op_sel_hi:[0,0] neg_lo:[0,1] neg_hi:[1,0]
	v_pk_add_f32 v[108:109], v[110:111], v[126:127]
	v_pk_add_f32 v[110:111], v[110:111], v[126:127] neg_lo:[0,1] neg_hi:[0,1]
	v_pk_mul_f32 v[126:127], v[110:111], s[12:13]
	v_pk_fma_f32 v[110:111], v[110:111], s[4:5], v[126:127] op_sel:[0,0,1] op_sel_hi:[1,0,0]
	v_pk_add_f32 v[126:127], v[112:113], v[128:129]
	v_pk_add_f32 v[112:113], v[112:113], v[128:129] neg_lo:[0,1] neg_hi:[0,1]
	v_pk_mul_f32 v[128:129], v[112:113], s[8:9]
	v_pk_fma_f32 v[112:113], v[112:113], s[8:9], v[128:129] op_sel:[0,0,1] op_sel_hi:[1,0,0]
	v_pk_add_f32 v[128:129], v[114:115], v[130:131]
	v_pk_add_f32 v[114:115], v[114:115], v[130:131] neg_lo:[0,1] neg_hi:[0,1]
	v_pk_mul_f32 v[130:131], v[114:115], s[4:5]
	v_pk_fma_f32 v[114:115], v[114:115], s[12:13], v[130:131] op_sel:[0,0,1] op_sel_hi:[1,0,0]
	v_pk_add_f32 v[130:131], v[66:67], v[118:119]
	v_pk_add_f32 v[66:67], v[66:67], v[118:119] neg_lo:[0,1] neg_hi:[0,1]
	v_pk_add_f32 v[118:119], v[68:69], v[84:85]
	v_pk_add_f32 v[68:69], v[68:69], v[84:85] neg_lo:[0,1] neg_hi:[0,1]
	v_pk_mul_f32 v[84:85], v[68:69], s[4:5]
	v_pk_fma_f32 v[68:69], v[68:69], s[6:7], v[84:85] op_sel:[0,0,1] op_sel_hi:[1,0,0]
	v_pk_add_f32 v[84:85], v[70:71], v[86:87]
	v_pk_add_f32 v[70:71], v[70:71], v[86:87] neg_lo:[0,1] neg_hi:[0,1]
	v_pk_mul_f32 v[86:87], v[70:71], s[8:9]
	v_pk_fma_f32 v[70:71], v[70:71], s[10:11], v[86:87] op_sel:[0,0,1] op_sel_hi:[1,0,0]
	v_pk_add_f32 v[86:87], v[72:73], v[88:89]
	v_pk_add_f32 v[72:73], v[72:73], v[88:89] neg_lo:[0,1] neg_hi:[0,1]
	v_pk_mul_f32 v[88:89], v[72:73], s[12:13]
	v_pk_fma_f32 v[72:73], v[72:73], s[14:15], v[88:89] op_sel:[0,0,1] op_sel_hi:[1,0,0]
	v_pk_add_f32 v[88:89], v[74:75], v[90:91]
	v_pk_add_f32 v[90:91], v[74:75], v[90:91] op_sel:[1,1] op_sel_hi:[0,0] neg_lo:[0,1] neg_hi:[1,0]
	v_pk_add_f32 v[74:75], v[76:77], v[92:93]
	v_pk_add_f32 v[76:77], v[76:77], v[92:93] neg_lo:[0,1] neg_hi:[0,1]
	v_pk_mul_f32 v[92:93], v[76:77], s[12:13]
	v_pk_fma_f32 v[76:77], v[76:77], s[4:5], v[92:93] op_sel:[0,0,1] op_sel_hi:[1,0,0]
	v_pk_add_f32 v[92:93], v[78:79], v[94:95]
	v_pk_add_f32 v[78:79], v[78:79], v[94:95] neg_lo:[0,1] neg_hi:[0,1]
	v_pk_mul_f32 v[94:95], v[78:79], s[8:9]
	v_pk_fma_f32 v[78:79], v[78:79], s[8:9], v[94:95] op_sel:[0,0,1] op_sel_hi:[1,0,0]
	v_pk_add_f32 v[94:95], v[80:81], v[96:97]
	v_pk_add_f32 v[80:81], v[80:81], v[96:97] neg_lo:[0,1] neg_hi:[0,1]
	v_pk_mul_f32 v[96:97], v[80:81], s[4:5]
	v_pk_fma_f32 v[80:81], v[80:81], s[12:13], v[96:97] op_sel:[0,0,1] op_sel_hi:[1,0,0]
	v_pk_add_f32 v[96:97], v[132:133], v[122:123]
	v_pk_add_f32 v[122:123], v[132:133], v[122:123] neg_lo:[0,1] neg_hi:[0,1]
	v_pk_add_f32 v[132:133], v[116:117], v[108:109]
	v_pk_add_f32 v[108:109], v[116:117], v[108:109] neg_lo:[0,1] neg_hi:[0,1]
	v_pk_mul_f32 v[116:117], v[108:109], s[8:9]
	v_pk_fma_f32 v[108:109], v[108:109], s[10:11], v[116:117] op_sel:[0,0,1] op_sel_hi:[1,0,0]
	v_pk_add_f32 v[116:117], v[98:99], v[126:127]
	v_pk_add_f32 v[126:127], v[98:99], v[126:127] op_sel:[1,1] op_sel_hi:[0,0] neg_lo:[0,1] neg_hi:[1,0]
	v_pk_add_f32 v[98:99], v[120:121], v[128:129]
	v_pk_add_f32 v[120:121], v[120:121], v[128:129] neg_lo:[0,1] neg_hi:[0,1]
	v_pk_mul_f32 v[128:129], v[120:121], s[8:9]
	v_pk_fma_f32 v[120:121], v[120:121], s[8:9], v[128:129] op_sel:[0,0,1] op_sel_hi:[1,0,0]
	v_pk_add_f32 v[128:129], v[102:103], v[124:125]
	v_pk_add_f32 v[102:103], v[102:103], v[124:125] neg_lo:[0,1] neg_hi:[0,1]
	v_pk_add_f32 v[124:125], v[82:83], v[110:111]
	v_pk_add_f32 v[82:83], v[82:83], v[110:111] neg_lo:[0,1] neg_hi:[0,1]
	v_pk_mul_f32 v[110:111], v[82:83], s[8:9]
	v_pk_fma_f32 v[82:83], v[82:83], s[10:11], v[110:111] op_sel:[0,0,1] op_sel_hi:[1,0,0]
	v_pk_add_f32 v[110:111], v[100:101], v[112:113]
	v_pk_add_f32 v[112:113], v[100:101], v[112:113] op_sel:[1,1] op_sel_hi:[0,0] neg_lo:[0,1] neg_hi:[1,0]
	v_pk_add_f32 v[100:101], v[106:107], v[114:115]
	v_pk_add_f32 v[106:107], v[106:107], v[114:115] neg_lo:[0,1] neg_hi:[0,1]
	v_pk_mul_f32 v[114:115], v[106:107], s[8:9]
	v_pk_fma_f32 v[106:107], v[106:107], s[8:9], v[114:115] op_sel:[0,0,1] op_sel_hi:[1,0,0]
	v_pk_add_f32 v[114:115], v[130:131], v[88:89]
	v_pk_add_f32 v[88:89], v[130:131], v[88:89] neg_lo:[0,1] neg_hi:[0,1]
	v_pk_add_f32 v[130:131], v[118:119], v[74:75]
	v_pk_add_f32 v[74:75], v[118:119], v[74:75] neg_lo:[0,1] neg_hi:[0,1]
	v_pk_mul_f32 v[118:119], v[74:75], s[8:9]
	v_pk_fma_f32 v[74:75], v[74:75], s[10:11], v[118:119] op_sel:[0,0,1] op_sel_hi:[1,0,0]
	v_pk_add_f32 v[118:119], v[84:85], v[92:93]
	v_pk_add_f32 v[92:93], v[84:85], v[92:93] op_sel:[1,1] op_sel_hi:[0,0] neg_lo:[0,1] neg_hi:[1,0]
	v_pk_add_f32 v[84:85], v[86:87], v[94:95]
	v_pk_add_f32 v[86:87], v[86:87], v[94:95] neg_lo:[0,1] neg_hi:[0,1]
	v_pk_mul_f32 v[94:95], v[86:87], s[8:9]
	v_pk_fma_f32 v[86:87], v[86:87], s[8:9], v[94:95] op_sel:[0,0,1] op_sel_hi:[1,0,0]
	v_pk_add_f32 v[94:95], v[66:67], v[90:91]
	v_pk_add_f32 v[66:67], v[66:67], v[90:91] neg_lo:[0,1] neg_hi:[0,1]
	v_pk_add_f32 v[90:91], v[68:69], v[76:77]
	v_pk_add_f32 v[68:69], v[68:69], v[76:77] neg_lo:[0,1] neg_hi:[0,1]
	v_pk_mul_f32 v[76:77], v[68:69], s[8:9]
	v_pk_fma_f32 v[68:69], v[68:69], s[10:11], v[76:77] op_sel:[0,0,1] op_sel_hi:[1,0,0]
	v_pk_add_f32 v[76:77], v[70:71], v[78:79]
	v_pk_add_f32 v[78:79], v[70:71], v[78:79] op_sel:[1,1] op_sel_hi:[0,0] neg_lo:[0,1] neg_hi:[1,0]
	v_pk_add_f32 v[70:71], v[72:73], v[80:81]
	v_pk_add_f32 v[72:73], v[72:73], v[80:81] neg_lo:[0,1] neg_hi:[0,1]
	v_pk_mul_f32 v[80:81], v[72:73], s[8:9]
	v_pk_fma_f32 v[72:73], v[72:73], s[8:9], v[80:81] op_sel:[0,0,1] op_sel_hi:[1,0,0]
	v_pk_add_f32 v[80:81], v[96:97], v[116:117]
	v_pk_add_f32 v[96:97], v[96:97], v[116:117] neg_lo:[0,1] neg_hi:[0,1]
	v_pk_add_f32 v[116:117], v[132:133], v[98:99]
	v_pk_add_f32 v[132:133], v[132:133], v[98:99] op_sel:[1,1] op_sel_hi:[0,0] neg_lo:[0,1] neg_hi:[1,0]
	v_pk_add_f32 v[98:99], v[122:123], v[126:127]
	v_pk_add_f32 v[122:123], v[122:123], v[126:127] neg_lo:[0,1] neg_hi:[0,1]
	v_pk_add_f32 v[126:127], v[108:109], v[120:121]
	v_pk_add_f32 v[120:121], v[108:109], v[120:121] op_sel:[1,1] op_sel_hi:[0,0] neg_lo:[0,1] neg_hi:[1,0]
	v_pk_add_f32 v[108:109], v[128:129], v[110:111]
	v_pk_add_f32 v[110:111], v[128:129], v[110:111] neg_lo:[0,1] neg_hi:[0,1]
	v_pk_add_f32 v[128:129], v[124:125], v[100:101]
	v_pk_add_f32 v[124:125], v[124:125], v[100:101] op_sel:[1,1] op_sel_hi:[0,0] neg_lo:[0,1] neg_hi:[1,0]
	v_pk_add_f32 v[100:101], v[102:103], v[112:113]
	v_pk_add_f32 v[102:103], v[102:103], v[112:113] neg_lo:[0,1] neg_hi:[0,1]
	v_pk_add_f32 v[112:113], v[82:83], v[106:107]
	v_pk_add_f32 v[106:107], v[82:83], v[106:107] op_sel:[1,1] op_sel_hi:[0,0] neg_lo:[0,1] neg_hi:[1,0]
	v_pk_add_f32 v[82:83], v[114:115], v[118:119]
	v_pk_add_f32 v[114:115], v[114:115], v[118:119] neg_lo:[0,1] neg_hi:[0,1]
	v_pk_add_f32 v[118:119], v[130:131], v[84:85]
	v_pk_add_f32 v[130:131], v[130:131], v[84:85] op_sel:[1,1] op_sel_hi:[0,0] neg_lo:[0,1] neg_hi:[1,0]
	v_pk_add_f32 v[84:85], v[88:89], v[92:93]
	v_pk_add_f32 v[88:89], v[88:89], v[92:93] neg_lo:[0,1] neg_hi:[0,1]
	v_pk_add_f32 v[92:93], v[74:75], v[86:87]
	v_pk_add_f32 v[86:87], v[74:75], v[86:87] op_sel:[1,1] op_sel_hi:[0,0] neg_lo:[0,1] neg_hi:[1,0]
	v_pk_add_f32 v[74:75], v[94:95], v[76:77]
	v_pk_add_f32 v[76:77], v[94:95], v[76:77] neg_lo:[0,1] neg_hi:[0,1]
	v_pk_add_f32 v[94:95], v[90:91], v[70:71]
	v_pk_add_f32 v[90:91], v[90:91], v[70:71] op_sel:[1,1] op_sel_hi:[0,0] neg_lo:[0,1] neg_hi:[1,0]
	v_pk_add_f32 v[70:71], v[66:67], v[78:79]
	v_pk_add_f32 v[66:67], v[66:67], v[78:79] neg_lo:[0,1] neg_hi:[0,1]
	v_pk_add_f32 v[78:79], v[68:69], v[72:73]
	v_pk_add_f32 v[72:73], v[68:69], v[72:73] op_sel:[1,1] op_sel_hi:[0,0] neg_lo:[0,1] neg_hi:[1,0]
	v_pk_add_f32 v[68:69], v[80:81], v[116:117]
	v_pk_add_f32 v[80:81], v[80:81], v[116:117] neg_lo:[0,1] neg_hi:[0,1]
	v_pk_add_f32 v[116:117], v[96:97], v[132:133]
	v_pk_add_f32 v[96:97], v[96:97], v[132:133] neg_lo:[0,1] neg_hi:[0,1]
	v_pk_add_f32 v[132:133], v[98:99], v[126:127]
	v_pk_add_f32 v[98:99], v[98:99], v[126:127] neg_lo:[0,1] neg_hi:[0,1]
	v_pk_add_f32 v[126:127], v[122:123], v[120:121]
	v_pk_add_f32 v[120:121], v[122:123], v[120:121] neg_lo:[0,1] neg_hi:[0,1]
	v_pk_add_f32 v[122:123], v[108:109], v[128:129]
	v_pk_add_f32 v[108:109], v[108:109], v[128:129] neg_lo:[0,1] neg_hi:[0,1]
	v_pk_add_f32 v[128:129], v[110:111], v[124:125]
	v_pk_add_f32 v[110:111], v[110:111], v[124:125] neg_lo:[0,1] neg_hi:[0,1]
	v_pk_add_f32 v[124:125], v[100:101], v[112:113]
	v_pk_add_f32 v[100:101], v[100:101], v[112:113] neg_lo:[0,1] neg_hi:[0,1]
	v_pk_add_f32 v[112:113], v[102:103], v[106:107]
	v_pk_add_f32 v[102:103], v[102:103], v[106:107] neg_lo:[0,1] neg_hi:[0,1]
	v_pk_add_f32 v[106:107], v[82:83], v[118:119]
	v_pk_mul_f32 v[68:69], v[68:69], s[2:3] op_sel_hi:[1,0]
	global_store_dwordx2 v[2:3], v[68:69], off
	v_pk_mul_f32 v[68:69], v[106:107], s[2:3] op_sel_hi:[1,0]
	v_pk_add_f32 v[82:83], v[82:83], v[118:119] neg_lo:[0,1] neg_hi:[0,1]
	v_pk_add_f32 v[118:119], v[114:115], v[130:131]
	v_pk_add_f32 v[114:115], v[114:115], v[130:131] neg_lo:[0,1] neg_hi:[0,1]
	v_pk_add_f32 v[130:131], v[84:85], v[92:93]
	v_pk_add_f32 v[84:85], v[84:85], v[92:93] neg_lo:[0,1] neg_hi:[0,1]
	v_pk_add_f32 v[92:93], v[88:89], v[86:87]
	v_pk_add_f32 v[86:87], v[88:89], v[86:87] neg_lo:[0,1] neg_hi:[0,1]
	v_pk_add_f32 v[88:89], v[74:75], v[94:95]
	global_store_dwordx2 v[4:5], v[68:69], off
	v_pk_mul_f32 v[68:69], v[122:123], s[2:3] op_sel_hi:[1,0]
	global_store_dwordx2 v[6:7], v[68:69], off
	v_pk_mul_f32 v[68:69], v[88:89], s[2:3] op_sel_hi:[1,0]
	global_store_dwordx2 v[8:9], v[68:69], off
	v_pk_mul_f32 v[68:69], v[132:133], s[2:3] op_sel_hi:[1,0]
	global_store_dwordx2 v[10:11], v[68:69], off
	v_pk_mul_f32 v[68:69], v[130:131], s[2:3] op_sel_hi:[1,0]
	v_pk_add_f32 v[74:75], v[74:75], v[94:95] neg_lo:[0,1] neg_hi:[0,1]
	v_pk_add_f32 v[94:95], v[76:77], v[90:91]
	v_pk_add_f32 v[76:77], v[76:77], v[90:91] neg_lo:[0,1] neg_hi:[0,1]
	v_pk_add_f32 v[90:91], v[70:71], v[78:79]
	global_store_dwordx2 v[12:13], v[68:69], off
	v_pk_mul_f32 v[68:69], v[124:125], s[2:3] op_sel_hi:[1,0]
	global_store_dwordx2 v[14:15], v[68:69], off
	v_pk_mul_f32 v[68:69], v[90:91], s[2:3] op_sel_hi:[1,0]
	global_store_dwordx2 v[16:17], v[68:69], off
	v_pk_mul_f32 v[68:69], v[116:117], s[2:3] op_sel_hi:[1,0]
	global_store_dwordx2 v[18:19], v[68:69], off
	v_pk_mul_f32 v[68:69], v[118:119], s[2:3] op_sel_hi:[1,0]
	global_store_dwordx2 v[20:21], v[68:69], off
	v_pk_mul_f32 v[68:69], v[128:129], s[2:3] op_sel_hi:[1,0]
	global_store_dwordx2 v[22:23], v[68:69], off
	v_pk_mul_f32 v[68:69], v[94:95], s[2:3] op_sel_hi:[1,0]
	global_store_dwordx2 v[24:25], v[68:69], off
	v_pk_mul_f32 v[68:69], v[126:127], s[2:3] op_sel_hi:[1,0]
	global_store_dwordx2 v[26:27], v[68:69], off
	v_pk_mul_f32 v[68:69], v[92:93], s[2:3] op_sel_hi:[1,0]
	v_pk_add_f32 v[70:71], v[70:71], v[78:79] neg_lo:[0,1] neg_hi:[0,1]
	v_pk_add_f32 v[78:79], v[66:67], v[72:73]
	global_store_dwordx2 v[28:29], v[68:69], off
	v_pk_mul_f32 v[68:69], v[112:113], s[2:3] op_sel_hi:[1,0]
	global_store_dwordx2 v[30:31], v[68:69], off
	v_pk_mul_f32 v[68:69], v[78:79], s[2:3] op_sel_hi:[1,0]
	global_store_dwordx2 v[32:33], v[68:69], off
	v_pk_mul_f32 v[68:69], v[80:81], s[2:3] op_sel_hi:[1,0]
	global_store_dwordx2 v[34:35], v[68:69], off
	v_pk_mul_f32 v[68:69], v[82:83], s[2:3] op_sel_hi:[1,0]
	global_store_dwordx2 v[36:37], v[68:69], off
	v_pk_mul_f32 v[68:69], v[108:109], s[2:3] op_sel_hi:[1,0]
	global_store_dwordx2 v[38:39], v[68:69], off
	v_pk_mul_f32 v[68:69], v[74:75], s[2:3] op_sel_hi:[1,0]
	global_store_dwordx2 v[40:41], v[68:69], off
	v_pk_mul_f32 v[68:69], v[98:99], s[2:3] op_sel_hi:[1,0]
	global_store_dwordx2 v[42:43], v[68:69], off
	v_pk_mul_f32 v[68:69], v[84:85], s[2:3] op_sel_hi:[1,0]
	global_store_dwordx2 v[44:45], v[68:69], off
	v_pk_mul_f32 v[68:69], v[100:101], s[2:3] op_sel_hi:[1,0]
	global_store_dwordx2 v[46:47], v[68:69], off
	v_pk_mul_f32 v[68:69], v[70:71], s[2:3] op_sel_hi:[1,0]
	global_store_dwordx2 v[48:49], v[68:69], off
	v_pk_mul_f32 v[68:69], v[96:97], s[2:3] op_sel_hi:[1,0]
	global_store_dwordx2 v[50:51], v[68:69], off
	v_pk_mul_f32 v[68:69], v[114:115], s[2:3] op_sel_hi:[1,0]
	global_store_dwordx2 v[52:53], v[68:69], off
	v_pk_mul_f32 v[68:69], v[110:111], s[2:3] op_sel_hi:[1,0]
	global_store_dwordx2 v[54:55], v[68:69], off
	v_pk_mul_f32 v[68:69], v[76:77], s[2:3] op_sel_hi:[1,0]
	global_store_dwordx2 v[56:57], v[68:69], off
	v_pk_mul_f32 v[68:69], v[120:121], s[2:3] op_sel_hi:[1,0]
	v_pk_add_f32 v[66:67], v[66:67], v[72:73] neg_lo:[0,1] neg_hi:[0,1]
	global_store_dwordx2 v[58:59], v[68:69], off
	v_pk_mul_f32 v[68:69], v[86:87], s[2:3] op_sel_hi:[1,0]
	global_store_dwordx2 v[60:61], v[68:69], off
	v_pk_mul_f32 v[68:69], v[102:103], s[2:3] op_sel_hi:[1,0]
	v_pk_mul_f32 v[66:67], v[66:67], s[2:3] op_sel_hi:[1,0]
	global_store_dwordx2 v[62:63], v[68:69], off
	global_store_dwordx2 v[64:65], v[66:67], off
	s_barrier

.Lmy_fft_hj:
	v_mov_b32 v66, 0
	s_movk_i32 s5, 0x200
	v_add_u32_e32 v0, v66, v0
	v_cvt_f32_i32_e32 v68, v0
	v_ashrrev_i32_e32 v66, 5, v0
	v_lshlrev_b32_e32 v67, 3, v0
	v_lshlrev_b32_e32 v66, 3, v66
	v_add3_u32 v171, 0, v66, v67
	v_add_u32_e32 v216, 0x10800, v171
	v_mul_f32_e32 v0, 0x38800000, v68
	v_sin_f32_e32 v67, v0
	v_cos_f32_e32 v66, v0
	v_xor_b32_e32 v68, 0x80000000, v67
	v_mov_b32_e32 v69, v67
	v_pk_mul_f32 v[70:71], v[68:69], v[66:67] op_sel:[0,1] op_sel_hi:[1,0]
	v_pk_fma_f32 v[70:71], v[66:67], v[66:67], v[70:71] op_sel_hi:[1,0,1]
	v_pk_mul_f32 v[74:75], v[68:69], v[70:71] op_sel:[0,1] op_sel_hi:[1,0]
	v_pk_fma_f32 v[74:75], v[70:71], v[66:67], v[74:75] op_sel_hi:[1,0,1]
	v_pk_mul_f32 v[78:79], v[68:69], v[74:75] op_sel:[0,1] op_sel_hi:[1,0]
	v_pk_fma_f32 v[78:79], v[74:75], v[66:67], v[78:79] op_sel_hi:[1,0,1]
	v_pk_mul_f32 v[82:83], v[68:69], v[78:79] op_sel:[0,1] op_sel_hi:[1,0]
	v_pk_fma_f32 v[82:83], v[78:79], v[66:67], v[82:83] op_sel_hi:[1,0,1]
	v_pk_mul_f32 v[86:87], v[68:69], v[82:83] op_sel:[0,1] op_sel_hi:[1,0]
	s_waitcnt vmcnt(31)
	v_lshlrev_b32_e32 v126, 16, v105
	v_pk_fma_f32 v[86:87], v[82:83], v[66:67], v[86:87] op_sel_hi:[1,0,1]
	s_waitcnt vmcnt(30)
	v_lshlrev_b32_e32 v127, 16, v127
	v_pk_mul_f32 v[90:91], v[68:69], v[86:87] op_sel:[0,1] op_sel_hi:[1,0]
	s_waitcnt vmcnt(29)
	v_lshlrev_b32_e32 v129, 16, v128
	v_pk_fma_f32 v[90:91], v[86:87], v[66:67], v[90:91] op_sel_hi:[1,0,1]
	s_waitcnt vmcnt(24)
	v_lshlrev_b32_e32 v128, 16, v134
	v_pk_mul_f32 v[94:95], v[68:69], v[90:91] op_sel:[0,1] op_sel_hi:[1,0]
	v_lshlrev_b32_e32 v130, 16, v130
	v_pk_fma_f32 v[94:95], v[90:91], v[66:67], v[94:95] op_sel_hi:[1,0,1]
	v_lshlrev_b32_e32 v131, 16, v131
	v_pk_mul_f32 v[98:99], v[68:69], v[94:95] op_sel:[0,1] op_sel_hi:[1,0]
	v_lshlrev_b32_e32 v132, 16, v132
	v_pk_fma_f32 v[98:99], v[94:95], v[66:67], v[98:99] op_sel_hi:[1,0,1]
	v_lshlrev_b32_e32 v133, 16, v133
	v_pk_mul_f32 v[102:103], v[68:69], v[98:99] op_sel:[0,1] op_sel_hi:[1,0]
	s_waitcnt vmcnt(22)
	v_lshlrev_b32_e32 v135, 16, v135
	v_pk_fma_f32 v[102:103], v[98:99], v[66:67], v[102:103] op_sel_hi:[1,0,1]
	v_lshlrev_b32_e32 v134, 16, v136
	v_pk_mul_f32 v[108:109], v[68:69], v[102:103] op_sel:[0,1] op_sel_hi:[1,0]
	s_waitcnt vmcnt(21)
	v_lshlrev_b32_e32 v136, 16, v137
	v_pk_fma_f32 v[108:109], v[102:103], v[66:67], v[108:109] op_sel_hi:[1,0,1]
	s_waitcnt vmcnt(20)
	v_lshlrev_b32_e32 v137, 16, v138
	v_pk_mul_f32 v[112:113], v[68:69], v[108:109] op_sel:[0,1] op_sel_hi:[1,0]
	s_waitcnt vmcnt(19)
	v_lshlrev_b32_e32 v138, 16, v139
	s_waitcnt vmcnt(18)
	v_lshlrev_b32_e32 v139, 16, v140
	s_waitcnt vmcnt(17)
	v_lshlrev_b32_e32 v140, 16, v141
	s_waitcnt vmcnt(16)
	v_lshlrev_b32_e32 v141, 16, v142
	v_pk_fma_f32 v[112:113], v[108:109], v[66:67], v[112:113] op_sel_hi:[1,0,1]
	v_pk_add_f32 v[142:143], v[126:127], 0 op_sel_hi:[1,0]
	v_pk_add_f32 v[144:145], v[128:129], 0 op_sel_hi:[1,0]
	v_pk_mul_f32 v[146:147], v[128:129], s[36:37]
	v_pk_add_f32 v[148:149], v[130:131], 0 op_sel_hi:[1,0]
	v_pk_mul_f32 v[150:151], v[130:131], s[16:17]
	v_pk_add_f32 v[152:153], v[132:133], 0 op_sel_hi:[1,0]
	v_pk_mul_f32 v[154:155], v[132:133], s[38:39]
	v_pk_add_f32 v[156:157], v[134:135], 0 op_sel_hi:[1,0]
	v_xor_b32_e32 v159, 0x80000000, v134
	v_mov_b32_e32 v158, v135
	v_pk_add_f32 v[134:135], v[136:137], 0 op_sel_hi:[1,0]
	v_pk_mul_f32 v[160:161], v[136:137], s[38:39]
	v_pk_add_f32 v[162:163], v[138:139], 0 op_sel_hi:[1,0]
	v_pk_mul_f32 v[164:165], v[138:139], s[16:17]
	v_pk_add_f32 v[166:167], v[140:141], 0 op_sel_hi:[1,0]
	v_pk_mul_f32 v[168:169], v[140:141], s[36:37]
	v_pk_mul_f32 v[116:117], v[68:69], v[112:113] op_sel:[0,1] op_sel_hi:[1,0]
	v_pk_fma_f32 v[128:129], v[128:129], s[6:7], v[146:147] op_sel:[0,0,1] op_sel_hi:[1,0,0]
	v_pk_fma_f32 v[130:131], v[130:131], s[10:11], v[150:151] op_sel:[0,0,1] op_sel_hi:[1,0,0]
	v_pk_fma_f32 v[132:133], v[132:133], s[14:15], v[154:155] op_sel:[0,0,1] op_sel_hi:[1,0,0]
	v_pk_fma_f32 v[136:137], v[136:137], s[4:5], v[160:161] op_sel:[0,0,1] op_sel_hi:[1,0,0]
	v_pk_fma_f32 v[138:139], v[138:139], s[8:9], v[164:165] op_sel:[0,0,1] op_sel_hi:[1,0,0]
	v_pk_fma_f32 v[140:141], v[140:141], s[12:13], v[168:169] op_sel:[0,0,1] op_sel_hi:[1,0,0]
	v_pk_add_f32 v[146:147], v[142:143], v[156:157]
	v_pk_add_f32 v[150:151], v[144:145], v[134:135]
	v_pk_add_f32 v[134:135], v[144:145], v[134:135] neg_lo:[0,1] neg_hi:[0,1]
	v_pk_add_f32 v[144:145], v[148:149], v[162:163]
	v_pk_add_f32 v[160:161], v[148:149], v[162:163] op_sel:[1,1] op_sel_hi:[0,0] neg_lo:[0,1] neg_hi:[1,0]
	v_pk_add_f32 v[154:155], v[152:153], v[166:167]
	v_pk_add_f32 v[152:153], v[152:153], v[166:167] neg_lo:[0,1] neg_hi:[0,1]
	v_pk_fma_f32 v[116:117], v[112:113], v[66:67], v[116:117] op_sel_hi:[1,0,1]
	v_pk_add_f32 v[142:143], v[142:143], v[156:157] neg_lo:[0,1] neg_hi:[0,1]
	v_pk_add_f32 v[156:157], v[158:159], v[126:127]
	v_pk_add_f32 v[126:127], v[126:127], v[158:159] neg_lo:[0,1] neg_hi:[0,1]
	v_pk_mul_f32 v[158:159], v[134:135], s[16:17]
	v_pk_mul_f32 v[148:149], v[152:153], s[16:17]
	v_pk_add_f32 v[162:163], v[128:129], v[136:137]
	v_pk_add_f32 v[128:129], v[128:129], v[136:137] neg_lo:[0,1] neg_hi:[0,1]
	v_pk_add_f32 v[136:137], v[130:131], v[138:139]
	v_pk_add_f32 v[130:131], v[130:131], v[138:139] neg_lo:[0,1] neg_hi:[0,1]
	v_pk_add_f32 v[138:139], v[132:133], v[140:141]
	v_pk_add_f32 v[132:133], v[132:133], v[140:141] neg_lo:[0,1] neg_hi:[0,1]
	v_pk_add_f32 v[140:141], v[146:147], v[144:145]
	v_pk_add_f32 v[144:145], v[146:147], v[144:145] neg_lo:[0,1] neg_hi:[0,1]
	v_pk_add_f32 v[146:147], v[150:151], v[154:155]
	v_pk_add_f32 v[150:151], v[150:151], v[154:155] neg_lo:[0,1] neg_hi:[0,1]
	v_pk_mul_f32 v[120:121], v[68:69], v[116:117] op_sel:[0,1] op_sel_hi:[1,0]
	v_pk_fma_f32 v[134:135], v[134:135], s[10:11], v[158:159] op_sel:[0,0,1] op_sel_hi:[1,0,0]
	v_pk_fma_f32 v[148:149], v[152:153], s[8:9], v[148:149] op_sel:[0,0,1] op_sel_hi:[1,0,0]
	v_pk_mul_f32 v[152:153], v[128:129], s[16:17]
	v_xor_b32_e32 v155, 0x80000000, v130
	v_mov_b32_e32 v154, v131
	v_pk_mul_f32 v[130:131], v[132:133], s[16:17]
	v_xor_b32_e32 v159, 0x80000000, v150
	v_mov_b32_e32 v158, v151
	v_pk_add_f32 v[150:151], v[142:143], v[160:161]
	v_pk_add_f32 v[142:143], v[142:143], v[160:161] neg_lo:[0,1] neg_hi:[0,1]
	v_pk_add_f32 v[160:161], v[156:157], v[136:137]
	v_pk_add_f32 v[136:137], v[156:157], v[136:137] neg_lo:[0,1] neg_hi:[0,1]
	v_pk_add_f32 v[156:157], v[162:163], v[138:139]
	v_pk_add_f32 v[138:139], v[162:163], v[138:139] neg_lo:[0,1] neg_hi:[0,1]
	v_mov_b32_e32 v0, v67
	v_pk_fma_f32 v[120:121], v[116:117], v[66:67], v[120:121] op_sel_hi:[1,0,1]
	v_pk_add_f32 v[162:163], v[140:141], v[146:147]
	v_pk_add_f32 v[140:141], v[140:141], v[146:147] neg_lo:[0,1] neg_hi:[0,1]
	v_pk_fma_f32 v[128:129], v[128:129], s[10:11], v[152:153] op_sel:[0,0,1] op_sel_hi:[1,0,0]
	v_pk_fma_f32 v[130:131], v[132:133], s[8:9], v[130:131] op_sel:[0,0,1] op_sel_hi:[1,0,0]
	v_pk_add_f32 v[132:133], v[134:135], v[148:149]
	v_pk_add_f32 v[134:135], v[134:135], v[148:149] neg_lo:[0,1] neg_hi:[0,1]
	v_xor_b32_e32 v147, 0x80000000, v138
	v_mov_b32_e32 v146, v139
	v_pk_add_f32 v[152:153], v[160:161], v[156:157]
	v_pk_mul_f32 v[68:69], v[68:69], v[120:121] op_sel:[0,1] op_sel_hi:[1,0]
	v_pk_add_f32 v[138:139], v[126:127], v[154:155]
	v_pk_add_f32 v[126:127], v[126:127], v[154:155] neg_lo:[0,1] neg_hi:[0,1]
	v_pk_add_f32 v[148:149], v[144:145], v[158:159]
	v_pk_add_f32 v[144:145], v[144:145], v[158:159] neg_lo:[0,1] neg_hi:[0,1]
	v_pk_add_f32 v[154:155], v[160:161], v[156:157] neg_lo:[0,1] neg_hi:[0,1]
	v_pk_mul_f32 v[96:97], v[140:141], v[94:95] op_sel:[1,1] op_sel_hi:[0,1] neg_hi:[0,1]
	v_xor_b32_e32 v157, 0x80000000, v134
	v_mov_b32_e32 v156, v135
	v_pk_add_f32 v[134:135], v[128:129], v[130:131]
	v_pk_add_f32 v[128:129], v[128:129], v[130:131] neg_lo:[0,1] neg_hi:[0,1]
	v_pk_add_f32 v[130:131], v[150:151], v[132:133]
	v_pk_add_f32 v[132:133], v[150:151], v[132:133] neg_lo:[0,1] neg_hi:[0,1]
	v_pk_add_f32 v[150:151], v[136:137], v[146:147]
	v_pk_add_f32 v[136:137], v[136:137], v[146:147] neg_lo:[0,1] neg_hi:[0,1]
	v_pk_mul_f32 v[146:147], v[0:1], v[152:153] op_sel:[0,1] op_sel_hi:[0,0] neg_hi:[1,0]
	v_pk_add_f32 v[92:93], v[90:91], 0 neg_lo:[1,1] neg_hi:[1,1]
	v_pk_fma_f32 v[68:69], v[120:121], v[66:67], v[68:69] op_sel_hi:[1,0,1]
	v_pk_mul_f32 v[80:81], v[148:149], v[78:79] op_sel:[1,1] op_sel_hi:[0,1] neg_hi:[0,1]
	v_pk_fma_f32 v[94:95], v[140:141], v[94:95], v[96:97] op_sel_hi:[1,0,1]
	v_pk_mul_f32 v[96:97], v[154:155], v[98:99] op_sel:[1,1] op_sel_hi:[0,1] neg_hi:[0,1]
	v_pk_mul_f32 v[100:101], v[144:145], v[112:113] op_sel:[1,1] op_sel_hi:[0,1] neg_hi:[0,1]
	v_xor_b32_e32 v115, 0x80000000, v128
	v_mov_b32_e32 v114, v129
	v_pk_add_f32 v[128:129], v[142:143], v[156:157]
	v_pk_add_f32 v[140:141], v[142:143], v[156:157] neg_lo:[0,1] neg_hi:[0,1]
	v_pk_add_f32 v[142:143], v[138:139], v[134:135]
	v_pk_fma_f32 v[66:67], v[152:153], v[66:67], v[146:147] op_sel_hi:[1,0,1]
	v_pk_mul_f32 v[72:73], v[130:131], v[70:71] op_sel:[1,1] op_sel_hi:[0,1] neg_hi:[0,1]
	v_mov_b32_e32 v92, v91
	v_pk_add_f32 v[110:111], v[108:109], 0 neg_lo:[1,1] neg_hi:[1,1]
	v_pk_add_f32 v[118:119], v[116:117], 0 neg_lo:[1,1] neg_hi:[1,1]
	v_pk_add_f32 v[122:123], v[120:121], 0 neg_lo:[1,1] neg_hi:[1,1]
	v_pk_add_f32 v[124:125], v[68:69], 0 neg_lo:[1,1] neg_hi:[1,1]
	ds_write_b64 v171, v[162:163]
	v_pk_fma_f32 v[78:79], v[148:149], v[78:79], v[80:81] op_sel_hi:[1,0,1]
	v_pk_mul_f32 v[80:81], v[150:151], v[82:83] op_sel:[1,1] op_sel_hi:[0,1] neg_hi:[0,1]
	v_pk_fma_f32 v[84:85], v[154:155], v[98:99], v[96:97] op_sel_hi:[1,0,1]
	v_pk_mul_f32 v[96:97], v[132:133], v[102:103] op_sel:[1,1] op_sel_hi:[0,1] neg_hi:[0,1]
	v_pk_add_f32 v[106:107], v[126:127], v[114:115]
	ds_write_b64 v171, v[66:67] offset:8448
	v_pk_fma_f32 v[66:67], v[130:131], v[70:71], v[72:73] op_sel_hi:[1,0,1]
	v_pk_mul_f32 v[70:71], v[142:143], v[74:75] op_sel:[1,1] op_sel_hi:[0,1] neg_hi:[0,1]
	v_mov_b32_e32 v110, v109
	v_mov_b32_e32 v118, v117
	v_mov_b32_e32 v122, v121
	v_mov_b32_e32 v124, v69
	v_pk_add_f32 v[134:135], v[138:139], v[134:135] neg_lo:[0,1] neg_hi:[0,1]
	v_pk_fma_f32 v[98:99], v[144:145], v[112:113], v[100:101] op_sel_hi:[1,0,1]
	v_pk_add_f32 v[112:113], v[126:127], v[114:115] neg_lo:[0,1] neg_hi:[0,1]
	v_pk_mul_f32 v[76:77], v[128:129], v[86:87] op_sel:[1,1] op_sel_hi:[0,1] neg_hi:[0,1]
	ds_write_b64 v171, v[66:67] offset:16896
	v_pk_fma_f32 v[66:67], v[142:143], v[74:75], v[70:71] op_sel_hi:[1,0,1]
	v_pk_mul_f32 v[74:75], v[106:107], v[92:93] op_sel:[1,0] op_sel_hi:[0,1]
	s_mov_b64 s[48:49], 0
	s_and_b64 vcc, exec, vcc
	v_pk_mul_f32 v[100:101], v[136:137], v[118:119] op_sel:[1,0] op_sel_hi:[0,1]
	v_pk_fma_f32 v[72:73], v[150:151], v[82:83], v[80:81] op_sel_hi:[1,0,1]
	v_pk_fma_f32 v[80:81], v[132:133], v[102:103], v[96:97] op_sel_hi:[1,0,1]
	v_pk_mul_f32 v[82:83], v[134:135], v[110:111] op_sel:[1,0] op_sel_hi:[0,1]
	v_pk_mul_f32 v[96:97], v[140:141], v[122:123] op_sel:[1,0] op_sel_hi:[0,1]
	v_pk_fma_f32 v[70:71], v[128:129], v[86:87], v[76:77] op_sel_hi:[1,0,1]
	v_pk_mul_f32 v[86:87], v[112:113], v[124:125] op_sel:[1,0] op_sel_hi:[0,1]
	ds_write_b64 v171, v[66:67] offset:25344
	ds_write_b64 v171, v[78:79] offset:33792
	ds_write_b64 v171, v[72:73] offset:42240
	ds_write_b64 v171, v[70:71] offset:50688
	v_pk_fma_f32 v[66:67], v[106:107], v[90:91], v[74:75] op_sel_hi:[1,0,1]
	v_pk_fma_f32 v[88:89], v[136:137], v[116:117], v[100:101] op_sel_hi:[1,0,1]
	v_pk_fma_f32 v[76:77], v[134:135], v[108:109], v[82:83] op_sel_hi:[1,0,1]
	v_pk_fma_f32 v[82:83], v[140:141], v[120:121], v[96:97] op_sel_hi:[1,0,1]
	v_pk_fma_f32 v[68:69], v[112:113], v[68:69], v[86:87] op_sel_hi:[1,0,1]
	ds_write_b64 v171, v[66:67] offset:59136
	ds_write_b64 v216, v[94:95]
	ds_write_b64 v216, v[84:85] offset:8448
	ds_write_b64 v216, v[80:81] offset:16896
	ds_write_b64 v216, v[76:77] offset:25344
	ds_write_b64 v216, v[98:99] offset:33792
	ds_write_b64 v216, v[88:89] offset:42240
	ds_write_b64 v216, v[82:83] offset:50688
	ds_write_b64 v216, v[68:69] offset:59136
	s_cbranch_vccz .LBB0_362
	s_waitcnt lgkmcnt(0)
	s_barrier
	v_mov_b32 v0, 0
	s_mov_b32 s5, s14
	v_add_u32_e32 v74, v0, v170
	v_lshlrev_b32_e32 v0, 5, v74
	v_and_b32_e32 v71, 0xfffffc00, v0
	v_and_b32_e32 v70, 31, v74
	v_lshlrev_b32_e32 v78, 3, v71
	v_lshlrev_b32_e32 v79, 3, v70
	v_or_b32_e32 v67, 32, v71
	v_ashrrev_i32_e32 v67, 2, v67
	v_add_u32_e32 v67, 0, v67
	v_add3_u32 v114, v67, v78, v79
	v_ashrrev_i32_e32 v66, 2, v71
	v_add_u32_e32 v66, 0, v66
	v_add3_u32 v66, v66, v78, v79
	v_mov_b32_e32 v222, v114
	ds_read_b64 v[66:67], v66
	ds_read_b64 v[68:69], v222 offset:256
	ds_read_b64 v[72:73], v222 offset:520
	ds_read_b64 v[76:77], v222 offset:784
	ds_read_b64 v[80:81], v222 offset:1048
	ds_read_b64 v[82:83], v222 offset:1312
	ds_read_b64 v[116:117], v222 offset:1576
	ds_read_b64 v[118:119], v222 offset:1840
	ds_read_b64 v[120:121], v222 offset:2104
	ds_read_b64 v[122:123], v222 offset:2368
	ds_read_b64 v[124:125], v222 offset:2632
	ds_read_b64 v[126:127], v222 offset:2896
	ds_read_b64 v[128:129], v222 offset:3160
	ds_read_b64 v[130:131], v222 offset:3424
	ds_read_b64 v[132:133], v222 offset:3688
	ds_read_b64 v[134:135], v222 offset:3952
	ds_read_b64 v[136:137], v222 offset:4216
	ds_read_b64 v[138:139], v222 offset:4480
	ds_read_b64 v[140:141], v222 offset:4744
	ds_read_b64 v[142:143], v222 offset:5008
	s_waitcnt lgkmcnt(3)
	v_pk_add_f32 v[168:169], v[66:67], v[136:137]
	v_pk_add_f32 v[66:67], v[66:67], v[136:137] neg_lo:[0,1] neg_hi:[0,1]
	s_waitcnt lgkmcnt(2)
	v_pk_add_f32 v[136:137], v[68:69], v[138:139]
	v_pk_add_f32 v[68:69], v[68:69], v[138:139] neg_lo:[0,1] neg_hi:[0,1]
	v_pk_mul_f32 v[138:139], v[68:69], s[18:19]
	v_pk_fma_f32 v[68:69], v[68:69], s[20:21], v[138:139] op_sel:[0,0,1] op_sel_hi:[1,0,0]
	s_waitcnt lgkmcnt(1)
	v_pk_add_f32 v[138:139], v[72:73], v[140:141]
	v_pk_add_f32 v[72:73], v[72:73], v[140:141] neg_lo:[0,1] neg_hi:[0,1]
	v_pk_mul_f32 v[140:141], v[72:73], s[4:5]
	ds_read_b64 v[144:145], v222 offset:5272
	ds_read_b64 v[146:147], v222 offset:5536
	ds_read_b64 v[148:149], v222 offset:5800
	ds_read_b64 v[150:151], v222 offset:6064
	v_pk_fma_f32 v[72:73], v[72:73], s[6:7], v[140:141] op_sel:[0,0,1] op_sel_hi:[1,0,0]
	s_waitcnt lgkmcnt(4)
	v_pk_add_f32 v[140:141], v[76:77], v[142:143]
	v_pk_add_f32 v[76:77], v[76:77], v[142:143] neg_lo:[0,1] neg_hi:[0,1]
	v_pk_mul_f32 v[142:143], v[76:77], s[22:23]
	v_pk_fma_f32 v[76:77], v[76:77], s[24:25], v[142:143] op_sel:[0,0,1] op_sel_hi:[1,0,0]
	s_waitcnt lgkmcnt(3)
	v_pk_add_f32 v[142:143], v[80:81], v[144:145]
	v_pk_add_f32 v[80:81], v[80:81], v[144:145] neg_lo:[0,1] neg_hi:[0,1]
	s_mov_b32 s9, s10
	v_pk_mul_f32 v[144:145], v[80:81], s[8:9]
	v_pk_fma_f32 v[80:81], v[80:81], s[10:11], v[144:145] op_sel:[0,0,1] op_sel_hi:[1,0,0]
	s_waitcnt lgkmcnt(2)
	v_pk_add_f32 v[144:145], v[82:83], v[146:147]
	v_pk_add_f32 v[82:83], v[82:83], v[146:147] neg_lo:[0,1] neg_hi:[0,1]
	s_mov_b32 s27, s24
	v_pk_mul_f32 v[146:147], v[82:83], s[26:27]
	s_mov_b32 s0, s23
	v_pk_fma_f32 v[82:83], v[82:83], s[0:1], v[146:147] op_sel:[0,0,1] op_sel_hi:[1,0,0]
	s_waitcnt lgkmcnt(1)
	v_pk_add_f32 v[146:147], v[116:117], v[148:149]
	v_pk_add_f32 v[116:117], v[116:117], v[148:149] neg_lo:[0,1] neg_hi:[0,1]
	s_mov_b32 s13, s6
	v_pk_mul_f32 v[148:149], v[116:117], s[12:13]
	ds_read_b64 v[152:153], v222 offset:6328
	ds_read_b64 v[154:155], v222 offset:6592
	ds_read_b64 v[156:157], v222 offset:6856
	ds_read_b64 v[158:159], v222 offset:7120
	v_pk_fma_f32 v[116:117], v[116:117], s[14:15], v[148:149] op_sel:[0,0,1] op_sel_hi:[1,0,0]
	s_waitcnt lgkmcnt(4)
	v_pk_add_f32 v[148:149], v[118:119], v[150:151]
	v_pk_add_f32 v[118:119], v[118:119], v[150:151] neg_lo:[0,1] neg_hi:[0,1]
	s_mov_b32 s35, s20
	v_pk_mul_f32 v[150:151], v[118:119], s[34:35]
	s_mov_b32 s48, s19
	v_pk_fma_f32 v[118:119], v[118:119], s[48:49], v[150:151] op_sel:[0,0,1] op_sel_hi:[1,0,0]
	s_waitcnt lgkmcnt(3)
	v_pk_add_f32 v[150:151], v[120:121], v[152:153]
	v_pk_add_f32 v[152:153], v[120:121], v[152:153] op_sel:[1,1] op_sel_hi:[0,0] neg_lo:[0,1] neg_hi:[1,0]
	s_waitcnt lgkmcnt(2)
	v_pk_add_f32 v[120:121], v[122:123], v[154:155]
	v_pk_add_f32 v[122:123], v[122:123], v[154:155] neg_lo:[0,1] neg_hi:[0,1]
	v_pk_mul_f32 v[154:155], v[122:123], s[34:35]
	v_pk_fma_f32 v[122:123], v[122:123], s[18:19], v[154:155] op_sel:[0,0,1] op_sel_hi:[1,0,0]
	s_waitcnt lgkmcnt(1)
	v_pk_add_f32 v[154:155], v[124:125], v[156:157]
	v_pk_add_f32 v[124:125], v[124:125], v[156:157] neg_lo:[0,1] neg_hi:[0,1]
	v_pk_mul_f32 v[156:157], v[124:125], s[12:13]
	ds_read_b64 v[160:161], v222 offset:7384
	ds_read_b64 v[162:163], v222 offset:7648
	ds_read_b64 v[164:165], v222 offset:7912
	ds_read_b64 v[166:167], v222 offset:8176
	v_pk_fma_f32 v[124:125], v[124:125], s[4:5], v[156:157] op_sel:[0,0,1] op_sel_hi:[1,0,0]
	s_waitcnt lgkmcnt(4)
	v_pk_add_f32 v[156:157], v[126:127], v[158:159]
	v_pk_add_f32 v[126:127], v[126:127], v[158:159] neg_lo:[0,1] neg_hi:[0,1]
	v_lshlrev_b32_e32 v70, 4, v70
	v_pk_mul_f32 v[158:159], v[126:127], s[26:27]
	v_cvt_f32_u32_e32 v75, v70
	v_pk_fma_f32 v[126:127], v[126:127], s[22:23], v[158:159] op_sel:[0,0,1] op_sel_hi:[1,0,0]
	s_waitcnt lgkmcnt(3)
	v_pk_add_f32 v[158:159], v[128:129], v[160:161]
	v_pk_add_f32 v[128:129], v[128:129], v[160:161] neg_lo:[0,1] neg_hi:[0,1]
	v_and_b32_e32 v74, 0x1fffffe0, v74
	v_pk_mul_f32 v[160:161], v[128:129], s[8:9]
	v_mul_f32_e32 v115, 0x38800000, v75
	v_pk_fma_f32 v[128:129], v[128:129], s[8:9], v[160:161] op_sel:[0,0,1] op_sel_hi:[1,0,0]
	s_waitcnt lgkmcnt(2)
	v_pk_add_f32 v[160:161], v[130:131], v[162:163]
	v_pk_add_f32 v[130:131], v[130:131], v[162:163] neg_lo:[0,1] neg_hi:[0,1]
	v_lshl_add_u32 v74, v74, 3, 0
	v_pk_mul_f32 v[162:163], v[130:131], s[22:23]
	v_sin_f32_e32 v75, v115
	v_pk_fma_f32 v[130:131], v[130:131], s[26:27], v[162:163] op_sel:[0,0,1] op_sel_hi:[1,0,0]
	s_waitcnt lgkmcnt(1)
	v_pk_add_f32 v[162:163], v[132:133], v[164:165]
	v_pk_add_f32 v[132:133], v[132:133], v[164:165] neg_lo:[0,1] neg_hi:[0,1]
	v_add3_u32 v74, v74, v78, v79
	v_pk_mul_f32 v[164:165], v[132:133], s[4:5]
	v_xor_b32_e32 v78, 0x80000000, v75
	v_pk_fma_f32 v[132:133], v[132:133], s[12:13], v[164:165] op_sel:[0,0,1] op_sel_hi:[1,0,0]
	s_waitcnt lgkmcnt(0)
	v_pk_add_f32 v[164:165], v[134:135], v[166:167]
	v_pk_add_f32 v[134:135], v[134:135], v[166:167] neg_lo:[0,1] neg_hi:[0,1]
	v_mov_b32_e32 v79, v75
	v_pk_mul_f32 v[166:167], v[134:135], s[18:19]
	s_mov_b32 s50, s19
	v_pk_fma_f32 v[134:135], v[134:135], s[34:35], v[166:167] op_sel:[0,0,1] op_sel_hi:[1,0,0]
	v_pk_add_f32 v[166:167], v[168:169], v[150:151]
	v_pk_add_f32 v[150:151], v[168:169], v[150:151] neg_lo:[0,1] neg_hi:[0,1]
	v_pk_add_f32 v[168:169], v[136:137], v[120:121]
	v_pk_add_f32 v[120:121], v[136:137], v[120:121] neg_lo:[0,1] neg_hi:[0,1]
	s_mov_b32 s51, s18
	v_pk_mul_f32 v[136:137], v[120:121], s[4:5]
	s_mov_b32 s52, s23
	v_pk_fma_f32 v[120:121], v[120:121], s[6:7], v[136:137] op_sel:[0,0,1] op_sel_hi:[1,0,0]
	v_pk_add_f32 v[136:137], v[138:139], v[154:155]
	v_pk_add_f32 v[138:139], v[138:139], v[154:155] neg_lo:[0,1] neg_hi:[0,1]
	s_mov_b32 s53, s22
	v_pk_mul_f32 v[154:155], v[138:139], s[8:9]
	v_pk_fma_f32 v[138:139], v[138:139], s[10:11], v[154:155] op_sel:[0,0,1] op_sel_hi:[1,0,0]
	v_pk_add_f32 v[154:155], v[140:141], v[156:157]
	v_pk_add_f32 v[140:141], v[140:141], v[156:157] neg_lo:[0,1] neg_hi:[0,1]
	v_pk_mul_f32 v[156:157], v[140:141], s[12:13]
	v_pk_fma_f32 v[140:141], v[140:141], s[14:15], v[156:157] op_sel:[0,0,1] op_sel_hi:[1,0,0]
	v_pk_add_f32 v[156:157], v[142:143], v[158:159]
	v_pk_add_f32 v[158:159], v[142:143], v[158:159] op_sel:[1,1] op_sel_hi:[0,0] neg_lo:[0,1] neg_hi:[1,0]
	v_pk_add_f32 v[142:143], v[144:145], v[160:161]
	v_pk_add_f32 v[144:145], v[144:145], v[160:161] neg_lo:[0,1] neg_hi:[0,1]
	v_pk_mul_f32 v[160:161], v[144:145], s[12:13]
	v_pk_fma_f32 v[144:145], v[144:145], s[4:5], v[160:161] op_sel:[0,0,1] op_sel_hi:[1,0,0]
	v_pk_add_f32 v[160:161], v[146:147], v[162:163]
	v_pk_add_f32 v[146:147], v[146:147], v[162:163] neg_lo:[0,1] neg_hi:[0,1]
	v_pk_mul_f32 v[162:163], v[146:147], s[8:9]
	v_pk_fma_f32 v[146:147], v[146:147], s[8:9], v[162:163] op_sel:[0,0,1] op_sel_hi:[1,0,0]
	v_pk_add_f32 v[162:163], v[148:149], v[164:165]
	v_pk_add_f32 v[148:149], v[148:149], v[164:165] neg_lo:[0,1] neg_hi:[0,1]
	v_pk_mul_f32 v[164:165], v[148:149], s[4:5]
	v_pk_fma_f32 v[148:149], v[148:149], s[12:13], v[164:165] op_sel:[0,0,1] op_sel_hi:[1,0,0]
	v_pk_add_f32 v[164:165], v[66:67], v[152:153]
	v_pk_add_f32 v[66:67], v[66:67], v[152:153] neg_lo:[0,1] neg_hi:[0,1]
	v_pk_add_f32 v[152:153], v[68:69], v[122:123]
	v_pk_add_f32 v[68:69], v[68:69], v[122:123] neg_lo:[0,1] neg_hi:[0,1]
	v_pk_mul_f32 v[122:123], v[68:69], s[4:5]
	v_pk_fma_f32 v[68:69], v[68:69], s[6:7], v[122:123] op_sel:[0,0,1] op_sel_hi:[1,0,0]
	v_pk_add_f32 v[122:123], v[72:73], v[124:125]
	v_pk_add_f32 v[72:73], v[72:73], v[124:125] neg_lo:[0,1] neg_hi:[0,1]
	v_pk_mul_f32 v[124:125], v[72:73], s[8:9]
	v_pk_fma_f32 v[72:73], v[72:73], s[10:11], v[124:125] op_sel:[0,0,1] op_sel_hi:[1,0,0]
	v_pk_add_f32 v[124:125], v[76:77], v[126:127]
	v_pk_add_f32 v[76:77], v[76:77], v[126:127] neg_lo:[0,1] neg_hi:[0,1]
	v_pk_mul_f32 v[126:127], v[76:77], s[12:13]
	v_pk_fma_f32 v[76:77], v[76:77], s[14:15], v[126:127] op_sel:[0,0,1] op_sel_hi:[1,0,0]
	v_pk_add_f32 v[126:127], v[80:81], v[128:129]
	v_pk_add_f32 v[128:129], v[80:81], v[128:129] op_sel:[1,1] op_sel_hi:[0,0] neg_lo:[0,1] neg_hi:[1,0]
	v_pk_add_f32 v[80:81], v[82:83], v[130:131]
	v_pk_add_f32 v[82:83], v[82:83], v[130:131] neg_lo:[0,1] neg_hi:[0,1]
	v_pk_mul_f32 v[130:131], v[82:83], s[12:13]
	v_pk_fma_f32 v[82:83], v[82:83], s[4:5], v[130:131] op_sel:[0,0,1] op_sel_hi:[1,0,0]
	v_pk_add_f32 v[130:131], v[116:117], v[132:133]
	v_pk_add_f32 v[116:117], v[116:117], v[132:133] neg_lo:[0,1] neg_hi:[0,1]
	v_pk_mul_f32 v[132:133], v[116:117], s[8:9]
	v_pk_fma_f32 v[116:117], v[116:117], s[8:9], v[132:133] op_sel:[0,0,1] op_sel_hi:[1,0,0]
	v_pk_add_f32 v[132:133], v[118:119], v[134:135]
	v_pk_add_f32 v[118:119], v[118:119], v[134:135] neg_lo:[0,1] neg_hi:[0,1]
	v_pk_mul_f32 v[134:135], v[118:119], s[4:5]
	v_pk_fma_f32 v[118:119], v[118:119], s[12:13], v[134:135] op_sel:[0,0,1] op_sel_hi:[1,0,0]
	v_pk_add_f32 v[134:135], v[166:167], v[156:157]
	v_pk_add_f32 v[156:157], v[166:167], v[156:157] neg_lo:[0,1] neg_hi:[0,1]
	v_pk_add_f32 v[166:167], v[168:169], v[142:143]
	v_pk_add_f32 v[142:143], v[168:169], v[142:143] neg_lo:[0,1] neg_hi:[0,1]
	v_pk_mul_f32 v[168:169], v[142:143], s[8:9]
	v_pk_fma_f32 v[142:143], v[142:143], s[10:11], v[168:169] op_sel:[0,0,1] op_sel_hi:[1,0,0]
	v_pk_add_f32 v[168:169], v[136:137], v[160:161]
	v_pk_add_f32 v[160:161], v[136:137], v[160:161] op_sel:[1,1] op_sel_hi:[0,0] neg_lo:[0,1] neg_hi:[1,0]
	v_pk_add_f32 v[136:137], v[154:155], v[162:163]
	v_pk_add_f32 v[154:155], v[154:155], v[162:163] neg_lo:[0,1] neg_hi:[0,1]
	v_pk_mul_f32 v[162:163], v[154:155], s[8:9]
	v_pk_fma_f32 v[154:155], v[154:155], s[8:9], v[162:163] op_sel:[0,0,1] op_sel_hi:[1,0,0]
	v_pk_add_f32 v[162:163], v[150:151], v[158:159]
	v_pk_add_f32 v[150:151], v[150:151], v[158:159] neg_lo:[0,1] neg_hi:[0,1]
	v_pk_add_f32 v[158:159], v[120:121], v[144:145]
	v_pk_add_f32 v[120:121], v[120:121], v[144:145] neg_lo:[0,1] neg_hi:[0,1]
	v_pk_mul_f32 v[144:145], v[120:121], s[8:9]
	v_pk_fma_f32 v[120:121], v[120:121], s[10:11], v[144:145] op_sel:[0,0,1] op_sel_hi:[1,0,0]
	v_pk_add_f32 v[144:145], v[138:139], v[146:147]
	v_pk_add_f32 v[146:147], v[138:139], v[146:147] op_sel:[1,1] op_sel_hi:[0,0] neg_lo:[0,1] neg_hi:[1,0]
	v_pk_add_f32 v[138:139], v[140:141], v[148:149]
	v_pk_add_f32 v[140:141], v[140:141], v[148:149] neg_lo:[0,1] neg_hi:[0,1]
	v_pk_mul_f32 v[148:149], v[140:141], s[8:9]
	v_pk_fma_f32 v[140:141], v[140:141], s[8:9], v[148:149] op_sel:[0,0,1] op_sel_hi:[1,0,0]
	v_pk_add_f32 v[148:149], v[164:165], v[126:127]
	v_pk_add_f32 v[126:127], v[164:165], v[126:127] neg_lo:[0,1] neg_hi:[0,1]
	v_pk_add_f32 v[164:165], v[152:153], v[80:81]
	v_pk_add_f32 v[80:81], v[152:153], v[80:81] neg_lo:[0,1] neg_hi:[0,1]
	v_pk_mul_f32 v[152:153], v[80:81], s[8:9]
	v_pk_fma_f32 v[80:81], v[80:81], s[10:11], v[152:153] op_sel:[0,0,1] op_sel_hi:[1,0,0]
	v_pk_add_f32 v[152:153], v[122:123], v[130:131]
	v_pk_add_f32 v[130:131], v[122:123], v[130:131] op_sel:[1,1] op_sel_hi:[0,0] neg_lo:[0,1] neg_hi:[1,0]
	v_pk_add_f32 v[122:123], v[124:125], v[132:133]
	v_pk_add_f32 v[124:125], v[124:125], v[132:133] neg_lo:[0,1] neg_hi:[0,1]
	v_pk_mul_f32 v[132:133], v[124:125], s[8:9]
	v_pk_fma_f32 v[124:125], v[124:125], s[8:9], v[132:133] op_sel:[0,0,1] op_sel_hi:[1,0,0]
	v_pk_add_f32 v[132:133], v[66:67], v[128:129]
	v_pk_add_f32 v[66:67], v[66:67], v[128:129] neg_lo:[0,1] neg_hi:[0,1]
	v_pk_add_f32 v[128:129], v[68:69], v[82:83]
	v_pk_add_f32 v[68:69], v[68:69], v[82:83] neg_lo:[0,1] neg_hi:[0,1]
	v_pk_mul_f32 v[82:83], v[68:69], s[8:9]
	v_pk_fma_f32 v[68:69], v[68:69], s[10:11], v[82:83] op_sel:[0,0,1] op_sel_hi:[1,0,0]
	v_pk_add_f32 v[82:83], v[72:73], v[116:117]
	v_pk_add_f32 v[116:117], v[72:73], v[116:117] op_sel:[1,1] op_sel_hi:[0,0] neg_lo:[0,1] neg_hi:[1,0]
	v_pk_add_f32 v[72:73], v[76:77], v[118:119]
	v_pk_add_f32 v[76:77], v[76:77], v[118:119] neg_lo:[0,1] neg_hi:[0,1]
	v_pk_add_f32 v[174:175], v[66:67], v[116:117]
	v_pk_mul_f32 v[118:119], v[76:77], s[8:9]
	v_pk_add_f32 v[116:117], v[66:67], v[116:117] neg_lo:[0,1] neg_hi:[0,1]
	v_pk_fma_f32 v[76:77], v[76:77], s[8:9], v[118:119] op_sel:[0,0,1] op_sel_hi:[1,0,0]
	v_pk_add_f32 v[118:119], v[134:135], v[168:169]
	v_pk_add_f32 v[134:135], v[134:135], v[168:169] neg_lo:[0,1] neg_hi:[0,1]
	v_pk_add_f32 v[168:169], v[166:167], v[136:137]
	v_pk_add_f32 v[166:167], v[166:167], v[136:137] op_sel:[1,1] op_sel_hi:[0,0] neg_lo:[0,1] neg_hi:[1,0]
	v_pk_add_f32 v[180:181], v[118:119], v[168:169]
	v_pk_add_f32 v[136:137], v[156:157], v[160:161]
	v_pk_add_f32 v[156:157], v[156:157], v[160:161] neg_lo:[0,1] neg_hi:[0,1]
	v_pk_add_f32 v[160:161], v[142:143], v[154:155]
	v_pk_add_f32 v[154:155], v[142:143], v[154:155] op_sel:[1,1] op_sel_hi:[0,0] neg_lo:[0,1] neg_hi:[1,0]
	v_pk_add_f32 v[178:179], v[68:69], v[76:77] op_sel:[1,1] op_sel_hi:[0,0] neg_lo:[0,1] neg_hi:[1,0]
	v_pk_add_f32 v[142:143], v[162:163], v[144:145]
	v_pk_add_f32 v[144:145], v[162:163], v[144:145] neg_lo:[0,1] neg_hi:[0,1]
	v_pk_add_f32 v[162:163], v[158:159], v[138:139]
	v_pk_add_f32 v[158:159], v[158:159], v[138:139] op_sel:[1,1] op_sel_hi:[0,0] neg_lo:[0,1] neg_hi:[1,0]
	ds_write_b64 v74, v[180:181]
	v_pk_add_f32 v[138:139], v[150:151], v[146:147]
	v_pk_add_f32 v[146:147], v[150:151], v[146:147] neg_lo:[0,1] neg_hi:[0,1]
	v_pk_add_f32 v[150:151], v[120:121], v[140:141]
	v_pk_add_f32 v[140:141], v[120:121], v[140:141] op_sel:[1,1] op_sel_hi:[0,0] neg_lo:[0,1] neg_hi:[1,0]
	v_cos_f32_e32 v74, v115
	v_pk_add_f32 v[120:121], v[148:149], v[152:153]
	v_pk_add_f32 v[148:149], v[148:149], v[152:153] neg_lo:[0,1] neg_hi:[0,1]
	v_pk_add_f32 v[152:153], v[164:165], v[122:123]
	v_pk_add_f32 v[164:165], v[164:165], v[122:123] op_sel:[1,1] op_sel_hi:[0,0] neg_lo:[0,1] neg_hi:[1,0]
	v_pk_add_f32 v[122:123], v[126:127], v[130:131]
	v_pk_add_f32 v[126:127], v[126:127], v[130:131] neg_lo:[0,1] neg_hi:[0,1]
	v_pk_add_f32 v[130:131], v[80:81], v[124:125]
	v_pk_add_f32 v[124:125], v[80:81], v[124:125] op_sel:[1,1] op_sel_hi:[0,0] neg_lo:[0,1] neg_hi:[1,0]
	v_pk_add_f32 v[80:81], v[132:133], v[82:83]
	v_pk_add_f32 v[132:133], v[132:133], v[82:83] neg_lo:[0,1] neg_hi:[0,1]
	v_pk_add_f32 v[176:177], v[68:69], v[76:77]
	v_pk_add_f32 v[118:119], v[118:119], v[168:169] neg_lo:[0,1] neg_hi:[0,1]
	v_pk_add_f32 v[168:169], v[134:135], v[166:167]
	v_pk_add_f32 v[82:83], v[134:135], v[166:167] neg_lo:[0,1] neg_hi:[0,1]
	v_pk_add_f32 v[134:135], v[136:137], v[160:161]
	v_pk_add_f32 v[136:137], v[136:137], v[160:161] neg_lo:[0,1] neg_hi:[0,1]
	v_pk_add_f32 v[160:161], v[156:157], v[154:155]
	v_pk_add_f32 v[68:69], v[156:157], v[154:155] neg_lo:[0,1] neg_hi:[0,1]
	v_pk_add_f32 v[154:155], v[142:143], v[162:163]
	v_pk_add_f32 v[142:143], v[142:143], v[162:163] neg_lo:[0,1] neg_hi:[0,1]
	v_pk_add_f32 v[156:157], v[144:145], v[158:159]
	v_pk_add_f32 v[76:77], v[144:145], v[158:159] neg_lo:[0,1] neg_hi:[0,1]
	v_pk_add_f32 v[144:145], v[138:139], v[150:151]
	v_pk_add_f32 v[138:139], v[138:139], v[150:151] neg_lo:[0,1] neg_hi:[0,1]
	v_pk_add_f32 v[150:151], v[146:147], v[140:141]
	v_pk_add_f32 v[66:67], v[146:147], v[140:141] neg_lo:[0,1] neg_hi:[0,1]
	v_pk_add_f32 v[140:141], v[120:121], v[152:153]
	v_pk_add_f32 v[162:163], v[116:117], v[178:179]
	v_pk_add_f32 v[70:71], v[116:117], v[178:179] neg_lo:[0,1] neg_hi:[0,1]
	v_mov_b32_e32 v116, v75
	v_pk_mul_f32 v[116:117], v[116:117], v[140:141] op_sel:[0,1] op_sel_hi:[0,0] neg_hi:[1,0]
	v_pk_fma_f32 v[116:117], v[140:141], v[74:75], v[116:117] op_sel_hi:[1,0,1]
	ds_write_b64 v222, v[116:117] offset:256
	v_pk_mul_f32 v[114:115], v[78:79], v[74:75] op_sel:[0,1] op_sel_hi:[1,0]
	v_pk_add_f32 v[172:173], v[128:129], v[72:73]
	v_pk_fma_f32 v[114:115], v[74:75], v[74:75], v[114:115] op_sel_hi:[1,0,1]
	v_pk_add_f32 v[128:129], v[128:129], v[72:73] op_sel:[1,1] op_sel_hi:[0,0] neg_lo:[0,1] neg_hi:[1,0]
	v_pk_mul_f32 v[116:117], v[154:155], v[114:115] op_sel:[1,1] op_sel_hi:[0,1] neg_hi:[0,1]
	v_pk_fma_f32 v[116:117], v[154:155], v[114:115], v[116:117] op_sel_hi:[1,0,1]
	ds_write_b64 v222, v[116:117] offset:520
	v_pk_mul_f32 v[116:117], v[78:79], v[114:115] op_sel:[0,1] op_sel_hi:[1,0]
	v_pk_add_f32 v[120:121], v[120:121], v[152:153] neg_lo:[0,1] neg_hi:[0,1]
	v_pk_fma_f32 v[114:115], v[114:115], v[74:75], v[116:117] op_sel_hi:[1,0,1]
	v_pk_add_f32 v[152:153], v[122:123], v[130:131]
	v_pk_add_f32 v[122:123], v[122:123], v[130:131] neg_lo:[0,1] neg_hi:[0,1]
	v_pk_add_f32 v[130:131], v[126:127], v[124:125]
	v_pk_add_f32 v[72:73], v[126:127], v[124:125] neg_lo:[0,1] neg_hi:[0,1]
	v_pk_add_f32 v[124:125], v[80:81], v[172:173]
	v_pk_mul_f32 v[116:117], v[124:125], v[114:115] op_sel:[1,1] op_sel_hi:[0,1] neg_hi:[0,1]
	v_pk_add_f32 v[126:127], v[80:81], v[172:173] neg_lo:[0,1] neg_hi:[0,1]
	v_pk_fma_f32 v[116:117], v[124:125], v[114:115], v[116:117] op_sel_hi:[1,0,1]
	ds_write_b64 v222, v[116:117] offset:784
	v_pk_mul_f32 v[112:113], v[78:79], v[114:115] op_sel:[0,1] op_sel_hi:[1,0]
	v_pk_add_f32 v[158:159], v[132:133], v[128:129]
	v_pk_fma_f32 v[112:113], v[114:115], v[74:75], v[112:113] op_sel_hi:[1,0,1]
	v_pk_add_f32 v[80:81], v[132:133], v[128:129] neg_lo:[0,1] neg_hi:[0,1]
	v_pk_add_f32 v[128:129], v[174:175], v[176:177]
	v_pk_mul_f32 v[114:115], v[134:135], v[112:113] op_sel:[1,1] op_sel_hi:[0,1] neg_hi:[0,1]
	v_pk_add_f32 v[146:147], v[148:149], v[164:165]
	v_pk_fma_f32 v[114:115], v[134:135], v[112:113], v[114:115] op_sel_hi:[1,0,1]
	ds_write_b64 v222, v[114:115] offset:1048
	v_pk_mul_f32 v[114:115], v[78:79], v[112:113] op_sel:[0,1] op_sel_hi:[1,0]
	v_pk_add_f32 v[132:133], v[174:175], v[176:177] neg_lo:[0,1] neg_hi:[0,1]
	v_pk_fma_f32 v[112:113], v[112:113], v[74:75], v[114:115] op_sel_hi:[1,0,1]
	v_pk_add_f32 v[148:149], v[148:149], v[164:165] neg_lo:[0,1] neg_hi:[0,1]
	v_pk_mul_f32 v[114:115], v[152:153], v[112:113] op_sel:[1,1] op_sel_hi:[0,1] neg_hi:[0,1]
	v_pk_fma_f32 v[114:115], v[152:153], v[112:113], v[114:115] op_sel_hi:[1,0,1]
	ds_write_b64 v222, v[114:115] offset:1312
	v_pk_mul_f32 v[110:111], v[78:79], v[112:113] op_sel:[0,1] op_sel_hi:[1,0]
	v_pk_fma_f32 v[110:111], v[112:113], v[74:75], v[110:111] op_sel_hi:[1,0,1]
	v_pk_mul_f32 v[112:113], v[144:145], v[110:111] op_sel:[1,1] op_sel_hi:[0,1] neg_hi:[0,1]
	v_pk_fma_f32 v[112:113], v[144:145], v[110:111], v[112:113] op_sel_hi:[1,0,1]
	ds_write_b64 v222, v[112:113] offset:1576
	v_pk_mul_f32 v[112:113], v[78:79], v[110:111] op_sel:[0,1] op_sel_hi:[1,0]
	v_pk_fma_f32 v[110:111], v[110:111], v[74:75], v[112:113] op_sel_hi:[1,0,1]
	v_pk_mul_f32 v[112:113], v[128:129], v[110:111] op_sel:[1,1] op_sel_hi:[0,1] neg_hi:[0,1]
	v_pk_fma_f32 v[112:113], v[128:129], v[110:111], v[112:113] op_sel_hi:[1,0,1]
	ds_write_b64 v222, v[112:113] offset:1840
	v_pk_mul_f32 v[108:109], v[78:79], v[110:111] op_sel:[0,1] op_sel_hi:[1,0]
	v_pk_fma_f32 v[108:109], v[110:111], v[74:75], v[108:109] op_sel_hi:[1,0,1]
	v_pk_mul_f32 v[110:111], v[168:169], v[108:109] op_sel:[1,1] op_sel_hi:[0,1] neg_hi:[0,1]
	v_pk_fma_f32 v[110:111], v[168:169], v[108:109], v[110:111] op_sel_hi:[1,0,1]
	ds_write_b64 v222, v[110:111] offset:2104
	v_pk_mul_f32 v[110:111], v[78:79], v[108:109] op_sel:[0,1] op_sel_hi:[1,0]
	v_pk_fma_f32 v[108:109], v[108:109], v[74:75], v[110:111] op_sel_hi:[1,0,1]
	v_pk_mul_f32 v[110:111], v[146:147], v[108:109] op_sel:[1,1] op_sel_hi:[0,1] neg_hi:[0,1]
	v_pk_fma_f32 v[110:111], v[146:147], v[108:109], v[110:111] op_sel_hi:[1,0,1]
	ds_write_b64 v222, v[110:111] offset:2368
	v_pk_mul_f32 v[106:107], v[78:79], v[108:109] op_sel:[0,1] op_sel_hi:[1,0]
	v_pk_fma_f32 v[106:107], v[108:109], v[74:75], v[106:107] op_sel_hi:[1,0,1]
	v_pk_mul_f32 v[108:109], v[156:157], v[106:107] op_sel:[1,1] op_sel_hi:[0,1] neg_hi:[0,1]
	v_pk_fma_f32 v[108:109], v[156:157], v[106:107], v[108:109] op_sel_hi:[1,0,1]
	ds_write_b64 v222, v[108:109] offset:2632
	v_pk_mul_f32 v[108:109], v[78:79], v[106:107] op_sel:[0,1] op_sel_hi:[1,0]
	v_pk_fma_f32 v[106:107], v[106:107], v[74:75], v[108:109] op_sel_hi:[1,0,1]
	v_pk_mul_f32 v[108:109], v[158:159], v[106:107] op_sel:[1,1] op_sel_hi:[0,1] neg_hi:[0,1]
	v_pk_fma_f32 v[108:109], v[158:159], v[106:107], v[108:109] op_sel_hi:[1,0,1]
	ds_write_b64 v222, v[108:109] offset:2896
	v_pk_mul_f32 v[108:109], v[78:79], v[106:107] op_sel:[0,1] op_sel_hi:[1,0]
	v_pk_fma_f32 v[106:107], v[106:107], v[74:75], v[108:109] op_sel_hi:[1,0,1]
	v_pk_mul_f32 v[108:109], v[160:161], v[106:107] op_sel:[1,1] op_sel_hi:[0,1] neg_hi:[0,1]
	v_pk_fma_f32 v[108:109], v[160:161], v[106:107], v[108:109] op_sel_hi:[1,0,1]
	ds_write_b64 v222, v[108:109] offset:3160
	v_pk_mul_f32 v[102:103], v[78:79], v[106:107] op_sel:[0,1] op_sel_hi:[1,0]
	v_pk_fma_f32 v[102:103], v[106:107], v[74:75], v[102:103] op_sel_hi:[1,0,1]
	v_pk_mul_f32 v[106:107], v[130:131], v[102:103] op_sel:[1,1] op_sel_hi:[0,1] neg_hi:[0,1]
	v_pk_fma_f32 v[106:107], v[130:131], v[102:103], v[106:107] op_sel_hi:[1,0,1]
	ds_write_b64 v222, v[106:107] offset:3424
	v_pk_mul_f32 v[106:107], v[78:79], v[102:103] op_sel:[0,1] op_sel_hi:[1,0]
	v_pk_fma_f32 v[102:103], v[102:103], v[74:75], v[106:107] op_sel_hi:[1,0,1]
	v_pk_mul_f32 v[106:107], v[150:151], v[102:103] op_sel:[1,1] op_sel_hi:[0,1] neg_hi:[0,1]
	v_pk_fma_f32 v[106:107], v[150:151], v[102:103], v[106:107] op_sel_hi:[1,0,1]
	ds_write_b64 v222, v[106:107] offset:3688
	v_pk_mul_f32 v[100:101], v[78:79], v[102:103] op_sel:[0,1] op_sel_hi:[1,0]
	v_pk_fma_f32 v[100:101], v[102:103], v[74:75], v[100:101] op_sel_hi:[1,0,1]
	v_pk_mul_f32 v[102:103], v[162:163], v[100:101] op_sel:[1,1] op_sel_hi:[0,1] neg_hi:[0,1]
	v_pk_fma_f32 v[102:103], v[162:163], v[100:101], v[102:103] op_sel_hi:[1,0,1]
	ds_write_b64 v222, v[102:103] offset:3952
	v_pk_mul_f32 v[102:103], v[78:79], v[100:101] op_sel:[0,1] op_sel_hi:[1,0]
	v_pk_fma_f32 v[100:101], v[100:101], v[74:75], v[102:103] op_sel_hi:[1,0,1]
	v_pk_mul_f32 v[102:103], v[118:119], v[100:101] op_sel:[1,1] op_sel_hi:[0,1] neg_hi:[0,1]
	v_pk_fma_f32 v[102:103], v[118:119], v[100:101], v[102:103] op_sel_hi:[1,0,1]
	ds_write_b64 v222, v[102:103] offset:4216
	v_pk_mul_f32 v[98:99], v[78:79], v[100:101] op_sel:[0,1] op_sel_hi:[1,0]
	v_pk_fma_f32 v[98:99], v[100:101], v[74:75], v[98:99] op_sel_hi:[1,0,1]
	v_pk_mul_f32 v[100:101], v[120:121], v[98:99] op_sel:[1,1] op_sel_hi:[0,1] neg_hi:[0,1]
	v_pk_fma_f32 v[100:101], v[120:121], v[98:99], v[100:101] op_sel_hi:[1,0,1]
	ds_write_b64 v222, v[100:101] offset:4480
	v_pk_mul_f32 v[100:101], v[78:79], v[98:99] op_sel:[0,1] op_sel_hi:[1,0]
	v_pk_fma_f32 v[98:99], v[98:99], v[74:75], v[100:101] op_sel_hi:[1,0,1]
	v_pk_mul_f32 v[100:101], v[142:143], v[98:99] op_sel:[1,1] op_sel_hi:[0,1] neg_hi:[0,1]
	v_pk_fma_f32 v[100:101], v[142:143], v[98:99], v[100:101] op_sel_hi:[1,0,1]
	ds_write_b64 v222, v[100:101] offset:4744
	v_pk_mul_f32 v[96:97], v[78:79], v[98:99] op_sel:[0,1] op_sel_hi:[1,0]
	v_pk_fma_f32 v[96:97], v[98:99], v[74:75], v[96:97] op_sel_hi:[1,0,1]
	v_pk_mul_f32 v[98:99], v[126:127], v[96:97] op_sel:[1,1] op_sel_hi:[0,1] neg_hi:[0,1]
	v_pk_fma_f32 v[98:99], v[126:127], v[96:97], v[98:99] op_sel_hi:[1,0,1]
	ds_write_b64 v222, v[98:99] offset:5008
	v_pk_mul_f32 v[98:99], v[78:79], v[96:97] op_sel:[0,1] op_sel_hi:[1,0]
	v_pk_fma_f32 v[96:97], v[96:97], v[74:75], v[98:99] op_sel_hi:[1,0,1]
	v_pk_mul_f32 v[98:99], v[136:137], v[96:97] op_sel:[1,1] op_sel_hi:[0,1] neg_hi:[0,1]
	v_pk_fma_f32 v[98:99], v[136:137], v[96:97], v[98:99] op_sel_hi:[1,0,1]
	ds_write_b64 v222, v[98:99] offset:5272
	v_pk_mul_f32 v[94:95], v[78:79], v[96:97] op_sel:[0,1] op_sel_hi:[1,0]
	v_pk_fma_f32 v[94:95], v[96:97], v[74:75], v[94:95] op_sel_hi:[1,0,1]
	v_pk_mul_f32 v[96:97], v[122:123], v[94:95] op_sel:[1,1] op_sel_hi:[0,1] neg_hi:[0,1]
	v_pk_fma_f32 v[96:97], v[122:123], v[94:95], v[96:97] op_sel_hi:[1,0,1]
	ds_write_b64 v222, v[96:97] offset:5536
	v_pk_mul_f32 v[96:97], v[78:79], v[94:95] op_sel:[0,1] op_sel_hi:[1,0]
	v_pk_fma_f32 v[94:95], v[94:95], v[74:75], v[96:97] op_sel_hi:[1,0,1]
	v_pk_mul_f32 v[96:97], v[138:139], v[94:95] op_sel:[1,1] op_sel_hi:[0,1] neg_hi:[0,1]
	v_pk_fma_f32 v[96:97], v[138:139], v[94:95], v[96:97] op_sel_hi:[1,0,1]
	ds_write_b64 v222, v[96:97] offset:5800
	v_pk_mul_f32 v[92:93], v[78:79], v[94:95] op_sel:[0,1] op_sel_hi:[1,0]
	v_pk_fma_f32 v[92:93], v[94:95], v[74:75], v[92:93] op_sel_hi:[1,0,1]
	v_pk_mul_f32 v[94:95], v[132:133], v[92:93] op_sel:[1,1] op_sel_hi:[0,1] neg_hi:[0,1]
	v_pk_fma_f32 v[94:95], v[132:133], v[92:93], v[94:95] op_sel_hi:[1,0,1]
	ds_write_b64 v222, v[94:95] offset:6064
	v_pk_mul_f32 v[94:95], v[78:79], v[92:93] op_sel:[0,1] op_sel_hi:[1,0]
	v_pk_fma_f32 v[92:93], v[92:93], v[74:75], v[94:95] op_sel_hi:[1,0,1]
	v_pk_mul_f32 v[94:95], v[82:83], v[92:93] op_sel:[1,1] op_sel_hi:[0,1] neg_hi:[0,1]
	v_pk_fma_f32 v[82:83], v[82:83], v[92:93], v[94:95] op_sel_hi:[1,0,1]
	ds_write_b64 v222, v[82:83] offset:6328
	v_pk_mul_f32 v[82:83], v[78:79], v[92:93] op_sel:[0,1] op_sel_hi:[1,0]
	v_pk_fma_f32 v[82:83], v[92:93], v[74:75], v[82:83] op_sel_hi:[1,0,1]
	v_pk_mul_f32 v[90:91], v[148:149], v[82:83] op_sel:[1,1] op_sel_hi:[0,1] neg_hi:[0,1]
	v_pk_fma_f32 v[90:91], v[148:149], v[82:83], v[90:91] op_sel_hi:[1,0,1]
	ds_write_b64 v222, v[90:91] offset:6592
	v_pk_mul_f32 v[90:91], v[78:79], v[82:83] op_sel:[0,1] op_sel_hi:[1,0]
	v_pk_fma_f32 v[82:83], v[82:83], v[74:75], v[90:91] op_sel_hi:[1,0,1]
	v_pk_mul_f32 v[90:91], v[76:77], v[82:83] op_sel:[1,1] op_sel_hi:[0,1] neg_hi:[0,1]
	v_pk_fma_f32 v[76:77], v[76:77], v[82:83], v[90:91] op_sel_hi:[1,0,1]
	ds_write_b64 v222, v[76:77] offset:6856
	v_pk_mul_f32 v[76:77], v[78:79], v[82:83] op_sel:[0,1] op_sel_hi:[1,0]
	v_pk_fma_f32 v[76:77], v[82:83], v[74:75], v[76:77] op_sel_hi:[1,0,1]
	v_pk_mul_f32 v[82:83], v[80:81], v[76:77] op_sel:[1,1] op_sel_hi:[0,1] neg_hi:[0,1]
	v_pk_fma_f32 v[80:81], v[80:81], v[76:77], v[82:83] op_sel_hi:[1,0,1]
	ds_write_b64 v222, v[80:81] offset:7120
	v_pk_mul_f32 v[80:81], v[78:79], v[76:77] op_sel:[0,1] op_sel_hi:[1,0]
	v_pk_fma_f32 v[76:77], v[76:77], v[74:75], v[80:81] op_sel_hi:[1,0,1]
	v_pk_mul_f32 v[80:81], v[68:69], v[76:77] op_sel:[1,1] op_sel_hi:[0,1] neg_hi:[0,1]
	v_pk_fma_f32 v[68:69], v[68:69], v[76:77], v[80:81] op_sel_hi:[1,0,1]
	ds_write_b64 v222, v[68:69] offset:7384
	v_pk_mul_f32 v[68:69], v[78:79], v[76:77] op_sel:[0,1] op_sel_hi:[1,0]
	v_pk_fma_f32 v[68:69], v[76:77], v[74:75], v[68:69] op_sel_hi:[1,0,1]
	v_pk_mul_f32 v[76:77], v[72:73], v[68:69] op_sel:[1,1] op_sel_hi:[0,1] neg_hi:[0,1]
	v_pk_fma_f32 v[72:73], v[72:73], v[68:69], v[76:77] op_sel_hi:[1,0,1]
	ds_write_b64 v222, v[72:73] offset:7648
	v_pk_mul_f32 v[72:73], v[78:79], v[68:69] op_sel:[0,1] op_sel_hi:[1,0]
	v_pk_fma_f32 v[68:69], v[68:69], v[74:75], v[72:73] op_sel_hi:[1,0,1]
	v_pk_mul_f32 v[72:73], v[66:67], v[68:69] op_sel:[1,1] op_sel_hi:[0,1] neg_hi:[0,1]
	v_pk_fma_f32 v[66:67], v[66:67], v[68:69], v[72:73] op_sel_hi:[1,0,1]
	ds_write_b64 v222, v[66:67] offset:7912
	v_pk_mul_f32 v[66:67], v[78:79], v[68:69] op_sel:[0,1] op_sel_hi:[1,0]
	v_pk_fma_f32 v[66:67], v[68:69], v[74:75], v[66:67] op_sel_hi:[1,0,1]
	v_pk_mul_f32 v[68:69], v[70:71], v[66:67] op_sel:[1,1] op_sel_hi:[0,1] neg_hi:[0,1]
	v_pk_fma_f32 v[66:67], v[70:71], v[66:67], v[68:69] op_sel_hi:[1,0,1]
	ds_write_b64 v222, v[66:67] offset:8176
	s_waitcnt lgkmcnt(0)
	s_barrier
	ds_read2_b64 v[66:69], v104 offset1:1
	ds_read2_b64 v[70:73], v104 offset0:2 offset1:3
	ds_read2_b64 v[74:77], v104 offset0:4 offset1:5
	ds_read2_b64 v[78:81], v104 offset0:6 offset1:7
	ds_read2_b64 v[82:85], v104 offset0:8 offset1:9
	ds_read2_b64 v[86:89], v104 offset0:10 offset1:11
	ds_read2_b64 v[90:93], v104 offset0:12 offset1:13
	ds_read2_b64 v[94:97], v104 offset0:14 offset1:15
	ds_read2_b64 v[98:101], v104 offset0:16 offset1:17
	ds_read2_b64 v[106:109], v104 offset0:18 offset1:19
	ds_read2_b64 v[110:113], v104 offset0:20 offset1:21
	ds_read2_b64 v[114:117], v104 offset0:22 offset1:23
	ds_read2_b64 v[118:121], v104 offset0:24 offset1:25
	ds_read2_b64 v[122:125], v104 offset0:26 offset1:27
	ds_read2_b64 v[126:129], v104 offset0:28 offset1:29
	ds_read2_b64 v[130:133], v104 offset0:30 offset1:31
	s_waitcnt lgkmcnt(7)
	v_pk_add_f32 v[102:103], v[66:67], v[98:99]
	v_pk_add_f32 v[66:67], v[66:67], v[98:99] neg_lo:[0,1] neg_hi:[0,1]
	v_pk_add_f32 v[98:99], v[68:69], v[100:101]
	v_pk_add_f32 v[68:69], v[68:69], v[100:101] neg_lo:[0,1] neg_hi:[0,1]
	global_load_dwordx2 v[134:135], v[2:3], off
	global_load_dwordx2 v[136:137], v[4:5], off
	global_load_dwordx2 v[138:139], v[6:7], off
	v_pk_mul_f32 v[100:101], v[68:69], s[18:19]
	global_load_dwordx2 v[148:149], v[14:15], off
	global_load_dwordx2 v[154:155], v[16:17], off
	v_pk_fma_f32 v[68:69], v[68:69], s[20:21], v[100:101] op_sel:[0,0,1] op_sel_hi:[1,0,0]
	s_waitcnt lgkmcnt(6)
	v_pk_add_f32 v[100:101], v[70:71], v[106:107]
	v_pk_add_f32 v[70:71], v[70:71], v[106:107] neg_lo:[0,1] neg_hi:[0,1]
	global_load_dwordx2 v[158:159], v[18:19], off
	v_pk_mul_f32 v[106:107], v[70:71], s[4:5]
	global_load_dwordx2 v[160:161], v[28:29], off
	global_load_dwordx2 v[164:165], v[32:33], off
	v_pk_fma_f32 v[70:71], v[70:71], s[6:7], v[106:107] op_sel:[0,0,1] op_sel_hi:[1,0,0]
	v_pk_add_f32 v[106:107], v[72:73], v[108:109]
	v_pk_add_f32 v[72:73], v[72:73], v[108:109] neg_lo:[0,1] neg_hi:[0,1]
	global_load_dwordx2 v[168:169], v[36:37], off
	v_pk_mul_f32 v[108:109], v[72:73], s[22:23]
	global_load_dwordx2 v[172:173], v[44:45], off
	v_pk_fma_f32 v[72:73], v[72:73], s[24:25], v[108:109] op_sel:[0,0,1] op_sel_hi:[1,0,0]
	s_waitcnt lgkmcnt(5)
	v_pk_add_f32 v[108:109], v[74:75], v[110:111]
	v_pk_add_f32 v[74:75], v[74:75], v[110:111] neg_lo:[0,1] neg_hi:[0,1]
	global_load_dwordx2 v[174:175], v[52:53], off
	v_pk_mul_f32 v[110:111], v[74:75], s[8:9]
	global_load_dwordx2 v[176:177], v[60:61], off
	v_pk_fma_f32 v[74:75], v[74:75], s[10:11], v[110:111] op_sel:[0,0,1] op_sel_hi:[1,0,0]
	v_pk_add_f32 v[110:111], v[76:77], v[112:113]
	v_pk_add_f32 v[76:77], v[76:77], v[112:113] neg_lo:[0,1] neg_hi:[0,1]
	v_pk_mul_f32 v[112:113], v[76:77], s[26:27]
	v_pk_fma_f32 v[76:77], v[76:77], s[0:1], v[112:113] op_sel:[0,0,1] op_sel_hi:[1,0,0]
	s_waitcnt lgkmcnt(4)
	v_pk_add_f32 v[112:113], v[78:79], v[114:115]
	v_pk_add_f32 v[78:79], v[78:79], v[114:115] neg_lo:[0,1] neg_hi:[0,1]
	v_pk_mul_f32 v[114:115], v[78:79], s[12:13]
	v_pk_fma_f32 v[78:79], v[78:79], s[14:15], v[114:115] op_sel:[0,0,1] op_sel_hi:[1,0,0]
	v_pk_add_f32 v[114:115], v[80:81], v[116:117]
	v_pk_add_f32 v[80:81], v[80:81], v[116:117] neg_lo:[0,1] neg_hi:[0,1]
	v_pk_mul_f32 v[116:117], v[80:81], s[34:35]
	v_pk_fma_f32 v[80:81], v[80:81], s[48:49], v[116:117] op_sel:[0,0,1] op_sel_hi:[1,0,0]
	s_waitcnt lgkmcnt(3)
	v_pk_add_f32 v[116:117], v[82:83], v[118:119]
	v_pk_add_f32 v[118:119], v[82:83], v[118:119] op_sel:[1,1] op_sel_hi:[0,0] neg_lo:[0,1] neg_hi:[1,0]
	v_pk_add_f32 v[82:83], v[84:85], v[120:121]
	v_pk_add_f32 v[84:85], v[84:85], v[120:121] neg_lo:[0,1] neg_hi:[0,1]
	v_pk_mul_f32 v[120:121], v[84:85], s[34:35]
	v_pk_fma_f32 v[84:85], v[84:85], s[18:19], v[120:121] op_sel:[0,0,1] op_sel_hi:[1,0,0]
	s_waitcnt lgkmcnt(2)
	v_pk_add_f32 v[120:121], v[86:87], v[122:123]
	v_pk_add_f32 v[86:87], v[86:87], v[122:123] neg_lo:[0,1] neg_hi:[0,1]
	v_pk_mul_f32 v[122:123], v[86:87], s[12:13]
	v_pk_fma_f32 v[86:87], v[86:87], s[4:5], v[122:123] op_sel:[0,0,1] op_sel_hi:[1,0,0]
	v_pk_add_f32 v[122:123], v[88:89], v[124:125]
	v_pk_add_f32 v[88:89], v[88:89], v[124:125] neg_lo:[0,1] neg_hi:[0,1]
	v_pk_mul_f32 v[124:125], v[88:89], s[26:27]
	v_pk_fma_f32 v[88:89], v[88:89], s[22:23], v[124:125] op_sel:[0,0,1] op_sel_hi:[1,0,0]
	s_waitcnt lgkmcnt(1)
	v_pk_add_f32 v[124:125], v[90:91], v[126:127]
	v_pk_add_f32 v[90:91], v[90:91], v[126:127] neg_lo:[0,1] neg_hi:[0,1]
	v_pk_mul_f32 v[126:127], v[90:91], s[8:9]
	v_pk_fma_f32 v[90:91], v[90:91], s[8:9], v[126:127] op_sel:[0,0,1] op_sel_hi:[1,0,0]
	v_pk_add_f32 v[126:127], v[92:93], v[128:129]
	v_pk_add_f32 v[92:93], v[92:93], v[128:129] neg_lo:[0,1] neg_hi:[0,1]
	v_pk_mul_f32 v[128:129], v[92:93], s[22:23]
	v_pk_fma_f32 v[92:93], v[92:93], s[26:27], v[128:129] op_sel:[0,0,1] op_sel_hi:[1,0,0]
	s_waitcnt lgkmcnt(0)
	v_pk_add_f32 v[128:129], v[94:95], v[130:131]
	v_pk_add_f32 v[94:95], v[94:95], v[130:131] neg_lo:[0,1] neg_hi:[0,1]
	v_pk_mul_f32 v[130:131], v[94:95], s[4:5]
	v_pk_fma_f32 v[94:95], v[94:95], s[12:13], v[130:131] op_sel:[0,0,1] op_sel_hi:[1,0,0]
	v_pk_add_f32 v[130:131], v[96:97], v[132:133]
	v_pk_add_f32 v[96:97], v[96:97], v[132:133] neg_lo:[0,1] neg_hi:[0,1]
	v_pk_mul_f32 v[132:133], v[96:97], s[18:19]
	v_pk_fma_f32 v[96:97], v[96:97], s[34:35], v[132:133] op_sel:[0,0,1] op_sel_hi:[1,0,0]
	v_pk_add_f32 v[132:133], v[102:103], v[116:117]
	v_pk_add_f32 v[102:103], v[102:103], v[116:117] neg_lo:[0,1] neg_hi:[0,1]
	v_pk_add_f32 v[116:117], v[98:99], v[82:83]
	v_pk_add_f32 v[82:83], v[98:99], v[82:83] neg_lo:[0,1] neg_hi:[0,1]
	v_pk_mul_f32 v[98:99], v[82:83], s[4:5]
	v_pk_fma_f32 v[82:83], v[82:83], s[6:7], v[98:99] op_sel:[0,0,1] op_sel_hi:[1,0,0]
	v_pk_add_f32 v[98:99], v[100:101], v[120:121]
	v_pk_add_f32 v[100:101], v[100:101], v[120:121] neg_lo:[0,1] neg_hi:[0,1]
	v_pk_mul_f32 v[120:121], v[100:101], s[8:9]
	v_pk_fma_f32 v[100:101], v[100:101], s[10:11], v[120:121] op_sel:[0,0,1] op_sel_hi:[1,0,0]
	v_pk_add_f32 v[120:121], v[106:107], v[122:123]
	v_pk_add_f32 v[106:107], v[106:107], v[122:123] neg_lo:[0,1] neg_hi:[0,1]
	v_pk_mul_f32 v[122:123], v[106:107], s[12:13]
	v_pk_fma_f32 v[106:107], v[106:107], s[14:15], v[122:123] op_sel:[0,0,1] op_sel_hi:[1,0,0]
	v_pk_add_f32 v[122:123], v[108:109], v[124:125]
	v_pk_add_f32 v[124:125], v[108:109], v[124:125] op_sel:[1,1] op_sel_hi:[0,0] neg_lo:[0,1] neg_hi:[1,0]
	v_pk_add_f32 v[108:109], v[110:111], v[126:127]
	v_pk_add_f32 v[110:111], v[110:111], v[126:127] neg_lo:[0,1] neg_hi:[0,1]
	v_pk_mul_f32 v[126:127], v[110:111], s[12:13]
	v_pk_fma_f32 v[110:111], v[110:111], s[4:5], v[126:127] op_sel:[0,0,1] op_sel_hi:[1,0,0]
	v_pk_add_f32 v[126:127], v[112:113], v[128:129]
	v_pk_add_f32 v[112:113], v[112:113], v[128:129] neg_lo:[0,1] neg_hi:[0,1]
	v_pk_mul_f32 v[128:129], v[112:113], s[8:9]
	v_pk_fma_f32 v[112:113], v[112:113], s[8:9], v[128:129] op_sel:[0,0,1] op_sel_hi:[1,0,0]
	v_pk_add_f32 v[128:129], v[114:115], v[130:131]
	v_pk_add_f32 v[114:115], v[114:115], v[130:131] neg_lo:[0,1] neg_hi:[0,1]
	v_pk_mul_f32 v[130:131], v[114:115], s[4:5]
	v_pk_fma_f32 v[114:115], v[114:115], s[12:13], v[130:131] op_sel:[0,0,1] op_sel_hi:[1,0,0]
	v_pk_add_f32 v[130:131], v[66:67], v[118:119]
	v_pk_add_f32 v[66:67], v[66:67], v[118:119] neg_lo:[0,1] neg_hi:[0,1]
	v_pk_add_f32 v[118:119], v[68:69], v[84:85]
	v_pk_add_f32 v[68:69], v[68:69], v[84:85] neg_lo:[0,1] neg_hi:[0,1]
	v_pk_mul_f32 v[84:85], v[68:69], s[4:5]
	v_pk_fma_f32 v[68:69], v[68:69], s[6:7], v[84:85] op_sel:[0,0,1] op_sel_hi:[1,0,0]
	v_pk_add_f32 v[84:85], v[70:71], v[86:87]
	v_pk_add_f32 v[70:71], v[70:71], v[86:87] neg_lo:[0,1] neg_hi:[0,1]
	v_pk_mul_f32 v[86:87], v[70:71], s[8:9]
	v_pk_fma_f32 v[70:71], v[70:71], s[10:11], v[86:87] op_sel:[0,0,1] op_sel_hi:[1,0,0]
	v_pk_add_f32 v[86:87], v[72:73], v[88:89]
	v_pk_add_f32 v[72:73], v[72:73], v[88:89] neg_lo:[0,1] neg_hi:[0,1]
	v_pk_mul_f32 v[88:89], v[72:73], s[12:13]
	v_pk_fma_f32 v[72:73], v[72:73], s[14:15], v[88:89] op_sel:[0,0,1] op_sel_hi:[1,0,0]
	v_pk_add_f32 v[88:89], v[74:75], v[90:91]
	v_pk_add_f32 v[90:91], v[74:75], v[90:91] op_sel:[1,1] op_sel_hi:[0,0] neg_lo:[0,1] neg_hi:[1,0]
	s_mov_b32 s15, s4
	v_pk_add_f32 v[74:75], v[76:77], v[92:93]
	v_pk_add_f32 v[76:77], v[76:77], v[92:93] neg_lo:[0,1] neg_hi:[0,1]
	v_pk_mul_f32 v[92:93], v[76:77], s[12:13]
	v_pk_fma_f32 v[76:77], v[76:77], s[4:5], v[92:93] op_sel:[0,0,1] op_sel_hi:[1,0,0]
	v_pk_add_f32 v[92:93], v[78:79], v[94:95]
	v_pk_add_f32 v[78:79], v[78:79], v[94:95] neg_lo:[0,1] neg_hi:[0,1]
	v_pk_mul_f32 v[94:95], v[78:79], s[8:9]
	v_pk_fma_f32 v[78:79], v[78:79], s[8:9], v[94:95] op_sel:[0,0,1] op_sel_hi:[1,0,0]
	v_pk_add_f32 v[94:95], v[80:81], v[96:97]
	v_pk_add_f32 v[80:81], v[80:81], v[96:97] neg_lo:[0,1] neg_hi:[0,1]
	v_pk_mul_f32 v[96:97], v[80:81], s[4:5]
	v_pk_fma_f32 v[80:81], v[80:81], s[12:13], v[96:97] op_sel:[0,0,1] op_sel_hi:[1,0,0]
	v_pk_add_f32 v[96:97], v[132:133], v[122:123]
	v_pk_add_f32 v[122:123], v[132:133], v[122:123] neg_lo:[0,1] neg_hi:[0,1]
	v_pk_add_f32 v[132:133], v[116:117], v[108:109]
	v_pk_add_f32 v[108:109], v[116:117], v[108:109] neg_lo:[0,1] neg_hi:[0,1]
	v_pk_mul_f32 v[116:117], v[108:109], s[8:9]
	v_pk_fma_f32 v[108:109], v[108:109], s[10:11], v[116:117] op_sel:[0,0,1] op_sel_hi:[1,0,0]
	v_pk_add_f32 v[116:117], v[98:99], v[126:127]
	v_pk_add_f32 v[126:127], v[98:99], v[126:127] op_sel:[1,1] op_sel_hi:[0,0] neg_lo:[0,1] neg_hi:[1,0]
	v_pk_add_f32 v[98:99], v[120:121], v[128:129]
	v_pk_add_f32 v[120:121], v[120:121], v[128:129] neg_lo:[0,1] neg_hi:[0,1]
	v_pk_mul_f32 v[128:129], v[120:121], s[8:9]
	v_pk_fma_f32 v[120:121], v[120:121], s[8:9], v[128:129] op_sel:[0,0,1] op_sel_hi:[1,0,0]
	v_pk_add_f32 v[128:129], v[102:103], v[124:125]
	v_pk_add_f32 v[102:103], v[102:103], v[124:125] neg_lo:[0,1] neg_hi:[0,1]
	v_pk_add_f32 v[124:125], v[82:83], v[110:111]
	v_pk_add_f32 v[82:83], v[82:83], v[110:111] neg_lo:[0,1] neg_hi:[0,1]
	v_pk_mul_f32 v[110:111], v[82:83], s[8:9]
	v_pk_fma_f32 v[82:83], v[82:83], s[10:11], v[110:111] op_sel:[0,0,1] op_sel_hi:[1,0,0]
	v_pk_add_f32 v[110:111], v[100:101], v[112:113]
	v_pk_add_f32 v[112:113], v[100:101], v[112:113] op_sel:[1,1] op_sel_hi:[0,0] neg_lo:[0,1] neg_hi:[1,0]
	v_pk_add_f32 v[100:101], v[106:107], v[114:115]
	v_pk_add_f32 v[106:107], v[106:107], v[114:115] neg_lo:[0,1] neg_hi:[0,1]
	v_pk_mul_f32 v[114:115], v[106:107], s[8:9]
	v_pk_fma_f32 v[106:107], v[106:107], s[8:9], v[114:115] op_sel:[0,0,1] op_sel_hi:[1,0,0]
	v_pk_add_f32 v[114:115], v[130:131], v[88:89]
	v_pk_add_f32 v[88:89], v[130:131], v[88:89] neg_lo:[0,1] neg_hi:[0,1]
	v_pk_add_f32 v[130:131], v[118:119], v[74:75]
	v_pk_add_f32 v[74:75], v[118:119], v[74:75] neg_lo:[0,1] neg_hi:[0,1]
	v_pk_mul_f32 v[118:119], v[74:75], s[8:9]
	v_pk_fma_f32 v[74:75], v[74:75], s[10:11], v[118:119] op_sel:[0,0,1] op_sel_hi:[1,0,0]
	v_pk_add_f32 v[118:119], v[84:85], v[92:93]
	v_pk_add_f32 v[92:93], v[84:85], v[92:93] op_sel:[1,1] op_sel_hi:[0,0] neg_lo:[0,1] neg_hi:[1,0]
	v_pk_add_f32 v[84:85], v[86:87], v[94:95]
	v_pk_add_f32 v[86:87], v[86:87], v[94:95] neg_lo:[0,1] neg_hi:[0,1]
	v_pk_add_f32 v[140:141], v[88:89], v[92:93]
	v_pk_mul_f32 v[94:95], v[86:87], s[8:9]
	v_pk_add_f32 v[88:89], v[88:89], v[92:93] neg_lo:[0,1] neg_hi:[0,1]
	v_pk_fma_f32 v[86:87], v[86:87], s[8:9], v[94:95] op_sel:[0,0,1] op_sel_hi:[1,0,0]
	v_pk_add_f32 v[94:95], v[66:67], v[90:91]
	v_pk_add_f32 v[66:67], v[66:67], v[90:91] neg_lo:[0,1] neg_hi:[0,1]
	v_pk_add_f32 v[90:91], v[68:69], v[76:77]
	v_pk_add_f32 v[68:69], v[68:69], v[76:77] neg_lo:[0,1] neg_hi:[0,1]
	v_pk_add_f32 v[92:93], v[74:75], v[86:87]
	v_pk_mul_f32 v[76:77], v[68:69], s[8:9]
	v_pk_add_f32 v[142:143], v[74:75], v[86:87] op_sel:[1,1] op_sel_hi:[0,0] neg_lo:[0,1] neg_hi:[1,0]
	v_pk_fma_f32 v[68:69], v[68:69], s[10:11], v[76:77] op_sel:[0,0,1] op_sel_hi:[1,0,0]
	v_pk_add_f32 v[76:77], v[70:71], v[78:79]
	v_pk_add_f32 v[78:79], v[70:71], v[78:79] op_sel:[1,1] op_sel_hi:[0,0] neg_lo:[0,1] neg_hi:[1,0]
	global_load_dwordx2 v[86:87], v[10:11], off
	v_pk_add_f32 v[70:71], v[72:73], v[80:81]
	v_pk_add_f32 v[72:73], v[72:73], v[80:81] neg_lo:[0,1] neg_hi:[0,1]
	v_pk_mul_f32 v[80:81], v[72:73], s[8:9]
	v_pk_fma_f32 v[72:73], v[72:73], s[8:9], v[80:81] op_sel:[0,0,1] op_sel_hi:[1,0,0]
	v_pk_add_f32 v[80:81], v[96:97], v[116:117]
	v_pk_add_f32 v[96:97], v[96:97], v[116:117] neg_lo:[0,1] neg_hi:[0,1]
	v_pk_add_f32 v[116:117], v[132:133], v[98:99]
	v_pk_add_f32 v[132:133], v[132:133], v[98:99] op_sel:[1,1] op_sel_hi:[0,0] neg_lo:[0,1] neg_hi:[1,0]
	v_pk_add_f32 v[74:75], v[94:95], v[76:77]
	v_pk_add_f32 v[98:99], v[122:123], v[126:127]
	v_pk_add_f32 v[122:123], v[122:123], v[126:127] neg_lo:[0,1] neg_hi:[0,1]
	v_pk_add_f32 v[126:127], v[108:109], v[120:121]
	v_pk_add_f32 v[120:121], v[108:109], v[120:121] op_sel:[1,1] op_sel_hi:[0,0] neg_lo:[0,1] neg_hi:[1,0]
	v_pk_add_f32 v[76:77], v[94:95], v[76:77] neg_lo:[0,1] neg_hi:[0,1]
	v_pk_add_f32 v[108:109], v[128:129], v[110:111]
	v_pk_add_f32 v[110:111], v[128:129], v[110:111] neg_lo:[0,1] neg_hi:[0,1]
	v_pk_add_f32 v[128:129], v[124:125], v[100:101]
	v_pk_add_f32 v[124:125], v[124:125], v[100:101] op_sel:[1,1] op_sel_hi:[0,0] neg_lo:[0,1] neg_hi:[1,0]
	global_load_dwordx2 v[94:95], v[12:13], off
	v_pk_add_f32 v[100:101], v[102:103], v[112:113]
	v_pk_add_f32 v[102:103], v[102:103], v[112:113] neg_lo:[0,1] neg_hi:[0,1]
	v_pk_add_f32 v[112:113], v[82:83], v[106:107]
	v_pk_add_f32 v[106:107], v[82:83], v[106:107] op_sel:[1,1] op_sel_hi:[0,0] neg_lo:[0,1] neg_hi:[1,0]
	v_pk_add_f32 v[146:147], v[66:67], v[78:79]
	v_pk_add_f32 v[82:83], v[114:115], v[118:119]
	v_pk_add_f32 v[114:115], v[114:115], v[118:119] neg_lo:[0,1] neg_hi:[0,1]
	v_pk_add_f32 v[118:119], v[130:131], v[84:85]
	v_pk_add_f32 v[130:131], v[130:131], v[84:85] op_sel:[1,1] op_sel_hi:[0,0] neg_lo:[0,1] neg_hi:[1,0]
	v_pk_add_f32 v[78:79], v[66:67], v[78:79] neg_lo:[0,1] neg_hi:[0,1]
	global_load_dwordx2 v[84:85], v[8:9], off
	v_pk_add_f32 v[152:153], v[68:69], v[72:73] op_sel:[1,1] op_sel_hi:[0,0] neg_lo:[0,1] neg_hi:[1,0]
	v_pk_add_f32 v[150:151], v[68:69], v[72:73]
	v_pk_add_f32 v[156:157], v[80:81], v[116:117]
	v_pk_add_f32 v[80:81], v[80:81], v[116:117] neg_lo:[0,1] neg_hi:[0,1]
	v_pk_add_f32 v[116:117], v[96:97], v[132:133]
	v_pk_add_f32 v[68:69], v[96:97], v[132:133] neg_lo:[0,1] neg_hi:[0,1]
	v_pk_add_f32 v[96:97], v[98:99], v[126:127]
	v_pk_add_f32 v[98:99], v[98:99], v[126:127] neg_lo:[0,1] neg_hi:[0,1]
	v_pk_add_f32 v[126:127], v[122:123], v[120:121]
	v_pk_add_f32 v[66:67], v[122:123], v[120:121] neg_lo:[0,1] neg_hi:[0,1]
	global_load_dwordx2 v[120:121], v[20:21], off
	v_pk_add_f32 v[122:123], v[108:109], v[128:129]
	v_pk_add_f32 v[108:109], v[108:109], v[128:129] neg_lo:[0,1] neg_hi:[0,1]
	v_pk_add_f32 v[128:129], v[110:111], v[124:125]
	v_pk_add_f32 v[72:73], v[110:111], v[124:125] neg_lo:[0,1] neg_hi:[0,1]
	global_load_dwordx2 v[110:111], v[22:23], off
	v_pk_add_f32 v[144:145], v[90:91], v[70:71]
	v_pk_add_f32 v[90:91], v[90:91], v[70:71] op_sel:[1,1] op_sel_hi:[0,0] neg_lo:[0,1] neg_hi:[1,0]
	v_pk_add_f32 v[124:125], v[100:101], v[112:113]
	v_pk_add_f32 v[100:101], v[100:101], v[112:113] neg_lo:[0,1] neg_hi:[0,1]
	v_pk_add_f32 v[112:113], v[102:103], v[106:107]
	v_pk_add_f32 v[70:71], v[102:103], v[106:107] neg_lo:[0,1] neg_hi:[0,1]
	global_load_dwordx2 v[102:103], v[24:25], off
	v_pk_add_f32 v[106:107], v[82:83], v[118:119]
	v_pk_add_f32 v[82:83], v[82:83], v[118:119] neg_lo:[0,1] neg_hi:[0,1]
	v_pk_add_f32 v[118:119], v[114:115], v[130:131]
	v_pk_add_f32 v[114:115], v[114:115], v[130:131] neg_lo:[0,1] neg_hi:[0,1]
	global_load_dwordx2 v[130:131], v[26:27], off
	v_pk_add_f32 v[162:163], v[76:77], v[90:91]
	v_pk_add_f32 v[76:77], v[76:77], v[90:91] neg_lo:[0,1] neg_hi:[0,1]
	v_pk_add_f32 v[90:91], v[146:147], v[150:151]
	v_pk_add_f32 v[146:147], v[146:147], v[150:151] neg_lo:[0,1] neg_hi:[0,1]
	v_pk_add_f32 v[150:151], v[78:79], v[152:153]
	v_pk_add_f32 v[78:79], v[78:79], v[152:153] neg_lo:[0,1] neg_hi:[0,1]
	global_load_dwordx2 v[152:153], v[34:35], off
	s_waitcnt vmcnt(19)
	v_pk_mul_f32 v[166:167], v[156:157], v[134:135] op_sel:[1,1] op_sel_hi:[0,1] neg_lo:[0,1]
	v_pk_add_f32 v[132:133], v[140:141], v[92:93]
	v_pk_fma_f32 v[134:135], v[156:157], v[134:135], v[166:167] op_sel_hi:[1,0,1]
	s_waitcnt vmcnt(18)
	global_load_dwordx2 v[166:167], v[38:39], off
	v_pk_mul_f32 v[156:157], v[106:107], v[136:137] op_sel:[1,1] op_sel_hi:[0,1] neg_lo:[0,1]
	v_pk_add_f32 v[92:93], v[140:141], v[92:93] neg_lo:[0,1] neg_hi:[0,1]
	v_pk_fma_f32 v[106:107], v[106:107], v[136:137], v[156:157] op_sel_hi:[1,0,1]
	s_waitcnt vmcnt(18)
	global_load_dwordx2 v[156:157], v[40:41], off
	v_pk_mul_f32 v[136:137], v[122:123], v[138:139] op_sel:[1,1] op_sel_hi:[0,1] neg_lo:[0,1]
	v_pk_add_f32 v[140:141], v[88:89], v[142:143]
	v_pk_fma_f32 v[122:123], v[122:123], v[138:139], v[136:137] op_sel_hi:[1,0,1]
	global_load_dwordx2 v[136:137], v[42:43], off
	v_pk_add_f32 v[88:89], v[88:89], v[142:143] neg_lo:[0,1] neg_hi:[0,1]
	v_pk_add_f32 v[142:143], v[74:75], v[144:145]
	v_pk_add_f32 v[74:75], v[74:75], v[144:145] neg_lo:[0,1] neg_hi:[0,1]
	global_load_dwordx2 v[144:145], v[30:31], off
	s_mov_b32 s11, s8
	s_waitcnt vmcnt(9)
	v_pk_mul_f32 v[138:139], v[142:143], v[84:85] op_sel:[1,1] op_sel_hi:[0,1] neg_lo:[0,1]
	v_pk_fma_f32 v[84:85], v[142:143], v[84:85], v[138:139] op_sel_hi:[1,0,1]
	global_load_dwordx2 v[142:143], v[46:47], off
	v_pk_mul_f32 v[138:139], v[96:97], v[86:87] op_sel:[1,1] op_sel_hi:[0,1] neg_lo:[0,1]
	v_pk_fma_f32 v[86:87], v[96:97], v[86:87], v[138:139] op_sel_hi:[1,0,1]
	global_load_dwordx2 v[138:139], v[48:49], off
	v_pk_mul_f32 v[96:97], v[132:133], v[94:95] op_sel:[1,1] op_sel_hi:[0,1] neg_lo:[0,1]
	v_pk_fma_f32 v[94:95], v[132:133], v[94:95], v[96:97] op_sel_hi:[1,0,1]
	global_load_dwordx2 v[96:97], v[50:51], off
	v_pk_mul_f32 v[132:133], v[124:125], v[148:149] op_sel:[1,1] op_sel_hi:[0,1] neg_lo:[0,1]
	v_pk_fma_f32 v[124:125], v[124:125], v[148:149], v[132:133] op_sel_hi:[1,0,1]
	global_load_dwordx2 v[148:149], v[54:55], off
	v_pk_mul_f32 v[132:133], v[90:91], v[154:155] op_sel:[1,1] op_sel_hi:[0,1] neg_lo:[0,1]
	v_pk_fma_f32 v[90:91], v[90:91], v[154:155], v[132:133] op_sel_hi:[1,0,1]
	global_load_dwordx2 v[154:155], v[56:57], off
	v_pk_mul_f32 v[132:133], v[116:117], v[158:159] op_sel:[1,1] op_sel_hi:[0,1] neg_lo:[0,1]
	v_pk_fma_f32 v[116:117], v[116:117], v[158:159], v[132:133] op_sel_hi:[1,0,1]
	global_load_dwordx2 v[132:133], v[58:59], off
	s_waitcnt vmcnt(14)
	v_pk_mul_f32 v[158:159], v[118:119], v[120:121] op_sel:[1,1] op_sel_hi:[0,1] neg_lo:[0,1]
	v_pk_fma_f32 v[118:119], v[118:119], v[120:121], v[158:159] op_sel_hi:[1,0,1]
	s_waitcnt vmcnt(13)
	global_load_dwordx2 v[158:159], v[62:63], off
	v_pk_mul_f32 v[120:121], v[128:129], v[110:111] op_sel:[1,1] op_sel_hi:[0,1] neg_lo:[0,1]
	v_pk_fma_f32 v[110:111], v[128:129], v[110:111], v[120:121] op_sel_hi:[1,0,1]
	global_load_dwordx2 v[128:129], v[64:65], off
	s_waitcnt vmcnt(14)
	v_pk_mul_f32 v[120:121], v[162:163], v[102:103] op_sel:[1,1] op_sel_hi:[0,1] neg_lo:[0,1]
	v_mov_b32 v0, 0
	s_nop 0
	v_pk_fma_f32 v[102:103], v[162:163], v[102:103], v[120:121] op_sel_hi:[1,0,1]
	s_waitcnt vmcnt(13)
	v_pk_mul_f32 v[120:121], v[126:127], v[130:131] op_sel:[1,1] op_sel_hi:[0,1] neg_lo:[0,1]
	v_pk_fma_f32 v[120:121], v[126:127], v[130:131], v[120:121] op_sel_hi:[1,0,1]
	v_pk_mul_f32 v[126:127], v[140:141], v[160:161] op_sel:[1,1] op_sel_hi:[0,1] neg_lo:[0,1]
	v_pk_fma_f32 v[126:127], v[140:141], v[160:161], v[126:127] op_sel_hi:[1,0,1]
	s_waitcnt vmcnt(12)
	v_pk_mul_f32 v[140:141], v[80:81], v[152:153] op_sel:[1,1] op_sel_hi:[0,1] neg_lo:[0,1]
	v_pk_fma_f32 v[80:81], v[80:81], v[152:153], v[140:141] op_sel_hi:[1,0,1]
	v_pk_mul_f32 v[140:141], v[82:83], v[168:169] op_sel:[1,1] op_sel_hi:[0,1] neg_lo:[0,1]
	v_pk_fma_f32 v[82:83], v[82:83], v[168:169], v[140:141] op_sel_hi:[1,0,1]
	s_waitcnt vmcnt(11)
	v_pk_mul_f32 v[140:141], v[108:109], v[166:167] op_sel:[1,1] op_sel_hi:[0,1] neg_lo:[0,1]
	v_pk_fma_f32 v[108:109], v[108:109], v[166:167], v[140:141] op_sel_hi:[1,0,1]
	s_waitcnt vmcnt(10)
	v_pk_mul_f32 v[140:141], v[74:75], v[156:157] op_sel:[1,1] op_sel_hi:[0,1] neg_lo:[0,1]
	v_pk_fma_f32 v[74:75], v[74:75], v[156:157], v[140:141] op_sel_hi:[1,0,1]
	s_waitcnt vmcnt(9)
	v_pk_mul_f32 v[140:141], v[98:99], v[136:137] op_sel:[1,1] op_sel_hi:[0,1] neg_lo:[0,1]
	v_pk_fma_f32 v[98:99], v[98:99], v[136:137], v[140:141] op_sel_hi:[1,0,1]
	v_pk_mul_f32 v[136:137], v[92:93], v[172:173] op_sel:[1,1] op_sel_hi:[0,1] neg_lo:[0,1]
	v_pk_fma_f32 v[92:93], v[92:93], v[172:173], v[136:137] op_sel_hi:[1,0,1]
	s_waitcnt vmcnt(8)
	v_pk_mul_f32 v[130:131], v[112:113], v[144:145] op_sel:[1,1] op_sel_hi:[0,1] neg_lo:[0,1]
	v_pk_fma_f32 v[112:113], v[112:113], v[144:145], v[130:131] op_sel_hi:[1,0,1]
	s_waitcnt vmcnt(7)
	v_pk_mul_f32 v[136:137], v[100:101], v[142:143] op_sel:[1,1] op_sel_hi:[0,1] neg_lo:[0,1]
	v_pk_fma_f32 v[100:101], v[100:101], v[142:143], v[136:137] op_sel_hi:[1,0,1]
	s_waitcnt vmcnt(6)
	v_pk_mul_f32 v[136:137], v[146:147], v[138:139] op_sel:[1,1] op_sel_hi:[0,1] neg_lo:[0,1]
	v_pk_fma_f32 v[136:137], v[146:147], v[138:139], v[136:137] op_sel_hi:[1,0,1]
	s_waitcnt vmcnt(5)
	v_pk_mul_f32 v[138:139], v[68:69], v[96:97] op_sel:[1,1] op_sel_hi:[0,1] neg_lo:[0,1]
	v_pk_fma_f32 v[68:69], v[68:69], v[96:97], v[138:139] op_sel_hi:[1,0,1]
	v_pk_mul_f32 v[96:97], v[114:115], v[174:175] op_sel:[1,1] op_sel_hi:[0,1] neg_lo:[0,1]
	v_pk_fma_f32 v[96:97], v[114:115], v[174:175], v[96:97] op_sel_hi:[1,0,1]
	s_waitcnt vmcnt(4)
	v_pk_mul_f32 v[114:115], v[72:73], v[148:149] op_sel:[1,1] op_sel_hi:[0,1] neg_lo:[0,1]
	v_pk_fma_f32 v[72:73], v[72:73], v[148:149], v[114:115] op_sel_hi:[1,0,1]
	v_pk_mul_f32 v[130:131], v[150:151], v[164:165] op_sel:[1,1] op_sel_hi:[0,1] neg_lo:[0,1]
	s_waitcnt vmcnt(3)
	v_pk_mul_f32 v[114:115], v[76:77], v[154:155] op_sel:[1,1] op_sel_hi:[0,1] neg_lo:[0,1]
	v_pk_fma_f32 v[76:77], v[76:77], v[154:155], v[114:115] op_sel_hi:[1,0,1]
	s_waitcnt vmcnt(2)
	v_pk_mul_f32 v[114:115], v[66:67], v[132:133] op_sel:[1,1] op_sel_hi:[0,1] neg_lo:[0,1]
	v_pk_fma_f32 v[66:67], v[66:67], v[132:133], v[114:115] op_sel_hi:[1,0,1]
	v_pk_mul_f32 v[114:115], v[88:89], v[176:177] op_sel:[1,1] op_sel_hi:[0,1] neg_lo:[0,1]
	v_pk_fma_f32 v[88:89], v[88:89], v[176:177], v[114:115] op_sel_hi:[1,0,1]
	s_waitcnt vmcnt(1)
	v_pk_mul_f32 v[114:115], v[70:71], v[158:159] op_sel:[1,1] op_sel_hi:[0,1] neg_lo:[0,1]
	v_pk_fma_f32 v[70:71], v[70:71], v[158:159], v[114:115] op_sel_hi:[1,0,1]
	s_waitcnt vmcnt(0)
	v_pk_mul_f32 v[114:115], v[78:79], v[128:129] op_sel:[1,1] op_sel_hi:[0,1] neg_lo:[0,1]
	v_pk_fma_f32 v[78:79], v[78:79], v[128:129], v[114:115] op_sel_hi:[1,0,1]
	v_pk_add_f32 v[128:129], v[106:107], v[82:83]
	v_pk_add_f32 v[82:83], v[106:107], v[82:83] neg_lo:[0,1] neg_hi:[0,1]
	v_pk_fma_f32 v[130:131], v[150:151], v[164:165], v[130:131] op_sel_hi:[1,0,1]
	v_pk_mul_f32 v[106:107], v[82:83], s[50:51]
	v_pk_add_f32 v[114:115], v[134:135], v[80:81]
	v_pk_fma_f32 v[82:83], v[82:83], s[20:21], v[106:107] op_sel:[0,0,1] op_sel_hi:[1,0,0]
	v_pk_add_f32 v[106:107], v[122:123], v[108:109]
	v_pk_add_f32 v[108:109], v[122:123], v[108:109] neg_lo:[0,1] neg_hi:[0,1]
	s_mov_b32 s21, s34
	v_pk_mul_f32 v[122:123], v[108:109], s[14:15]
	v_pk_add_f32 v[80:81], v[134:135], v[80:81] neg_lo:[0,1] neg_hi:[0,1]
	v_pk_fma_f32 v[108:109], v[108:109], s[6:7], v[122:123] op_sel:[0,0,1] op_sel_hi:[1,0,0]
	v_pk_add_f32 v[122:123], v[84:85], v[74:75]
	v_pk_add_f32 v[74:75], v[84:85], v[74:75] neg_lo:[0,1] neg_hi:[0,1]
	s_mov_b32 s7, s12
	v_pk_mul_f32 v[84:85], v[74:75], s[52:53]
	v_add_u32_e32 v0, v0, v170
	v_pk_fma_f32 v[74:75], v[74:75], s[24:25], v[84:85] op_sel:[0,0,1] op_sel_hi:[1,0,0]
	v_pk_add_f32 v[84:85], v[86:87], v[98:99]
	v_pk_add_f32 v[86:87], v[86:87], v[98:99] neg_lo:[0,1] neg_hi:[0,1]
	s_mov_b32 s25, s26
	v_pk_mul_f32 v[98:99], v[86:87], s[10:11]
	v_lshlrev_b32_e32 v105, 5, v0
	v_pk_fma_f32 v[86:87], v[86:87], s[10:11], v[98:99] op_sel:[0,0,1] op_sel_hi:[1,0,0]
	v_pk_add_f32 v[98:99], v[94:95], v[92:93]
	v_pk_add_f32 v[92:93], v[94:95], v[92:93] neg_lo:[0,1] neg_hi:[0,1]
	v_pk_mul_f32 v[94:95], v[92:93], s[24:25]
	v_pk_fma_f32 v[92:93], v[92:93], s[0:1], v[94:95] op_sel:[0,0,1] op_sel_hi:[1,0,0]
	v_pk_add_f32 v[94:95], v[124:125], v[100:101]
	v_pk_add_f32 v[100:101], v[124:125], v[100:101] neg_lo:[0,1] neg_hi:[0,1]
	v_pk_mul_f32 v[124:125], v[100:101], s[6:7]
	v_pk_fma_f32 v[100:101], v[100:101], s[14:15], v[124:125] op_sel:[0,0,1] op_sel_hi:[1,0,0]
	v_pk_add_f32 v[124:125], v[90:91], v[136:137]
	v_pk_add_f32 v[90:91], v[90:91], v[136:137] neg_lo:[0,1] neg_hi:[0,1]
	v_pk_mul_f32 v[132:133], v[90:91], s[20:21]
	v_pk_fma_f32 v[90:91], v[90:91], s[48:49], v[132:133] op_sel:[0,0,1] op_sel_hi:[1,0,0]
	v_pk_add_f32 v[132:133], v[116:117], v[68:69]
	v_pk_add_f32 v[116:117], v[116:117], v[68:69] op_sel:[1,1] op_sel_hi:[0,0] neg_lo:[1,0] neg_hi:[0,1]
	v_pk_add_f32 v[68:69], v[118:119], v[96:97]
	v_pk_add_f32 v[96:97], v[118:119], v[96:97] neg_lo:[0,1] neg_hi:[0,1]
	v_pk_mul_f32 v[118:119], v[96:97], s[20:21]
	v_pk_fma_f32 v[96:97], v[96:97], s[18:19], v[118:119] op_sel:[0,0,1] op_sel_hi:[1,0,0]
	v_pk_add_f32 v[118:119], v[110:111], v[72:73]
	v_pk_add_f32 v[72:73], v[110:111], v[72:73] neg_lo:[0,1] neg_hi:[0,1]
	v_pk_mul_f32 v[110:111], v[72:73], s[6:7]
	v_pk_fma_f32 v[72:73], v[72:73], s[4:5], v[110:111] op_sel:[0,0,1] op_sel_hi:[1,0,0]
	v_pk_add_f32 v[110:111], v[102:103], v[76:77]
	v_pk_add_f32 v[76:77], v[102:103], v[76:77] neg_lo:[0,1] neg_hi:[0,1]
	v_pk_mul_f32 v[102:103], v[76:77], s[24:25]
	v_pk_fma_f32 v[76:77], v[76:77], s[22:23], v[102:103] op_sel:[0,0,1] op_sel_hi:[1,0,0]
	v_pk_add_f32 v[102:103], v[120:121], v[66:67]
	v_pk_add_f32 v[66:67], v[120:121], v[66:67] neg_lo:[0,1] neg_hi:[0,1]
	v_pk_mul_f32 v[120:121], v[66:67], s[10:11]
	v_pk_fma_f32 v[66:67], v[66:67], s[8:9], v[120:121] op_sel:[0,0,1] op_sel_hi:[1,0,0]
	v_pk_add_f32 v[120:121], v[126:127], v[88:89]
	v_pk_add_f32 v[88:89], v[126:127], v[88:89] neg_lo:[0,1] neg_hi:[0,1]
	v_pk_mul_f32 v[126:127], v[88:89], s[52:53]
	v_pk_fma_f32 v[88:89], v[88:89], s[26:27], v[126:127] op_sel:[0,0,1] op_sel_hi:[1,0,0]
	v_pk_add_f32 v[126:127], v[112:113], v[70:71]
	v_pk_add_f32 v[70:71], v[112:113], v[70:71] neg_lo:[0,1] neg_hi:[0,1]
	v_pk_mul_f32 v[112:113], v[70:71], s[14:15]
	v_pk_fma_f32 v[70:71], v[70:71], s[12:13], v[112:113] op_sel:[0,0,1] op_sel_hi:[1,0,0]
	v_pk_add_f32 v[112:113], v[130:131], v[78:79]
	v_pk_add_f32 v[78:79], v[130:131], v[78:79] neg_lo:[0,1] neg_hi:[0,1]
	v_pk_mul_f32 v[130:131], v[78:79], s[50:51]
	v_pk_fma_f32 v[78:79], v[78:79], s[34:35], v[130:131] op_sel:[0,0,1] op_sel_hi:[1,0,0]
	v_pk_add_f32 v[130:131], v[114:115], v[132:133]
	v_pk_add_f32 v[114:115], v[114:115], v[132:133] neg_lo:[0,1] neg_hi:[0,1]
	v_pk_add_f32 v[132:133], v[128:129], v[68:69]
	v_pk_add_f32 v[68:69], v[128:129], v[68:69] neg_lo:[0,1] neg_hi:[0,1]
	v_pk_mul_f32 v[128:129], v[68:69], s[14:15]
	v_pk_fma_f32 v[68:69], v[68:69], s[6:7], v[128:129] op_sel:[0,0,1] op_sel_hi:[1,0,0]
	v_pk_add_f32 v[128:129], v[106:107], v[118:119]
	v_pk_add_f32 v[106:107], v[106:107], v[118:119] neg_lo:[0,1] neg_hi:[0,1]
	v_pk_mul_f32 v[118:119], v[106:107], s[10:11]
	v_pk_fma_f32 v[106:107], v[106:107], s[10:11], v[118:119] op_sel:[0,0,1] op_sel_hi:[1,0,0]
	v_pk_add_f32 v[118:119], v[122:123], v[110:111]
	v_pk_add_f32 v[110:111], v[122:123], v[110:111] neg_lo:[0,1] neg_hi:[0,1]
	v_pk_mul_f32 v[122:123], v[110:111], s[6:7]
	v_pk_fma_f32 v[110:111], v[110:111], s[14:15], v[122:123] op_sel:[0,0,1] op_sel_hi:[1,0,0]
	v_pk_add_f32 v[122:123], v[84:85], v[102:103]
	v_pk_add_f32 v[102:103], v[84:85], v[102:103] op_sel:[1,1] op_sel_hi:[0,0] neg_lo:[1,0] neg_hi:[0,1]
	v_pk_add_f32 v[84:85], v[98:99], v[120:121]
	v_pk_add_f32 v[98:99], v[98:99], v[120:121] neg_lo:[0,1] neg_hi:[0,1]
	v_pk_mul_f32 v[120:121], v[98:99], s[6:7]
	v_pk_fma_f32 v[98:99], v[98:99], s[4:5], v[120:121] op_sel:[0,0,1] op_sel_hi:[1,0,0]
	v_pk_add_f32 v[120:121], v[94:95], v[126:127]
	v_pk_add_f32 v[94:95], v[94:95], v[126:127] neg_lo:[0,1] neg_hi:[0,1]
	v_pk_mul_f32 v[126:127], v[94:95], s[10:11]
	v_pk_fma_f32 v[94:95], v[94:95], s[8:9], v[126:127] op_sel:[0,0,1] op_sel_hi:[1,0,0]
	v_pk_add_f32 v[126:127], v[124:125], v[112:113]
	v_pk_add_f32 v[112:113], v[124:125], v[112:113] neg_lo:[0,1] neg_hi:[0,1]
	v_pk_mul_f32 v[124:125], v[112:113], s[14:15]
	v_pk_fma_f32 v[112:113], v[112:113], s[12:13], v[124:125] op_sel:[0,0,1] op_sel_hi:[1,0,0]
	v_pk_add_f32 v[124:125], v[80:81], v[116:117]
	v_pk_add_f32 v[80:81], v[80:81], v[116:117] neg_lo:[0,1] neg_hi:[0,1]
	v_pk_add_f32 v[116:117], v[82:83], v[96:97]
	v_pk_add_f32 v[82:83], v[82:83], v[96:97] neg_lo:[0,1] neg_hi:[0,1]
	v_pk_mul_f32 v[96:97], v[82:83], s[14:15]
	v_pk_fma_f32 v[82:83], v[82:83], s[6:7], v[96:97] op_sel:[0,0,1] op_sel_hi:[1,0,0]
	v_pk_add_f32 v[96:97], v[108:109], v[72:73]
	v_pk_add_f32 v[72:73], v[108:109], v[72:73] neg_lo:[0,1] neg_hi:[0,1]
	v_pk_mul_f32 v[108:109], v[72:73], s[10:11]
	v_pk_fma_f32 v[72:73], v[72:73], s[10:11], v[108:109] op_sel:[0,0,1] op_sel_hi:[1,0,0]
	v_pk_add_f32 v[108:109], v[74:75], v[76:77]
	v_pk_add_f32 v[74:75], v[74:75], v[76:77] neg_lo:[0,1] neg_hi:[0,1]
	v_pk_mul_f32 v[76:77], v[74:75], s[6:7]
	v_pk_fma_f32 v[74:75], v[74:75], s[14:15], v[76:77] op_sel:[0,0,1] op_sel_hi:[1,0,0]
	v_pk_add_f32 v[76:77], v[86:87], v[66:67]
	v_pk_add_f32 v[86:87], v[86:87], v[66:67] op_sel:[1,1] op_sel_hi:[0,0] neg_lo:[1,0] neg_hi:[0,1]
	v_pk_add_f32 v[66:67], v[92:93], v[88:89]
	v_pk_add_f32 v[88:89], v[92:93], v[88:89] neg_lo:[0,1] neg_hi:[0,1]
	v_pk_mul_f32 v[92:93], v[88:89], s[6:7]
	v_pk_fma_f32 v[88:89], v[88:89], s[4:5], v[92:93] op_sel:[0,0,1] op_sel_hi:[1,0,0]
	v_pk_add_f32 v[92:93], v[100:101], v[70:71]
	v_pk_add_f32 v[70:71], v[100:101], v[70:71] neg_lo:[0,1] neg_hi:[0,1]
	v_pk_mul_f32 v[100:101], v[70:71], s[10:11]
	v_pk_fma_f32 v[70:71], v[70:71], s[8:9], v[100:101] op_sel:[0,0,1] op_sel_hi:[1,0,0]
	v_pk_add_f32 v[100:101], v[90:91], v[78:79]
	v_pk_add_f32 v[78:79], v[90:91], v[78:79] neg_lo:[0,1] neg_hi:[0,1]
	v_pk_mul_f32 v[90:91], v[78:79], s[14:15]
	v_pk_fma_f32 v[78:79], v[78:79], s[12:13], v[90:91] op_sel:[0,0,1] op_sel_hi:[1,0,0]
	v_pk_add_f32 v[90:91], v[130:131], v[122:123]
	v_pk_add_f32 v[122:123], v[130:131], v[122:123] neg_lo:[0,1] neg_hi:[0,1]
	v_pk_add_f32 v[130:131], v[132:133], v[84:85]
	v_pk_add_f32 v[84:85], v[132:133], v[84:85] neg_lo:[0,1] neg_hi:[0,1]
	v_pk_mul_f32 v[132:133], v[84:85], s[10:11]
	v_pk_fma_f32 v[84:85], v[84:85], s[10:11], v[132:133] op_sel:[0,0,1] op_sel_hi:[1,0,0]
	v_pk_add_f32 v[132:133], v[128:129], v[120:121]
	v_pk_add_f32 v[128:129], v[128:129], v[120:121] op_sel:[1,1] op_sel_hi:[0,0] neg_lo:[1,0] neg_hi:[0,1]
	v_pk_add_f32 v[120:121], v[118:119], v[126:127]
	v_pk_add_f32 v[118:119], v[118:119], v[126:127] neg_lo:[0,1] neg_hi:[0,1]
	v_pk_mul_f32 v[126:127], v[118:119], s[10:11]
	v_pk_fma_f32 v[118:119], v[118:119], s[8:9], v[126:127] op_sel:[0,0,1] op_sel_hi:[1,0,0]
	v_pk_add_f32 v[126:127], v[114:115], v[102:103]
	v_pk_add_f32 v[102:103], v[114:115], v[102:103] neg_lo:[0,1] neg_hi:[0,1]
	v_pk_add_f32 v[114:115], v[68:69], v[98:99]
	v_pk_add_f32 v[68:69], v[68:69], v[98:99] neg_lo:[0,1] neg_hi:[0,1]
	v_pk_mul_f32 v[98:99], v[68:69], s[10:11]
	v_pk_fma_f32 v[68:69], v[68:69], s[10:11], v[98:99] op_sel:[0,0,1] op_sel_hi:[1,0,0]
	v_pk_add_f32 v[98:99], v[106:107], v[94:95]
	v_pk_add_f32 v[106:107], v[106:107], v[94:95] op_sel:[1,1] op_sel_hi:[0,0] neg_lo:[1,0] neg_hi:[0,1]
	v_pk_add_f32 v[94:95], v[110:111], v[112:113]
	v_pk_add_f32 v[110:111], v[110:111], v[112:113] neg_lo:[0,1] neg_hi:[0,1]
	v_pk_mul_f32 v[112:113], v[110:111], s[10:11]
	v_pk_fma_f32 v[110:111], v[110:111], s[8:9], v[112:113] op_sel:[0,0,1] op_sel_hi:[1,0,0]
	v_pk_add_f32 v[112:113], v[124:125], v[76:77]
	v_pk_add_f32 v[76:77], v[124:125], v[76:77] neg_lo:[0,1] neg_hi:[0,1]
	v_pk_add_f32 v[124:125], v[116:117], v[66:67]
	v_pk_add_f32 v[66:67], v[116:117], v[66:67] neg_lo:[0,1] neg_hi:[0,1]
	v_pk_mul_f32 v[116:117], v[66:67], s[10:11]
	v_pk_fma_f32 v[66:67], v[66:67], s[10:11], v[116:117] op_sel:[0,0,1] op_sel_hi:[1,0,0]
	v_pk_add_f32 v[116:117], v[96:97], v[92:93]
	v_pk_add_f32 v[96:97], v[96:97], v[92:93] op_sel:[1,1] op_sel_hi:[0,0] neg_lo:[1,0] neg_hi:[0,1]
	v_pk_add_f32 v[134:135], v[112:113], v[116:117]
	v_pk_add_f32 v[92:93], v[108:109], v[100:101]
	v_pk_add_f32 v[100:101], v[108:109], v[100:101] neg_lo:[0,1] neg_hi:[0,1]
	v_pk_add_f32 v[112:113], v[112:113], v[116:117] neg_lo:[0,1] neg_hi:[0,1]
	v_pk_mul_f32 v[108:109], v[100:101], s[10:11]
	v_pk_add_f32 v[116:117], v[124:125], v[92:93]
	v_pk_fma_f32 v[100:101], v[100:101], s[8:9], v[108:109] op_sel:[0,0,1] op_sel_hi:[1,0,0]
	v_pk_add_f32 v[108:109], v[80:81], v[86:87]
	v_pk_add_f32 v[80:81], v[80:81], v[86:87] neg_lo:[0,1] neg_hi:[0,1]
	v_pk_add_f32 v[86:87], v[82:83], v[88:89]
	v_pk_add_f32 v[82:83], v[82:83], v[88:89] neg_lo:[0,1] neg_hi:[0,1]
	v_pk_mul_f32 v[88:89], v[82:83], s[10:11]
	v_pk_fma_f32 v[82:83], v[82:83], s[10:11], v[88:89] op_sel:[0,0,1] op_sel_hi:[1,0,0]
	v_pk_add_f32 v[88:89], v[72:73], v[70:71]
	v_pk_add_f32 v[72:73], v[72:73], v[70:71] op_sel:[1,1] op_sel_hi:[0,0] neg_lo:[1,0] neg_hi:[0,1]
	v_pk_add_f32 v[136:137], v[108:109], v[88:89]
	v_pk_add_f32 v[70:71], v[74:75], v[78:79]
	v_pk_add_f32 v[74:75], v[74:75], v[78:79] neg_lo:[0,1] neg_hi:[0,1]
	v_pk_add_f32 v[88:89], v[108:109], v[88:89] neg_lo:[0,1] neg_hi:[0,1]
	v_pk_mul_f32 v[78:79], v[74:75], s[10:11]
	v_pk_add_f32 v[108:109], v[86:87], v[70:71]
	v_pk_fma_f32 v[74:75], v[74:75], s[8:9], v[78:79] op_sel:[0,0,1] op_sel_hi:[1,0,0]
	v_pk_add_f32 v[78:79], v[90:91], v[132:133]
	v_pk_add_f32 v[90:91], v[90:91], v[132:133] neg_lo:[0,1] neg_hi:[0,1]
	v_pk_add_f32 v[132:133], v[130:131], v[120:121]
	v_pk_add_f32 v[130:131], v[130:131], v[120:121] op_sel:[1,1] op_sel_hi:[0,0] neg_lo:[1,0] neg_hi:[0,1]
	v_pk_add_f32 v[138:139], v[80:81], v[72:73] neg_lo:[0,1] neg_hi:[0,1]
	v_pk_add_f32 v[120:121], v[122:123], v[128:129]
	v_pk_add_f32 v[122:123], v[122:123], v[128:129] neg_lo:[0,1] neg_hi:[0,1]
	v_pk_add_f32 v[128:129], v[84:85], v[118:119]
	v_pk_add_f32 v[118:119], v[84:85], v[118:119] op_sel:[1,1] op_sel_hi:[0,0] neg_lo:[1,0] neg_hi:[0,1]
	v_pk_add_f32 v[140:141], v[82:83], v[74:75]
	v_pk_add_f32 v[84:85], v[126:127], v[98:99]
	v_pk_add_f32 v[98:99], v[126:127], v[98:99] neg_lo:[0,1] neg_hi:[0,1]
	v_pk_add_f32 v[126:127], v[114:115], v[94:95]
	v_pk_add_f32 v[114:115], v[114:115], v[94:95] op_sel:[1,1] op_sel_hi:[0,0] neg_lo:[1,0] neg_hi:[0,1]
	v_pk_add_f32 v[142:143], v[78:79], v[132:133]
	v_pk_add_f32 v[94:95], v[102:103], v[106:107]
	v_pk_add_f32 v[102:103], v[102:103], v[106:107] neg_lo:[0,1] neg_hi:[0,1]
	v_pk_add_f32 v[106:107], v[68:69], v[110:111]
	v_pk_add_f32 v[110:111], v[68:69], v[110:111] op_sel:[1,1] op_sel_hi:[0,0] neg_lo:[1,0] neg_hi:[0,1]
	v_pk_add_f32 v[132:133], v[78:79], v[132:133] neg_lo:[0,1] neg_hi:[0,1]
	v_pk_add_f32 v[92:93], v[124:125], v[92:93] op_sel:[1,1] op_sel_hi:[0,0] neg_lo:[1,0] neg_hi:[0,1]
	v_pk_add_f32 v[124:125], v[76:77], v[96:97]
	v_pk_add_f32 v[76:77], v[76:77], v[96:97] neg_lo:[0,1] neg_hi:[0,1]
	v_pk_add_f32 v[96:97], v[66:67], v[100:101]
	v_pk_add_f32 v[100:101], v[66:67], v[100:101] op_sel:[1,1] op_sel_hi:[0,0] neg_lo:[1,0] neg_hi:[0,1]
	v_pk_add_f32 v[70:71], v[86:87], v[70:71] op_sel:[1,1] op_sel_hi:[0,0] neg_lo:[1,0] neg_hi:[0,1]
	v_pk_add_f32 v[74:75], v[82:83], v[74:75] op_sel:[1,1] op_sel_hi:[0,0] neg_lo:[1,0] neg_hi:[0,1]
	v_pk_add_f32 v[86:87], v[80:81], v[72:73]
	v_pk_add_f32 v[144:145], v[90:91], v[130:131]
	v_pk_add_f32 v[82:83], v[90:91], v[130:131] neg_lo:[0,1] neg_hi:[0,1]
	v_pk_add_f32 v[90:91], v[120:121], v[128:129]
	v_pk_add_f32 v[120:121], v[120:121], v[128:129] neg_lo:[0,1] neg_hi:[0,1]
	v_pk_add_f32 v[128:129], v[122:123], v[118:119]
	v_pk_add_f32 v[68:69], v[122:123], v[118:119] neg_lo:[0,1] neg_hi:[0,1]
	v_pk_add_f32 v[118:119], v[84:85], v[126:127]
	v_pk_add_f32 v[122:123], v[84:85], v[126:127] neg_lo:[0,1] neg_hi:[0,1]
	v_pk_add_f32 v[126:127], v[98:99], v[114:115]
	v_pk_add_f32 v[78:79], v[98:99], v[114:115] neg_lo:[0,1] neg_hi:[0,1]
	v_pk_add_f32 v[98:99], v[94:95], v[106:107]
	v_pk_add_f32 v[94:95], v[94:95], v[106:107] neg_lo:[0,1] neg_hi:[0,1]
	v_pk_add_f32 v[106:107], v[102:103], v[110:111]
	v_pk_add_f32 v[66:67], v[102:103], v[110:111] neg_lo:[0,1] neg_hi:[0,1]
	v_pk_add_f32 v[102:103], v[134:135], v[116:117]
	v_pk_add_f32 v[110:111], v[134:135], v[116:117] neg_lo:[0,1] neg_hi:[0,1]
	v_pk_add_f32 v[116:117], v[88:89], v[70:71]
	v_pk_add_f32 v[80:81], v[88:89], v[70:71] neg_lo:[0,1] neg_hi:[0,1]
	v_lshlrev_b32_e32 v70, 4, v0
	v_and_b32_e32 v70, 0x1f0, v70
	v_pk_add_f32 v[114:115], v[112:113], v[92:93]
	v_pk_add_f32 v[84:85], v[112:113], v[92:93] neg_lo:[0,1] neg_hi:[0,1]
	v_pk_add_f32 v[112:113], v[76:77], v[100:101]
	v_pk_add_f32 v[72:73], v[76:77], v[100:101] neg_lo:[0,1] neg_hi:[0,1]
	v_cvt_f32_u32_e32 v76, v70
	v_pk_add_f32 v[92:93], v[124:125], v[96:97]
	v_pk_add_f32 v[96:97], v[124:125], v[96:97] neg_lo:[0,1] neg_hi:[0,1]
	v_pk_add_f32 v[124:125], v[138:139], v[74:75]
	v_mul_f32_e32 v76, 0x38800000, v76
	v_pk_add_f32 v[70:71], v[138:139], v[74:75] neg_lo:[0,1] neg_hi:[0,1]
	v_sin_f32_e32 v75, v76
	v_ashrrev_i32_e32 v74, 2, v105
	v_lshlrev_b32_e32 v0, 8, v0
	v_add3_u32 v0, 0, v74, v0
	v_cos_f32_e32 v74, v76
	v_xor_b32_e32 v76, 0x80000000, v75
	v_mov_b32_e32 v77, v75
	v_pk_mul_f32 v[130:131], v[76:77], v[102:103] op_sel:[0,1] op_sel_hi:[1,0]
	v_pk_add_f32 v[100:101], v[136:137], v[108:109]
	v_pk_fma_f32 v[102:103], v[102:103], v[74:75], v[130:131] op_sel_hi:[1,0,1]
	ds_write2_b64 v0, v[142:143], v[102:103] offset1:1
	v_pk_mul_f32 v[102:103], v[76:77], v[74:75] op_sel:[0,1] op_sel_hi:[1,0]
	v_pk_add_f32 v[88:89], v[86:87], v[140:141]
	v_pk_fma_f32 v[102:103], v[74:75], v[74:75], v[102:103] op_sel_hi:[1,0,1]
	v_pk_add_f32 v[108:109], v[136:137], v[108:109] neg_lo:[0,1] neg_hi:[0,1]
	v_pk_mul_f32 v[130:131], v[118:119], v[102:103] op_sel:[1,1] op_sel_hi:[0,1] neg_lo:[0,1]
	v_pk_fma_f32 v[118:119], v[118:119], v[102:103], v[130:131] op_sel_hi:[1,0,1]
	v_pk_mul_f32 v[130:131], v[76:77], v[102:103] op_sel:[0,1] op_sel_hi:[1,0]
	v_pk_add_f32 v[86:87], v[86:87], v[140:141] neg_lo:[0,1] neg_hi:[0,1]
	v_pk_fma_f32 v[102:103], v[102:103], v[74:75], v[130:131] op_sel_hi:[1,0,1]
	v_pk_mul_f32 v[130:131], v[100:101], v[102:103] op_sel:[1,1] op_sel_hi:[0,1] neg_lo:[0,1]
	v_pk_fma_f32 v[100:101], v[100:101], v[102:103], v[130:131] op_sel_hi:[1,0,1]
	ds_write2_b64 v0, v[118:119], v[100:101] offset0:2 offset1:3
	v_pk_mul_f32 v[100:101], v[76:77], v[102:103] op_sel:[0,1] op_sel_hi:[1,0]
	v_pk_fma_f32 v[100:101], v[102:103], v[74:75], v[100:101] op_sel_hi:[1,0,1]
	v_pk_mul_f32 v[102:103], v[90:91], v[100:101] op_sel:[1,1] op_sel_hi:[0,1] neg_lo:[0,1]
	v_pk_fma_f32 v[90:91], v[90:91], v[100:101], v[102:103] op_sel_hi:[1,0,1]
	v_pk_mul_f32 v[102:103], v[76:77], v[100:101] op_sel:[0,1] op_sel_hi:[1,0]
	v_pk_fma_f32 v[100:101], v[100:101], v[74:75], v[102:103] op_sel_hi:[1,0,1]
	v_pk_mul_f32 v[102:103], v[92:93], v[100:101] op_sel:[1,1] op_sel_hi:[0,1] neg_lo:[0,1]
	v_pk_fma_f32 v[92:93], v[92:93], v[100:101], v[102:103] op_sel_hi:[1,0,1]
	ds_write2_b64 v0, v[90:91], v[92:93] offset0:4 offset1:5
	v_pk_mul_f32 v[90:91], v[76:77], v[100:101] op_sel:[0,1] op_sel_hi:[1,0]
	v_pk_fma_f32 v[90:91], v[100:101], v[74:75], v[90:91] op_sel_hi:[1,0,1]
	v_pk_mul_f32 v[92:93], v[98:99], v[90:91] op_sel:[1,1] op_sel_hi:[0,1] neg_lo:[0,1]
	v_pk_fma_f32 v[92:93], v[98:99], v[90:91], v[92:93] op_sel_hi:[1,0,1]
	v_pk_mul_f32 v[98:99], v[76:77], v[90:91] op_sel:[0,1] op_sel_hi:[1,0]
	v_pk_fma_f32 v[90:91], v[90:91], v[74:75], v[98:99] op_sel_hi:[1,0,1]
	v_pk_mul_f32 v[98:99], v[88:89], v[90:91] op_sel:[1,1] op_sel_hi:[0,1] neg_lo:[0,1]
	v_pk_fma_f32 v[88:89], v[88:89], v[90:91], v[98:99] op_sel_hi:[1,0,1]
	ds_write2_b64 v0, v[92:93], v[88:89] offset0:6 offset1:7
	v_pk_mul_f32 v[88:89], v[76:77], v[90:91] op_sel:[0,1] op_sel_hi:[1,0]
	v_pk_fma_f32 v[88:89], v[90:91], v[74:75], v[88:89] op_sel_hi:[1,0,1]
	v_pk_mul_f32 v[90:91], v[144:145], v[88:89] op_sel:[1,1] op_sel_hi:[0,1] neg_lo:[0,1]
	v_pk_mul_f32 v[92:93], v[76:77], v[88:89] op_sel:[0,1] op_sel_hi:[1,0]
	v_pk_fma_f32 v[90:91], v[144:145], v[88:89], v[90:91] op_sel_hi:[1,0,1]
	v_pk_fma_f32 v[88:89], v[88:89], v[74:75], v[92:93] op_sel_hi:[1,0,1]
	v_pk_mul_f32 v[92:93], v[114:115], v[88:89] op_sel:[1,1] op_sel_hi:[0,1] neg_lo:[0,1]
	v_pk_fma_f32 v[92:93], v[114:115], v[88:89], v[92:93] op_sel_hi:[1,0,1]
	ds_write2_b64 v0, v[90:91], v[92:93] offset0:8 offset1:9
	v_pk_mul_f32 v[90:91], v[76:77], v[88:89] op_sel:[0,1] op_sel_hi:[1,0]
	v_pk_fma_f32 v[88:89], v[88:89], v[74:75], v[90:91] op_sel_hi:[1,0,1]
	v_pk_mul_f32 v[90:91], v[126:127], v[88:89] op_sel:[1,1] op_sel_hi:[0,1] neg_lo:[0,1]
	v_pk_mul_f32 v[92:93], v[76:77], v[88:89] op_sel:[0,1] op_sel_hi:[1,0]
	v_pk_fma_f32 v[90:91], v[126:127], v[88:89], v[90:91] op_sel_hi:[1,0,1]
	v_pk_fma_f32 v[88:89], v[88:89], v[74:75], v[92:93] op_sel_hi:[1,0,1]
	v_pk_mul_f32 v[92:93], v[116:117], v[88:89] op_sel:[1,1] op_sel_hi:[0,1] neg_lo:[0,1]
	v_pk_fma_f32 v[92:93], v[116:117], v[88:89], v[92:93] op_sel_hi:[1,0,1]
	ds_write2_b64 v0, v[90:91], v[92:93] offset0:10 offset1:11
	v_pk_mul_f32 v[90:91], v[76:77], v[88:89] op_sel:[0,1] op_sel_hi:[1,0]
	v_pk_fma_f32 v[88:89], v[88:89], v[74:75], v[90:91] op_sel_hi:[1,0,1]
	v_pk_mul_f32 v[90:91], v[128:129], v[88:89] op_sel:[1,1] op_sel_hi:[0,1] neg_lo:[0,1]
	v_pk_mul_f32 v[92:93], v[76:77], v[88:89] op_sel:[0,1] op_sel_hi:[1,0]
	v_pk_fma_f32 v[90:91], v[128:129], v[88:89], v[90:91] op_sel_hi:[1,0,1]
	v_pk_fma_f32 v[88:89], v[88:89], v[74:75], v[92:93] op_sel_hi:[1,0,1]
	v_pk_mul_f32 v[92:93], v[112:113], v[88:89] op_sel:[1,1] op_sel_hi:[0,1] neg_lo:[0,1]
	v_pk_fma_f32 v[92:93], v[112:113], v[88:89], v[92:93] op_sel_hi:[1,0,1]
	ds_write2_b64 v0, v[90:91], v[92:93] offset0:12 offset1:13
	v_pk_mul_f32 v[90:91], v[76:77], v[88:89] op_sel:[0,1] op_sel_hi:[1,0]
	v_pk_fma_f32 v[88:89], v[88:89], v[74:75], v[90:91] op_sel_hi:[1,0,1]
	v_pk_mul_f32 v[90:91], v[106:107], v[88:89] op_sel:[1,1] op_sel_hi:[0,1] neg_lo:[0,1]
	v_pk_mul_f32 v[92:93], v[76:77], v[88:89] op_sel:[0,1] op_sel_hi:[1,0]
	v_pk_fma_f32 v[90:91], v[106:107], v[88:89], v[90:91] op_sel_hi:[1,0,1]
	v_pk_fma_f32 v[88:89], v[88:89], v[74:75], v[92:93] op_sel_hi:[1,0,1]
	v_pk_mul_f32 v[92:93], v[124:125], v[88:89] op_sel:[1,1] op_sel_hi:[0,1] neg_lo:[0,1]
	v_pk_fma_f32 v[92:93], v[124:125], v[88:89], v[92:93] op_sel_hi:[1,0,1]
	ds_write2_b64 v0, v[90:91], v[92:93] offset0:14 offset1:15
	v_pk_mul_f32 v[90:91], v[76:77], v[88:89] op_sel:[0,1] op_sel_hi:[1,0]
	v_pk_fma_f32 v[88:89], v[88:89], v[74:75], v[90:91] op_sel_hi:[1,0,1]
	v_pk_mul_f32 v[90:91], v[132:133], v[88:89] op_sel:[1,1] op_sel_hi:[0,1] neg_lo:[0,1]
	v_pk_mul_f32 v[92:93], v[76:77], v[88:89] op_sel:[0,1] op_sel_hi:[1,0]
	v_pk_fma_f32 v[90:91], v[132:133], v[88:89], v[90:91] op_sel_hi:[1,0,1]
	v_pk_fma_f32 v[88:89], v[88:89], v[74:75], v[92:93] op_sel_hi:[1,0,1]
	v_pk_mul_f32 v[92:93], v[110:111], v[88:89] op_sel:[1,1] op_sel_hi:[0,1] neg_lo:[0,1]
	v_pk_fma_f32 v[92:93], v[110:111], v[88:89], v[92:93] op_sel_hi:[1,0,1]
	ds_write2_b64 v0, v[90:91], v[92:93] offset0:16 offset1:17
	v_pk_mul_f32 v[90:91], v[76:77], v[88:89] op_sel:[0,1] op_sel_hi:[1,0]
	v_pk_fma_f32 v[88:89], v[88:89], v[74:75], v[90:91] op_sel_hi:[1,0,1]
	v_pk_mul_f32 v[90:91], v[122:123], v[88:89] op_sel:[1,1] op_sel_hi:[0,1] neg_lo:[0,1]
	v_pk_mul_f32 v[92:93], v[76:77], v[88:89] op_sel:[0,1] op_sel_hi:[1,0]
	v_pk_fma_f32 v[90:91], v[122:123], v[88:89], v[90:91] op_sel_hi:[1,0,1]
	v_pk_fma_f32 v[88:89], v[88:89], v[74:75], v[92:93] op_sel_hi:[1,0,1]
	v_pk_mul_f32 v[92:93], v[108:109], v[88:89] op_sel:[1,1] op_sel_hi:[0,1] neg_lo:[0,1]
	v_pk_fma_f32 v[92:93], v[108:109], v[88:89], v[92:93] op_sel_hi:[1,0,1]
	ds_write2_b64 v0, v[90:91], v[92:93] offset0:18 offset1:19
	v_pk_mul_f32 v[90:91], v[76:77], v[88:89] op_sel:[0,1] op_sel_hi:[1,0]
	v_pk_fma_f32 v[88:89], v[88:89], v[74:75], v[90:91] op_sel_hi:[1,0,1]
	v_pk_mul_f32 v[90:91], v[120:121], v[88:89] op_sel:[1,1] op_sel_hi:[0,1] neg_lo:[0,1]
	v_pk_mul_f32 v[92:93], v[76:77], v[88:89] op_sel:[0,1] op_sel_hi:[1,0]
	v_pk_fma_f32 v[90:91], v[120:121], v[88:89], v[90:91] op_sel_hi:[1,0,1]
	v_pk_fma_f32 v[88:89], v[88:89], v[74:75], v[92:93] op_sel_hi:[1,0,1]
	v_pk_mul_f32 v[92:93], v[96:97], v[88:89] op_sel:[1,1] op_sel_hi:[0,1] neg_lo:[0,1]
	v_pk_fma_f32 v[92:93], v[96:97], v[88:89], v[92:93] op_sel_hi:[1,0,1]
	ds_write2_b64 v0, v[90:91], v[92:93] offset0:20 offset1:21
	v_pk_mul_f32 v[90:91], v[76:77], v[88:89] op_sel:[0,1] op_sel_hi:[1,0]
	v_pk_fma_f32 v[88:89], v[88:89], v[74:75], v[90:91] op_sel_hi:[1,0,1]
	v_pk_mul_f32 v[90:91], v[94:95], v[88:89] op_sel:[1,1] op_sel_hi:[0,1] neg_lo:[0,1]
	v_pk_mul_f32 v[92:93], v[76:77], v[88:89] op_sel:[0,1] op_sel_hi:[1,0]
	v_pk_fma_f32 v[90:91], v[94:95], v[88:89], v[90:91] op_sel_hi:[1,0,1]
	v_pk_fma_f32 v[88:89], v[88:89], v[74:75], v[92:93] op_sel_hi:[1,0,1]
	v_pk_mul_f32 v[92:93], v[86:87], v[88:89] op_sel:[1,1] op_sel_hi:[0,1] neg_lo:[0,1]
	v_pk_fma_f32 v[86:87], v[86:87], v[88:89], v[92:93] op_sel_hi:[1,0,1]
	ds_write2_b64 v0, v[90:91], v[86:87] offset0:22 offset1:23
	v_pk_mul_f32 v[86:87], v[76:77], v[88:89] op_sel:[0,1] op_sel_hi:[1,0]
	v_pk_fma_f32 v[86:87], v[88:89], v[74:75], v[86:87] op_sel_hi:[1,0,1]
	v_pk_mul_f32 v[88:89], v[82:83], v[86:87] op_sel:[1,1] op_sel_hi:[0,1] neg_lo:[0,1]
	v_pk_fma_f32 v[82:83], v[82:83], v[86:87], v[88:89] op_sel_hi:[1,0,1]
	v_pk_mul_f32 v[88:89], v[76:77], v[86:87] op_sel:[0,1] op_sel_hi:[1,0]
	v_pk_fma_f32 v[86:87], v[86:87], v[74:75], v[88:89] op_sel_hi:[1,0,1]
	v_pk_mul_f32 v[88:89], v[84:85], v[86:87] op_sel:[1,1] op_sel_hi:[0,1] neg_lo:[0,1]
	v_pk_fma_f32 v[84:85], v[84:85], v[86:87], v[88:89] op_sel_hi:[1,0,1]
	ds_write2_b64 v0, v[82:83], v[84:85] offset0:24 offset1:25
	v_pk_mul_f32 v[82:83], v[76:77], v[86:87] op_sel:[0,1] op_sel_hi:[1,0]
	v_pk_fma_f32 v[82:83], v[86:87], v[74:75], v[82:83] op_sel_hi:[1,0,1]
	v_pk_mul_f32 v[84:85], v[78:79], v[82:83] op_sel:[1,1] op_sel_hi:[0,1] neg_lo:[0,1]
	v_pk_fma_f32 v[78:79], v[78:79], v[82:83], v[84:85] op_sel_hi:[1,0,1]
	v_pk_mul_f32 v[84:85], v[76:77], v[82:83] op_sel:[0,1] op_sel_hi:[1,0]
	v_pk_fma_f32 v[82:83], v[82:83], v[74:75], v[84:85] op_sel_hi:[1,0,1]
	v_pk_mul_f32 v[84:85], v[80:81], v[82:83] op_sel:[1,1] op_sel_hi:[0,1] neg_lo:[0,1]
	v_pk_fma_f32 v[80:81], v[80:81], v[82:83], v[84:85] op_sel_hi:[1,0,1]
	ds_write2_b64 v0, v[78:79], v[80:81] offset0:26 offset1:27
	v_pk_mul_f32 v[78:79], v[76:77], v[82:83] op_sel:[0,1] op_sel_hi:[1,0]
	v_pk_fma_f32 v[78:79], v[82:83], v[74:75], v[78:79] op_sel_hi:[1,0,1]
	v_pk_mul_f32 v[80:81], v[68:69], v[78:79] op_sel:[1,1] op_sel_hi:[0,1] neg_lo:[0,1]
	v_pk_fma_f32 v[68:69], v[68:69], v[78:79], v[80:81] op_sel_hi:[1,0,1]
	v_pk_mul_f32 v[80:81], v[76:77], v[78:79] op_sel:[0,1] op_sel_hi:[1,0]
	v_pk_fma_f32 v[78:79], v[78:79], v[74:75], v[80:81] op_sel_hi:[1,0,1]
	v_pk_mul_f32 v[80:81], v[72:73], v[78:79] op_sel:[1,1] op_sel_hi:[0,1] neg_lo:[0,1]
	v_pk_fma_f32 v[72:73], v[72:73], v[78:79], v[80:81] op_sel_hi:[1,0,1]
	ds_write2_b64 v0, v[68:69], v[72:73] offset0:28 offset1:29
	v_pk_mul_f32 v[68:69], v[76:77], v[78:79] op_sel:[0,1] op_sel_hi:[1,0]
	v_pk_fma_f32 v[68:69], v[78:79], v[74:75], v[68:69] op_sel_hi:[1,0,1]
	v_pk_mul_f32 v[72:73], v[66:67], v[68:69] op_sel:[1,1] op_sel_hi:[0,1] neg_lo:[0,1]
	v_pk_fma_f32 v[66:67], v[66:67], v[68:69], v[72:73] op_sel_hi:[1,0,1]
	v_pk_mul_f32 v[72:73], v[76:77], v[68:69] op_sel:[0,1] op_sel_hi:[1,0]
	v_pk_fma_f32 v[68:69], v[68:69], v[74:75], v[72:73] op_sel_hi:[1,0,1]
	v_pk_mul_f32 v[72:73], v[70:71], v[68:69] op_sel:[1,1] op_sel_hi:[0,1] neg_lo:[0,1]
	v_pk_fma_f32 v[68:69], v[70:71], v[68:69], v[72:73] op_sel_hi:[1,0,1]
	ds_write2_b64 v0, v[66:67], v[68:69] offset0:30 offset1:31
	s_waitcnt lgkmcnt(0)
	s_barrier
	v_mov_b32 v0, 0
	s_nop 0
	v_add_u32_e32 v71, v0, v170
	v_ashrrev_i32_e32 v105, 5, v71
	v_lshlrev_b32_e32 v0, 10, v105
	v_and_b32_e32 v140, 31, v71
	v_ashrrev_i32_e32 v0, 2, v0
	v_lshlrev_b32_e32 v67, 13, v105
	v_lshlrev_b32_e32 v68, 3, v140
	v_add_u32_e32 v0, 0, v0
	v_lshl_add_u32 v66, v105, 8, 0
	v_add3_u32 v0, v0, v67, v68
	v_add3_u32 v142, v66, v67, v68
	v_add_u32_e32 v143, 0x400, v0
	v_add_u32_e32 v144, 0x800, v0
	v_add_u32_e32 v145, 0xc00, v0
	ds_read_b64 v[130:131], v142
	ds_read2_b64 v[66:69], v0 offset0:33 offset1:66
	ds_read2_b64 v[72:75], v0 offset0:99 offset1:132
	ds_read2_b64 v[76:79], v0 offset0:165 offset1:198
	ds_read2_b64 v[80:83], v143 offset0:103 offset1:136
	ds_read2_b64 v[84:87], v144 offset0:41 offset1:74
	ds_read2_b64 v[88:91], v144 offset0:107 offset1:140
	ds_read2_b64 v[92:95], v144 offset0:173 offset1:206
	ds_read2_b64 v[96:99], v145 offset0:111 offset1:144
	v_add_u32_e32 v146, 0x1000, v0
	ds_read2_b64 v[100:103], v146 offset0:49 offset1:82
	ds_read2_b64 v[106:109], v146 offset0:115 offset1:148
	ds_read2_b64 v[110:113], v146 offset0:181 offset1:214
	v_add_u32_e32 v147, 0x1400, v0
	ds_read2_b64 v[114:117], v147 offset0:119 offset1:152
	s_waitcnt lgkmcnt(4)
	v_pk_add_f32 v[134:135], v[130:131], v[98:99]
	v_pk_add_f32 v[98:99], v[130:131], v[98:99] neg_lo:[0,1] neg_hi:[0,1]
	s_waitcnt lgkmcnt(3)
	v_pk_add_f32 v[130:131], v[66:67], v[100:101]
	v_pk_add_f32 v[66:67], v[66:67], v[100:101] neg_lo:[0,1] neg_hi:[0,1]
	v_add_u32_e32 v70, 0x1800, v0
	v_pk_mul_f32 v[100:101], v[66:67], s[50:51]
	ds_read2_b64 v[118:121], v70 offset0:57 offset1:90
	ds_read2_b64 v[122:125], v70 offset0:123 offset1:156
	ds_read2_b64 v[126:129], v70 offset0:189 offset1:222
	ds_read_b64 v[132:133], v0 offset:8184
	v_pk_fma_f32 v[66:67], v[66:67], s[20:21], v[100:101] op_sel:[0,0,1] op_sel_hi:[1,0,0]
	v_pk_add_f32 v[100:101], v[68:69], v[102:103]
	v_pk_add_f32 v[68:69], v[68:69], v[102:103] neg_lo:[0,1] neg_hi:[0,1]
	v_mul_lo_u32 v105, v140, v105
	v_pk_mul_f32 v[102:103], v[68:69], s[14:15]
	v_cvt_f32_i32_e32 v105, v105
	v_pk_fma_f32 v[68:69], v[68:69], s[6:7], v[102:103] op_sel:[0,0,1] op_sel_hi:[1,0,0]
	s_waitcnt lgkmcnt(6)
	v_pk_add_f32 v[102:103], v[72:73], v[106:107]
	v_pk_add_f32 v[72:73], v[72:73], v[106:107] neg_lo:[0,1] neg_hi:[0,1]
	v_and_b32_e32 v71, 0xffffffe0, v71
	v_pk_mul_f32 v[106:107], v[72:73], s[52:53]
	v_cvt_f32_i32_e32 v71, v71
	v_pk_fma_f32 v[72:73], v[72:73], s[24:25], v[106:107] op_sel:[0,0,1] op_sel_hi:[1,0,0]
	v_pk_add_f32 v[106:107], v[74:75], v[108:109]
	v_pk_add_f32 v[74:75], v[74:75], v[108:109] neg_lo:[0,1] neg_hi:[0,1]
	v_mul_f32_e32 v71, 0x38800000, v71
	v_pk_mul_f32 v[108:109], v[74:75], s[10:11]
	s_nop 0
	v_pk_fma_f32 v[74:75], v[74:75], s[10:11], v[108:109] op_sel:[0,0,1] op_sel_hi:[1,0,0]
	s_waitcnt lgkmcnt(5)
	v_pk_add_f32 v[108:109], v[76:77], v[110:111]
	v_pk_add_f32 v[76:77], v[76:77], v[110:111] neg_lo:[0,1] neg_hi:[0,1]
	v_pk_mul_f32 v[110:111], v[76:77], s[24:25]
	v_pk_fma_f32 v[76:77], v[76:77], s[0:1], v[110:111] op_sel:[0,0,1] op_sel_hi:[1,0,0]
	v_pk_add_f32 v[110:111], v[78:79], v[112:113]
	v_pk_add_f32 v[78:79], v[78:79], v[112:113] neg_lo:[0,1] neg_hi:[0,1]
	v_pk_mul_f32 v[112:113], v[78:79], s[6:7]
	v_pk_fma_f32 v[78:79], v[78:79], s[14:15], v[112:113] op_sel:[0,0,1] op_sel_hi:[1,0,0]
	s_waitcnt lgkmcnt(4)
	v_pk_add_f32 v[112:113], v[80:81], v[114:115]
	v_pk_add_f32 v[80:81], v[80:81], v[114:115] neg_lo:[0,1] neg_hi:[0,1]
	v_pk_mul_f32 v[114:115], v[80:81], s[20:21]
	v_pk_fma_f32 v[80:81], v[80:81], s[48:49], v[114:115] op_sel:[0,0,1] op_sel_hi:[1,0,0]
	v_pk_add_f32 v[114:115], v[82:83], v[116:117]
	v_pk_add_f32 v[116:117], v[82:83], v[116:117] op_sel:[1,1] op_sel_hi:[0,0] neg_lo:[1,0] neg_hi:[0,1]
	s_mov_b64 s[48:49], -1
	s_waitcnt lgkmcnt(3)
	v_pk_add_f32 v[82:83], v[84:85], v[118:119]
	v_pk_add_f32 v[84:85], v[84:85], v[118:119] neg_lo:[0,1] neg_hi:[0,1]
	v_pk_mul_f32 v[118:119], v[84:85], s[20:21]
	v_pk_fma_f32 v[84:85], v[84:85], s[18:19], v[118:119] op_sel:[0,0,1] op_sel_hi:[1,0,0]
	v_pk_add_f32 v[118:119], v[86:87], v[120:121]
	v_pk_add_f32 v[86:87], v[86:87], v[120:121] neg_lo:[0,1] neg_hi:[0,1]
	v_pk_mul_f32 v[120:121], v[86:87], s[6:7]
	v_pk_fma_f32 v[86:87], v[86:87], s[4:5], v[120:121] op_sel:[0,0,1] op_sel_hi:[1,0,0]
	s_waitcnt lgkmcnt(2)
	v_pk_add_f32 v[120:121], v[88:89], v[122:123]
	v_pk_add_f32 v[88:89], v[88:89], v[122:123] neg_lo:[0,1] neg_hi:[0,1]
	v_pk_mul_f32 v[122:123], v[88:89], s[24:25]
	v_pk_fma_f32 v[88:89], v[88:89], s[22:23], v[122:123] op_sel:[0,0,1] op_sel_hi:[1,0,0]
	v_pk_add_f32 v[122:123], v[90:91], v[124:125]
	v_pk_add_f32 v[90:91], v[90:91], v[124:125] neg_lo:[0,1] neg_hi:[0,1]
	v_pk_mul_f32 v[124:125], v[90:91], s[10:11]
	v_pk_fma_f32 v[90:91], v[90:91], s[8:9], v[124:125] op_sel:[0,0,1] op_sel_hi:[1,0,0]
	s_waitcnt lgkmcnt(1)
	v_pk_add_f32 v[124:125], v[92:93], v[126:127]
	v_pk_add_f32 v[92:93], v[92:93], v[126:127] neg_lo:[0,1] neg_hi:[0,1]
	v_pk_mul_f32 v[126:127], v[92:93], s[52:53]
	v_pk_fma_f32 v[92:93], v[92:93], s[26:27], v[126:127] op_sel:[0,0,1] op_sel_hi:[1,0,0]
	v_pk_add_f32 v[126:127], v[94:95], v[128:129]
	v_pk_add_f32 v[94:95], v[94:95], v[128:129] neg_lo:[0,1] neg_hi:[0,1]
	v_pk_mul_f32 v[128:129], v[94:95], s[14:15]
	v_pk_fma_f32 v[94:95], v[94:95], s[12:13], v[128:129] op_sel:[0,0,1] op_sel_hi:[1,0,0]
	s_waitcnt lgkmcnt(0)
	v_pk_add_f32 v[128:129], v[96:97], v[132:133]
	v_pk_add_f32 v[96:97], v[96:97], v[132:133] neg_lo:[0,1] neg_hi:[0,1]
	v_pk_mul_f32 v[132:133], v[96:97], s[50:51]
	v_pk_fma_f32 v[96:97], v[96:97], s[34:35], v[132:133] op_sel:[0,0,1] op_sel_hi:[1,0,0]
	v_pk_add_f32 v[132:133], v[134:135], v[114:115]
	v_pk_add_f32 v[114:115], v[134:135], v[114:115] neg_lo:[0,1] neg_hi:[0,1]
	v_pk_add_f32 v[134:135], v[130:131], v[82:83]
	v_pk_add_f32 v[82:83], v[130:131], v[82:83] neg_lo:[0,1] neg_hi:[0,1]
	v_pk_mul_f32 v[130:131], v[82:83], s[14:15]
	v_pk_fma_f32 v[82:83], v[82:83], s[6:7], v[130:131] op_sel:[0,0,1] op_sel_hi:[1,0,0]
	v_pk_add_f32 v[130:131], v[100:101], v[118:119]
	v_pk_add_f32 v[100:101], v[100:101], v[118:119] neg_lo:[0,1] neg_hi:[0,1]
	v_pk_mul_f32 v[118:119], v[100:101], s[10:11]
	v_pk_fma_f32 v[100:101], v[100:101], s[10:11], v[118:119] op_sel:[0,0,1] op_sel_hi:[1,0,0]
	v_pk_add_f32 v[118:119], v[102:103], v[120:121]
	v_pk_add_f32 v[102:103], v[102:103], v[120:121] neg_lo:[0,1] neg_hi:[0,1]
	v_pk_mul_f32 v[120:121], v[102:103], s[6:7]
	v_pk_fma_f32 v[102:103], v[102:103], s[14:15], v[120:121] op_sel:[0,0,1] op_sel_hi:[1,0,0]
	v_pk_add_f32 v[120:121], v[106:107], v[122:123]
	v_pk_add_f32 v[122:123], v[106:107], v[122:123] op_sel:[1,1] op_sel_hi:[0,0] neg_lo:[1,0] neg_hi:[0,1]
	v_pk_add_f32 v[106:107], v[108:109], v[124:125]
	v_pk_add_f32 v[108:109], v[108:109], v[124:125] neg_lo:[0,1] neg_hi:[0,1]
	v_pk_mul_f32 v[124:125], v[108:109], s[6:7]
	v_pk_fma_f32 v[108:109], v[108:109], s[4:5], v[124:125] op_sel:[0,0,1] op_sel_hi:[1,0,0]
	v_pk_add_f32 v[124:125], v[110:111], v[126:127]
	v_pk_add_f32 v[110:111], v[110:111], v[126:127] neg_lo:[0,1] neg_hi:[0,1]
	v_pk_mul_f32 v[126:127], v[110:111], s[10:11]
	v_pk_fma_f32 v[110:111], v[110:111], s[8:9], v[126:127] op_sel:[0,0,1] op_sel_hi:[1,0,0]
	v_pk_add_f32 v[126:127], v[112:113], v[128:129]
	v_pk_add_f32 v[112:113], v[112:113], v[128:129] neg_lo:[0,1] neg_hi:[0,1]
	v_pk_mul_f32 v[128:129], v[112:113], s[14:15]
	v_pk_fma_f32 v[112:113], v[112:113], s[12:13], v[128:129] op_sel:[0,0,1] op_sel_hi:[1,0,0]
	v_pk_add_f32 v[128:129], v[98:99], v[116:117]
	v_pk_add_f32 v[98:99], v[98:99], v[116:117] neg_lo:[0,1] neg_hi:[0,1]
	v_pk_add_f32 v[116:117], v[66:67], v[84:85]
	v_pk_add_f32 v[66:67], v[66:67], v[84:85] neg_lo:[0,1] neg_hi:[0,1]
	v_pk_mul_f32 v[84:85], v[66:67], s[14:15]
	v_pk_fma_f32 v[66:67], v[66:67], s[6:7], v[84:85] op_sel:[0,0,1] op_sel_hi:[1,0,0]
	v_pk_add_f32 v[84:85], v[68:69], v[86:87]
	v_pk_add_f32 v[68:69], v[68:69], v[86:87] neg_lo:[0,1] neg_hi:[0,1]
	v_pk_mul_f32 v[86:87], v[68:69], s[10:11]
	v_pk_fma_f32 v[68:69], v[68:69], s[10:11], v[86:87] op_sel:[0,0,1] op_sel_hi:[1,0,0]
	v_pk_add_f32 v[86:87], v[72:73], v[88:89]
	v_pk_add_f32 v[72:73], v[72:73], v[88:89] neg_lo:[0,1] neg_hi:[0,1]
	v_pk_mul_f32 v[88:89], v[72:73], s[6:7]
	v_pk_fma_f32 v[72:73], v[72:73], s[14:15], v[88:89] op_sel:[0,0,1] op_sel_hi:[1,0,0]
	v_pk_add_f32 v[88:89], v[74:75], v[90:91]
	v_pk_add_f32 v[90:91], v[74:75], v[90:91] op_sel:[1,1] op_sel_hi:[0,0] neg_lo:[1,0] neg_hi:[0,1]
	v_pk_add_f32 v[74:75], v[76:77], v[92:93]
	v_pk_add_f32 v[76:77], v[76:77], v[92:93] neg_lo:[0,1] neg_hi:[0,1]
	v_pk_mul_f32 v[92:93], v[76:77], s[6:7]
	v_pk_fma_f32 v[76:77], v[76:77], s[4:5], v[92:93] op_sel:[0,0,1] op_sel_hi:[1,0,0]
	v_pk_add_f32 v[92:93], v[78:79], v[94:95]
	v_pk_add_f32 v[78:79], v[78:79], v[94:95] neg_lo:[0,1] neg_hi:[0,1]
	s_mov_b32 s5, 0
	v_pk_mul_f32 v[94:95], v[78:79], s[10:11]
	v_pk_fma_f32 v[78:79], v[78:79], s[8:9], v[94:95] op_sel:[0,0,1] op_sel_hi:[1,0,0]
	v_pk_add_f32 v[94:95], v[80:81], v[96:97]
	v_pk_add_f32 v[80:81], v[80:81], v[96:97] neg_lo:[0,1] neg_hi:[0,1]
	v_pk_mul_f32 v[96:97], v[80:81], s[14:15]
	v_pk_fma_f32 v[80:81], v[80:81], s[12:13], v[96:97] op_sel:[0,0,1] op_sel_hi:[1,0,0]
	v_pk_add_f32 v[96:97], v[132:133], v[120:121]
	v_pk_add_f32 v[120:121], v[132:133], v[120:121] neg_lo:[0,1] neg_hi:[0,1]
	v_pk_add_f32 v[132:133], v[134:135], v[106:107]
	v_pk_add_f32 v[106:107], v[134:135], v[106:107] neg_lo:[0,1] neg_hi:[0,1]
	v_pk_mul_f32 v[134:135], v[106:107], s[10:11]
	v_pk_fma_f32 v[106:107], v[106:107], s[10:11], v[134:135] op_sel:[0,0,1] op_sel_hi:[1,0,0]
	v_pk_add_f32 v[134:135], v[130:131], v[124:125]
	v_pk_add_f32 v[130:131], v[130:131], v[124:125] op_sel:[1,1] op_sel_hi:[0,0] neg_lo:[1,0] neg_hi:[0,1]
	v_pk_add_f32 v[124:125], v[118:119], v[126:127]
	v_pk_add_f32 v[118:119], v[118:119], v[126:127] neg_lo:[0,1] neg_hi:[0,1]
	v_pk_mul_f32 v[126:127], v[118:119], s[10:11]
	v_pk_fma_f32 v[118:119], v[118:119], s[8:9], v[126:127] op_sel:[0,0,1] op_sel_hi:[1,0,0]
	v_pk_add_f32 v[126:127], v[114:115], v[122:123]
	v_pk_add_f32 v[114:115], v[114:115], v[122:123] neg_lo:[0,1] neg_hi:[0,1]
	v_pk_add_f32 v[122:123], v[82:83], v[108:109]
	v_pk_add_f32 v[82:83], v[82:83], v[108:109] neg_lo:[0,1] neg_hi:[0,1]
	v_pk_mul_f32 v[108:109], v[82:83], s[10:11]
	v_pk_fma_f32 v[82:83], v[82:83], s[10:11], v[108:109] op_sel:[0,0,1] op_sel_hi:[1,0,0]
	v_pk_add_f32 v[108:109], v[100:101], v[110:111]
	v_pk_add_f32 v[110:111], v[100:101], v[110:111] op_sel:[1,1] op_sel_hi:[0,0] neg_lo:[1,0] neg_hi:[0,1]
	v_pk_add_f32 v[100:101], v[102:103], v[112:113]
	v_pk_add_f32 v[102:103], v[102:103], v[112:113] neg_lo:[0,1] neg_hi:[0,1]
	v_pk_mul_f32 v[112:113], v[102:103], s[10:11]
	v_pk_fma_f32 v[102:103], v[102:103], s[8:9], v[112:113] op_sel:[0,0,1] op_sel_hi:[1,0,0]
	v_pk_add_f32 v[112:113], v[128:129], v[88:89]
	v_pk_add_f32 v[88:89], v[128:129], v[88:89] neg_lo:[0,1] neg_hi:[0,1]
	v_pk_add_f32 v[128:129], v[116:117], v[74:75]
	v_pk_add_f32 v[74:75], v[116:117], v[74:75] neg_lo:[0,1] neg_hi:[0,1]
	v_pk_mul_f32 v[116:117], v[74:75], s[10:11]
	v_pk_fma_f32 v[74:75], v[74:75], s[10:11], v[116:117] op_sel:[0,0,1] op_sel_hi:[1,0,0]
	v_pk_add_f32 v[116:117], v[84:85], v[92:93]
	v_pk_add_f32 v[92:93], v[84:85], v[92:93] op_sel:[1,1] op_sel_hi:[0,0] neg_lo:[1,0] neg_hi:[0,1]
	v_pk_add_f32 v[84:85], v[86:87], v[94:95]
	v_pk_add_f32 v[86:87], v[86:87], v[94:95] neg_lo:[0,1] neg_hi:[0,1]
	v_pk_mul_f32 v[94:95], v[86:87], s[10:11]
	v_pk_fma_f32 v[86:87], v[86:87], s[8:9], v[94:95] op_sel:[0,0,1] op_sel_hi:[1,0,0]
	v_pk_add_f32 v[94:95], v[98:99], v[90:91]
	v_pk_add_f32 v[90:91], v[98:99], v[90:91] neg_lo:[0,1] neg_hi:[0,1]
	v_pk_add_f32 v[98:99], v[66:67], v[76:77]
	v_pk_add_f32 v[66:67], v[66:67], v[76:77] neg_lo:[0,1] neg_hi:[0,1]
	v_pk_mul_f32 v[76:77], v[66:67], s[10:11]
	v_pk_fma_f32 v[66:67], v[66:67], s[10:11], v[76:77] op_sel:[0,0,1] op_sel_hi:[1,0,0]
	v_pk_add_f32 v[76:77], v[68:69], v[78:79]
	v_pk_add_f32 v[78:79], v[68:69], v[78:79] op_sel:[1,1] op_sel_hi:[0,0] neg_lo:[1,0] neg_hi:[0,1]
	v_pk_add_f32 v[68:69], v[72:73], v[80:81]
	v_pk_add_f32 v[72:73], v[72:73], v[80:81] neg_lo:[0,1] neg_hi:[0,1]
	v_pk_add_f32 v[136:137], v[90:91], v[78:79]
	v_pk_mul_f32 v[80:81], v[72:73], s[10:11]
	v_pk_add_f32 v[78:79], v[90:91], v[78:79] neg_lo:[0,1] neg_hi:[0,1]
	v_pk_fma_f32 v[72:73], v[72:73], s[8:9], v[80:81] op_sel:[0,0,1] op_sel_hi:[1,0,0]
	v_pk_add_f32 v[80:81], v[96:97], v[134:135]
	v_pk_add_f32 v[96:97], v[96:97], v[134:135] neg_lo:[0,1] neg_hi:[0,1]
	v_pk_add_f32 v[134:135], v[132:133], v[124:125]
	v_pk_add_f32 v[132:133], v[132:133], v[124:125] op_sel:[1,1] op_sel_hi:[0,0] neg_lo:[1,0] neg_hi:[0,1]
	v_pk_add_f32 v[90:91], v[66:67], v[72:73]
	v_pk_add_f32 v[124:125], v[120:121], v[130:131]
	v_pk_add_f32 v[120:121], v[120:121], v[130:131] neg_lo:[0,1] neg_hi:[0,1]
	v_pk_add_f32 v[130:131], v[106:107], v[118:119]
	v_pk_add_f32 v[118:119], v[106:107], v[118:119] op_sel:[1,1] op_sel_hi:[0,0] neg_lo:[1,0] neg_hi:[0,1]
	v_pk_add_f32 v[72:73], v[66:67], v[72:73] op_sel:[1,1] op_sel_hi:[0,0] neg_lo:[1,0] neg_hi:[0,1]
	v_pk_add_f32 v[106:107], v[126:127], v[108:109]
	v_pk_add_f32 v[108:109], v[126:127], v[108:109] neg_lo:[0,1] neg_hi:[0,1]
	v_pk_add_f32 v[126:127], v[122:123], v[100:101]
	v_pk_add_f32 v[122:123], v[122:123], v[100:101] op_sel:[1,1] op_sel_hi:[0,0] neg_lo:[1,0] neg_hi:[0,1]
	v_pk_add_f32 v[100:101], v[114:115], v[110:111]
	v_pk_add_f32 v[110:111], v[114:115], v[110:111] neg_lo:[0,1] neg_hi:[0,1]
	v_pk_add_f32 v[114:115], v[82:83], v[102:103]
	v_pk_add_f32 v[102:103], v[82:83], v[102:103] op_sel:[1,1] op_sel_hi:[0,0] neg_lo:[1,0] neg_hi:[0,1]
	v_pk_add_f32 v[82:83], v[112:113], v[116:117]
	v_pk_add_f32 v[112:113], v[112:113], v[116:117] neg_lo:[0,1] neg_hi:[0,1]
	v_pk_add_f32 v[116:117], v[128:129], v[84:85]
	v_pk_add_f32 v[128:129], v[128:129], v[84:85] op_sel:[1,1] op_sel_hi:[0,0] neg_lo:[1,0] neg_hi:[0,1]
	v_pk_add_f32 v[138:139], v[80:81], v[134:135]
	v_pk_add_f32 v[84:85], v[88:89], v[92:93]
	v_pk_add_f32 v[88:89], v[88:89], v[92:93] neg_lo:[0,1] neg_hi:[0,1]
	v_pk_add_f32 v[92:93], v[74:75], v[86:87]
	v_pk_add_f32 v[86:87], v[74:75], v[86:87] op_sel:[1,1] op_sel_hi:[0,0] neg_lo:[1,0] neg_hi:[0,1]
	v_pk_add_f32 v[80:81], v[80:81], v[134:135] neg_lo:[0,1] neg_hi:[0,1]
	v_pk_add_f32 v[74:75], v[94:95], v[76:77]
	v_pk_add_f32 v[76:77], v[94:95], v[76:77] neg_lo:[0,1] neg_hi:[0,1]
	v_pk_add_f32 v[94:95], v[98:99], v[68:69]
	v_pk_add_f32 v[98:99], v[98:99], v[68:69] op_sel:[1,1] op_sel_hi:[0,0] neg_lo:[1,0] neg_hi:[0,1]
	v_pk_add_f32 v[134:135], v[96:97], v[132:133]
	v_pk_add_f32 v[96:97], v[96:97], v[132:133] neg_lo:[0,1] neg_hi:[0,1]
	v_pk_add_f32 v[132:133], v[124:125], v[130:131]
	v_pk_add_f32 v[124:125], v[124:125], v[130:131] neg_lo:[0,1] neg_hi:[0,1]
	v_pk_add_f32 v[130:131], v[120:121], v[118:119]
	v_pk_add_f32 v[68:69], v[120:121], v[118:119] neg_lo:[0,1] neg_hi:[0,1]
	v_pk_add_f32 v[118:119], v[106:107], v[126:127]
	v_pk_add_f32 v[106:107], v[106:107], v[126:127] neg_lo:[0,1] neg_hi:[0,1]
	v_pk_add_f32 v[126:127], v[78:79], v[72:73]
	v_pk_add_f32 v[72:73], v[78:79], v[72:73] neg_lo:[0,1] neg_hi:[0,1]
	v_mul_f32_e32 v78, 0x38800000, v105
	v_sin_f32_e32 v79, v78
	v_cos_f32_e32 v78, v78
	v_pk_add_f32 v[120:121], v[108:109], v[122:123]
	v_pk_add_f32 v[108:109], v[108:109], v[122:123] neg_lo:[0,1] neg_hi:[0,1]
	v_pk_add_f32 v[122:123], v[100:101], v[114:115]
	v_pk_add_f32 v[100:101], v[100:101], v[114:115] neg_lo:[0,1] neg_hi:[0,1]
	v_pk_add_f32 v[114:115], v[110:111], v[102:103]
	v_pk_add_f32 v[66:67], v[110:111], v[102:103] neg_lo:[0,1] neg_hi:[0,1]
	v_pk_add_f32 v[102:103], v[82:83], v[116:117]
	v_pk_add_f32 v[82:83], v[82:83], v[116:117] neg_lo:[0,1] neg_hi:[0,1]
	v_pk_add_f32 v[116:117], v[84:85], v[92:93]
	v_pk_add_f32 v[84:85], v[84:85], v[92:93] neg_lo:[0,1] neg_hi:[0,1]
	v_pk_add_f32 v[92:93], v[88:89], v[86:87]
	v_pk_add_f32 v[86:87], v[88:89], v[86:87] neg_lo:[0,1] neg_hi:[0,1]
	v_pk_add_f32 v[88:89], v[74:75], v[94:95]
	v_pk_add_f32 v[74:75], v[74:75], v[94:95] neg_lo:[0,1] neg_hi:[0,1]
	v_pk_add_f32 v[94:95], v[76:77], v[98:99]
	v_pk_add_f32 v[76:77], v[76:77], v[98:99] neg_lo:[0,1] neg_hi:[0,1]
	v_pk_add_f32 v[98:99], v[136:137], v[90:91]
	v_pk_add_f32 v[90:91], v[136:137], v[90:91] neg_lo:[0,1] neg_hi:[0,1]
	v_sin_f32_e32 v136, v71
	v_pk_add_f32 v[110:111], v[112:113], v[128:129]
	v_pk_add_f32 v[112:113], v[112:113], v[128:129] neg_lo:[0,1] neg_hi:[0,1]
	v_cos_f32_e32 v128, v71
	v_pk_mul_f32 v[140:141], v[138:139], v[78:79] op_sel:[1,1] op_sel_hi:[0,1] neg_lo:[0,1]
	s_nop 0
	v_pk_fma_f32 v[138:139], v[138:139], v[78:79], v[140:141] op_sel_hi:[1,0,1]
	ds_write_b64 v142, v[138:139]
	v_pk_mul_f32 v[138:139], v[136:137], v[78:79] op_sel:[0,1] op_sel_hi:[0,0] neg_lo:[1,0]
	v_pk_fma_f32 v[78:79], v[78:79], v[128:129], v[138:139] op_sel_hi:[1,0,1]
	v_pk_mul_f32 v[138:139], v[102:103], v[78:79] op_sel:[1,1] op_sel_hi:[0,1] neg_lo:[0,1]
	v_pk_fma_f32 v[102:103], v[102:103], v[78:79], v[138:139] op_sel_hi:[1,0,1]
	v_pk_mul_f32 v[138:139], v[136:137], v[78:79] op_sel:[0,1] op_sel_hi:[0,0] neg_lo:[1,0]
	v_pk_fma_f32 v[78:79], v[78:79], v[128:129], v[138:139] op_sel_hi:[1,0,1]
	v_pk_mul_f32 v[138:139], v[118:119], v[78:79] op_sel:[1,1] op_sel_hi:[0,1] neg_lo:[0,1]
	v_pk_fma_f32 v[118:119], v[118:119], v[78:79], v[138:139] op_sel_hi:[1,0,1]
	ds_write2_b64 v0, v[102:103], v[118:119] offset0:33 offset1:66
	v_pk_mul_f32 v[102:103], v[136:137], v[78:79] op_sel:[0,1] op_sel_hi:[0,0] neg_lo:[1,0]
	v_pk_fma_f32 v[78:79], v[78:79], v[128:129], v[102:103] op_sel_hi:[1,0,1]
	v_pk_mul_f32 v[102:103], v[88:89], v[78:79] op_sel:[1,1] op_sel_hi:[0,1] neg_lo:[0,1]
	v_pk_fma_f32 v[88:89], v[88:89], v[78:79], v[102:103] op_sel_hi:[1,0,1]
	v_pk_mul_f32 v[102:103], v[136:137], v[78:79] op_sel:[0,1] op_sel_hi:[0,0] neg_lo:[1,0]
	v_pk_fma_f32 v[78:79], v[78:79], v[128:129], v[102:103] op_sel_hi:[1,0,1]
	v_pk_mul_f32 v[102:103], v[132:133], v[78:79] op_sel:[1,1] op_sel_hi:[0,1] neg_lo:[0,1]
	v_pk_fma_f32 v[102:103], v[132:133], v[78:79], v[102:103] op_sel_hi:[1,0,1]
	ds_write2_b64 v0, v[88:89], v[102:103] offset0:99 offset1:132
	v_pk_mul_f32 v[88:89], v[136:137], v[78:79] op_sel:[0,1] op_sel_hi:[0,0] neg_lo:[1,0]
	v_pk_fma_f32 v[78:79], v[78:79], v[128:129], v[88:89] op_sel_hi:[1,0,1]
	v_pk_mul_f32 v[88:89], v[116:117], v[78:79] op_sel:[1,1] op_sel_hi:[0,1] neg_lo:[0,1]
	v_pk_mul_f32 v[102:103], v[136:137], v[78:79] op_sel:[0,1] op_sel_hi:[0,0] neg_lo:[1,0]
	v_pk_fma_f32 v[88:89], v[116:117], v[78:79], v[88:89] op_sel_hi:[1,0,1]
	v_pk_fma_f32 v[78:79], v[78:79], v[128:129], v[102:103] op_sel_hi:[1,0,1]
	v_pk_mul_f32 v[102:103], v[122:123], v[78:79] op_sel:[1,1] op_sel_hi:[0,1] neg_lo:[0,1]
	v_pk_fma_f32 v[102:103], v[122:123], v[78:79], v[102:103] op_sel_hi:[1,0,1]
	ds_write2_b64 v0, v[88:89], v[102:103] offset0:165 offset1:198
	v_pk_mul_f32 v[88:89], v[136:137], v[78:79] op_sel:[0,1] op_sel_hi:[0,0] neg_lo:[1,0]
	v_pk_fma_f32 v[78:79], v[78:79], v[128:129], v[88:89] op_sel_hi:[1,0,1]
	v_pk_mul_f32 v[88:89], v[98:99], v[78:79] op_sel:[1,1] op_sel_hi:[0,1] neg_lo:[0,1]
	v_pk_fma_f32 v[88:89], v[98:99], v[78:79], v[88:89] op_sel_hi:[1,0,1]
	v_pk_mul_f32 v[98:99], v[136:137], v[78:79] op_sel:[0,1] op_sel_hi:[0,0] neg_lo:[1,0]
	v_pk_fma_f32 v[78:79], v[78:79], v[128:129], v[98:99] op_sel_hi:[1,0,1]
	v_pk_mul_f32 v[98:99], v[134:135], v[78:79] op_sel:[1,1] op_sel_hi:[0,1] neg_lo:[0,1]
	v_pk_fma_f32 v[98:99], v[134:135], v[78:79], v[98:99] op_sel_hi:[1,0,1]
	ds_write2_b64 v143, v[88:89], v[98:99] offset0:103 offset1:136
	v_pk_mul_f32 v[88:89], v[136:137], v[78:79] op_sel:[0,1] op_sel_hi:[0,0] neg_lo:[1,0]
	v_pk_fma_f32 v[78:79], v[78:79], v[128:129], v[88:89] op_sel_hi:[1,0,1]
	v_pk_mul_f32 v[88:89], v[110:111], v[78:79] op_sel:[1,1] op_sel_hi:[0,1] neg_lo:[0,1]
	v_pk_mul_f32 v[98:99], v[136:137], v[78:79] op_sel:[0,1] op_sel_hi:[0,0] neg_lo:[1,0]
	v_pk_fma_f32 v[88:89], v[110:111], v[78:79], v[88:89] op_sel_hi:[1,0,1]
	v_pk_fma_f32 v[78:79], v[78:79], v[128:129], v[98:99] op_sel_hi:[1,0,1]
	v_pk_mul_f32 v[98:99], v[120:121], v[78:79] op_sel:[1,1] op_sel_hi:[0,1] neg_lo:[0,1]
	v_pk_fma_f32 v[98:99], v[120:121], v[78:79], v[98:99] op_sel_hi:[1,0,1]
	ds_write2_b64 v144, v[88:89], v[98:99] offset0:41 offset1:74
	v_pk_mul_f32 v[88:89], v[136:137], v[78:79] op_sel:[0,1] op_sel_hi:[0,0] neg_lo:[1,0]
	v_pk_fma_f32 v[78:79], v[78:79], v[128:129], v[88:89] op_sel_hi:[1,0,1]
	v_pk_mul_f32 v[88:89], v[94:95], v[78:79] op_sel:[1,1] op_sel_hi:[0,1] neg_lo:[0,1]
	v_pk_fma_f32 v[88:89], v[94:95], v[78:79], v[88:89] op_sel_hi:[1,0,1]
	v_pk_mul_f32 v[94:95], v[136:137], v[78:79] op_sel:[0,1] op_sel_hi:[0,0] neg_lo:[1,0]
	v_pk_fma_f32 v[78:79], v[78:79], v[128:129], v[94:95] op_sel_hi:[1,0,1]
	v_pk_mul_f32 v[94:95], v[130:131], v[78:79] op_sel:[1,1] op_sel_hi:[0,1] neg_lo:[0,1]
	v_pk_fma_f32 v[94:95], v[130:131], v[78:79], v[94:95] op_sel_hi:[1,0,1]
	ds_write2_b64 v144, v[88:89], v[94:95] offset0:107 offset1:140
	v_pk_mul_f32 v[88:89], v[136:137], v[78:79] op_sel:[0,1] op_sel_hi:[0,0] neg_lo:[1,0]
	v_pk_fma_f32 v[78:79], v[78:79], v[128:129], v[88:89] op_sel_hi:[1,0,1]
	v_pk_mul_f32 v[88:89], v[92:93], v[78:79] op_sel:[1,1] op_sel_hi:[0,1] neg_lo:[0,1]
	v_pk_fma_f32 v[88:89], v[92:93], v[78:79], v[88:89] op_sel_hi:[1,0,1]
	v_pk_mul_f32 v[92:93], v[136:137], v[78:79] op_sel:[0,1] op_sel_hi:[0,0] neg_lo:[1,0]
	v_pk_fma_f32 v[78:79], v[78:79], v[128:129], v[92:93] op_sel_hi:[1,0,1]
	v_pk_mul_f32 v[92:93], v[114:115], v[78:79] op_sel:[1,1] op_sel_hi:[0,1] neg_lo:[0,1]
	v_pk_fma_f32 v[92:93], v[114:115], v[78:79], v[92:93] op_sel_hi:[1,0,1]
	ds_write2_b64 v144, v[88:89], v[92:93] offset0:173 offset1:206
	v_pk_mul_f32 v[88:89], v[136:137], v[78:79] op_sel:[0,1] op_sel_hi:[0,0] neg_lo:[1,0]
	v_pk_fma_f32 v[78:79], v[78:79], v[128:129], v[88:89] op_sel_hi:[1,0,1]
	v_pk_mul_f32 v[88:89], v[126:127], v[78:79] op_sel:[1,1] op_sel_hi:[0,1] neg_lo:[0,1]
	v_pk_mul_f32 v[92:93], v[136:137], v[78:79] op_sel:[0,1] op_sel_hi:[0,0] neg_lo:[1,0]
	v_pk_fma_f32 v[88:89], v[126:127], v[78:79], v[88:89] op_sel_hi:[1,0,1]
	v_pk_fma_f32 v[78:79], v[78:79], v[128:129], v[92:93] op_sel_hi:[1,0,1]
	v_pk_mul_f32 v[92:93], v[80:81], v[78:79] op_sel:[1,1] op_sel_hi:[0,1] neg_lo:[0,1]
	v_pk_fma_f32 v[80:81], v[80:81], v[78:79], v[92:93] op_sel_hi:[1,0,1]
	ds_write2_b64 v145, v[88:89], v[80:81] offset0:111 offset1:144
	v_pk_mul_f32 v[80:81], v[136:137], v[78:79] op_sel:[0,1] op_sel_hi:[0,0] neg_lo:[1,0]
	v_pk_fma_f32 v[78:79], v[78:79], v[128:129], v[80:81] op_sel_hi:[1,0,1]
	v_pk_mul_f32 v[80:81], v[82:83], v[78:79] op_sel:[1,1] op_sel_hi:[0,1] neg_lo:[0,1]
	v_pk_fma_f32 v[80:81], v[82:83], v[78:79], v[80:81] op_sel_hi:[1,0,1]
	v_pk_mul_f32 v[82:83], v[136:137], v[78:79] op_sel:[0,1] op_sel_hi:[0,0] neg_lo:[1,0]
	v_pk_fma_f32 v[78:79], v[78:79], v[128:129], v[82:83] op_sel_hi:[1,0,1]
	v_pk_mul_f32 v[82:83], v[106:107], v[78:79] op_sel:[1,1] op_sel_hi:[0,1] neg_lo:[0,1]
	v_pk_fma_f32 v[82:83], v[106:107], v[78:79], v[82:83] op_sel_hi:[1,0,1]
	ds_write2_b64 v146, v[80:81], v[82:83] offset0:49 offset1:82
	v_pk_mul_f32 v[80:81], v[136:137], v[78:79] op_sel:[0,1] op_sel_hi:[0,0] neg_lo:[1,0]
	v_pk_fma_f32 v[78:79], v[78:79], v[128:129], v[80:81] op_sel_hi:[1,0,1]
	v_pk_mul_f32 v[80:81], v[74:75], v[78:79] op_sel:[1,1] op_sel_hi:[0,1] neg_lo:[0,1]
	v_pk_fma_f32 v[74:75], v[74:75], v[78:79], v[80:81] op_sel_hi:[1,0,1]
	v_pk_mul_f32 v[80:81], v[136:137], v[78:79] op_sel:[0,1] op_sel_hi:[0,0] neg_lo:[1,0]
	v_pk_fma_f32 v[78:79], v[78:79], v[128:129], v[80:81] op_sel_hi:[1,0,1]
	v_pk_mul_f32 v[80:81], v[124:125], v[78:79] op_sel:[1,1] op_sel_hi:[0,1] neg_lo:[0,1]
	v_pk_fma_f32 v[80:81], v[124:125], v[78:79], v[80:81] op_sel_hi:[1,0,1]
	ds_write2_b64 v146, v[74:75], v[80:81] offset0:115 offset1:148
	v_pk_mul_f32 v[74:75], v[136:137], v[78:79] op_sel:[0,1] op_sel_hi:[0,0] neg_lo:[1,0]
	v_pk_fma_f32 v[74:75], v[78:79], v[128:129], v[74:75] op_sel_hi:[1,0,1]
	v_pk_mul_f32 v[78:79], v[84:85], v[74:75] op_sel:[1,1] op_sel_hi:[0,1] neg_lo:[0,1]
	v_pk_mul_f32 v[80:81], v[136:137], v[74:75] op_sel:[0,1] op_sel_hi:[0,0] neg_lo:[1,0]
	v_pk_fma_f32 v[78:79], v[84:85], v[74:75], v[78:79] op_sel_hi:[1,0,1]
	v_pk_fma_f32 v[74:75], v[74:75], v[128:129], v[80:81] op_sel_hi:[1,0,1]
	v_pk_mul_f32 v[80:81], v[100:101], v[74:75] op_sel:[1,1] op_sel_hi:[0,1] neg_lo:[0,1]
	v_pk_fma_f32 v[80:81], v[100:101], v[74:75], v[80:81] op_sel_hi:[1,0,1]
	ds_write2_b64 v146, v[78:79], v[80:81] offset0:181 offset1:214
	v_pk_mul_f32 v[78:79], v[136:137], v[74:75] op_sel:[0,1] op_sel_hi:[0,0] neg_lo:[1,0]
	v_pk_fma_f32 v[74:75], v[74:75], v[128:129], v[78:79] op_sel_hi:[1,0,1]
	v_pk_mul_f32 v[78:79], v[90:91], v[74:75] op_sel:[1,1] op_sel_hi:[0,1] neg_lo:[0,1]
	v_pk_mul_f32 v[80:81], v[136:137], v[74:75] op_sel:[0,1] op_sel_hi:[0,0] neg_lo:[1,0]
	v_pk_fma_f32 v[78:79], v[90:91], v[74:75], v[78:79] op_sel_hi:[1,0,1]
	v_pk_fma_f32 v[74:75], v[74:75], v[128:129], v[80:81] op_sel_hi:[1,0,1]
	v_pk_mul_f32 v[80:81], v[96:97], v[74:75] op_sel:[1,1] op_sel_hi:[0,1] neg_lo:[0,1]
	v_pk_fma_f32 v[80:81], v[96:97], v[74:75], v[80:81] op_sel_hi:[1,0,1]
	ds_write2_b64 v147, v[78:79], v[80:81] offset0:119 offset1:152
	v_pk_mul_f32 v[78:79], v[136:137], v[74:75] op_sel:[0,1] op_sel_hi:[0,0] neg_lo:[1,0]
	v_pk_fma_f32 v[74:75], v[74:75], v[128:129], v[78:79] op_sel_hi:[1,0,1]
	v_pk_mul_f32 v[78:79], v[112:113], v[74:75] op_sel:[1,1] op_sel_hi:[0,1] neg_lo:[0,1]
	v_pk_mul_f32 v[80:81], v[136:137], v[74:75] op_sel:[0,1] op_sel_hi:[0,0] neg_lo:[1,0]
	v_pk_fma_f32 v[78:79], v[112:113], v[74:75], v[78:79] op_sel_hi:[1,0,1]
	v_pk_fma_f32 v[74:75], v[74:75], v[128:129], v[80:81] op_sel_hi:[1,0,1]
	v_pk_mul_f32 v[80:81], v[108:109], v[74:75] op_sel:[1,1] op_sel_hi:[0,1] neg_lo:[0,1]
	v_pk_fma_f32 v[80:81], v[108:109], v[74:75], v[80:81] op_sel_hi:[1,0,1]
	ds_write2_b64 v70, v[78:79], v[80:81] offset0:57 offset1:90
	v_pk_mul_f32 v[78:79], v[136:137], v[74:75] op_sel:[0,1] op_sel_hi:[0,0] neg_lo:[1,0]
	v_pk_fma_f32 v[74:75], v[74:75], v[128:129], v[78:79] op_sel_hi:[1,0,1]
	v_pk_mul_f32 v[78:79], v[76:77], v[74:75] op_sel:[1,1] op_sel_hi:[0,1] neg_lo:[0,1]
	v_pk_fma_f32 v[76:77], v[76:77], v[74:75], v[78:79] op_sel_hi:[1,0,1]
	v_pk_mul_f32 v[78:79], v[136:137], v[74:75] op_sel:[0,1] op_sel_hi:[0,0] neg_lo:[1,0]
	v_pk_fma_f32 v[74:75], v[74:75], v[128:129], v[78:79] op_sel_hi:[1,0,1]
	v_pk_mul_f32 v[78:79], v[68:69], v[74:75] op_sel:[1,1] op_sel_hi:[0,1] neg_lo:[0,1]
	v_pk_fma_f32 v[68:69], v[68:69], v[74:75], v[78:79] op_sel_hi:[1,0,1]
	ds_write2_b64 v70, v[76:77], v[68:69] offset0:123 offset1:156
	v_pk_mul_f32 v[68:69], v[136:137], v[74:75] op_sel:[0,1] op_sel_hi:[0,0] neg_lo:[1,0]
	v_pk_fma_f32 v[68:69], v[74:75], v[128:129], v[68:69] op_sel_hi:[1,0,1]
	v_pk_mul_f32 v[74:75], v[86:87], v[68:69] op_sel:[1,1] op_sel_hi:[0,1] neg_lo:[0,1]
	v_pk_mul_f32 v[76:77], v[136:137], v[68:69] op_sel:[0,1] op_sel_hi:[0,0] neg_lo:[1,0]
	v_pk_fma_f32 v[74:75], v[86:87], v[68:69], v[74:75] op_sel_hi:[1,0,1]
	v_pk_fma_f32 v[68:69], v[68:69], v[128:129], v[76:77] op_sel_hi:[1,0,1]
	v_pk_mul_f32 v[76:77], v[66:67], v[68:69] op_sel:[1,1] op_sel_hi:[0,1] neg_lo:[0,1]
	v_pk_fma_f32 v[66:67], v[66:67], v[68:69], v[76:77] op_sel_hi:[1,0,1]
	ds_write2_b64 v70, v[74:75], v[66:67] offset0:189 offset1:222
	v_pk_mul_f32 v[66:67], v[136:137], v[68:69] op_sel:[0,1] op_sel_hi:[0,0] neg_lo:[1,0]
	v_pk_fma_f32 v[66:67], v[68:69], v[128:129], v[66:67] op_sel_hi:[1,0,1]
	v_pk_mul_f32 v[68:69], v[72:73], v[66:67] op_sel:[1,1] op_sel_hi:[0,1] neg_lo:[0,1]
	v_pk_fma_f32 v[66:67], v[72:73], v[66:67], v[68:69] op_sel_hi:[1,0,1]
	ds_write_b64 v0, v[66:67] offset:8184
	s_waitcnt lgkmcnt(0)
	s_barrier
